# loop-edge rotation (doc 7.11): K-loop scalar updates, exit test and next-iteration address set-up moved in front of the iteration's last barrier; barrier becomes the loop head; exit path has its own b
# speedup vs baseline: 1.0104x; 1.0104x over previous
; #define PG8_STAGE(bufoff, gbase, voff) do { _Pragma("unroll") for (int _i = 0; _i < 2; ++_i) \
;         __builtin_amdgcn_global_load_lds((const unsigned*)((const char*)(gbase) + (voff)[_i]), (PG8_LAS unsigned*)(lds + (bufoff) + ldsw + _i * 8192), 16, 0, 0); } while (0)
; #define PG8_WAIT_V(n) asm volatile("s_waitcnt vmcnt(" #n ")" ::: "memory")
; #define PG8_BAR __builtin_amdgcn_s_barrier()
; template <class Epi, class Sched, bool ALIGN_EPI = false, bool SP2 = false>
; __device__ __forceinline__ void gemm_phase(PG8_LAS unsigned char* lds, const Gemm g, const Sched& S, const Epi& E, int wave_in) {
;     ...
;         const bool has_next = S.next(ui + 1, nxt);
;         const char* nA = has_next ? (const char*)g.A + (size_t)(nxt.pm >> g.ash) * g.astride + (size_t)nxt.pm * tstep : cA; const char* nB = has_next ? (const char*)g.Bt + (size_t)(nxt.pm >> g.bsh) * g.bstride + (size_t)nxt.pn * tstep : cB;
;         for (int t = 0; t < nt; t += 2) {
;             const bool last = (t == nt - 2);
;             const char* a1 = cA + (size_t)(t + 1) * kstep;
;             const char* a2 = last ? nA : cA + (size_t)(t + 2) * kstep; const char* b2 = last ? nB : cB + (size_t)(t + 2) * kstep;
;             const char* a3 = a2 + kstep; const char* b3 = b2 + kstep;
;             if (last && has_next) S.a_ready(nxt);
;             if constexpr (SP2) {
;             PG8_LDB(B0, 0, 0); PG8_LDB(B1, 0, 1); PG8_SCHED; PG8_LDA(At, 0, 0); PG8_STAGE(PG8_SA(1, 1), a1 + hstep, voffA);
;             PG8_WAIT_V(8); PG8_WAIT_L(0); PG8_BAR; PG8_MMA(0, 0, At, B0); PG8_MMA(0, 1, At, B1); PG8_BAR; PG8_SCHED;
;             PG8_LDA(At, 0, 1); PG8_STAGE(PG8_SB(0, 0), b2, voffB); PG8_STAGE(PG8_SB(0, 1), b2 + hstep, voffB); PG8_STAGE(PG8_SA(0, 0), a2, voffA);
;             PG8_WAIT_V(8); PG8_WAIT_L(0); PG8_BAR; PG8_MMA(1, 0, At, B0); PG8_MMA(1, 1, At, B1); PG8_BAR; PG8_SCHED;
;             PG8_LDB(B0, 1, 0); PG8_LDB(B1, 1, 1); PG8_SCHED; PG8_LDA(At, 1, 0); PG8_STAGE(PG8_SA(0, 1), a2 + hstep, voffA);
;             PG8_WAIT_V(8); PG8_WAIT_L(0); PG8_BAR; PG8_MMA(0, 0, At, B0); PG8_MMA(0, 1, At, B1); PG8_BAR; PG8_SCHED;
;             PG8_LDA(At, 1, 1); PG8_STAGE(PG8_SB(1, 0), b3, voffB); PG8_STAGE(PG8_SB(1, 1), b3 + hstep, voffB); PG8_STAGE(PG8_SA(1, 0), a3, voffA);
;             PG8_WAIT_V(8); PG8_WAIT_L(0); PG8_BAR; PG8_MMA(1, 0, At, B0); PG8_MMA(1, 1, At, B1); PG8_BAR; PG8_SCHED;
.LBB0_272:
	s_ashr_i32 s77, s76, 31
	s_lshl_b64 s[8:9], s[76:77], 19
	s_add_u32 s84, s22, s8
	s_addc_u32 s85, s23, s9
	s_and_b64 s[8:9], s[40:41], exec
	s_cselect_b32 s8, s85, s5
	s_cselect_b32 s9, s84, s4
	s_ashr_i32 s95, s94, 31
	s_lshl_b64 s[10:11], s[94:95], 19
	v_readlane_b32 s16, v255, 39
	v_readlane_b32 s17, v255, 40
	s_add_u32 s24, s16, s10
	s_addc_u32 s25, s17, s11
	s_and_b64 s[10:11], s[40:41], exec
	s_cselect_b32 s16, s25, s1
	s_cselect_b32 s17, s24, s0
	s_add_u32 s31, s0, 0x100
	s_addc_u32 s33, s1, 0
	s_add_u32 s0, s4, 0x40080
	s_addc_u32 s1, s5, 0
	s_mov_b32 s34, -2
	s_waitcnt lgkmcnt(0)
	s_add_u32 s4, s0, 0xfffc0080
	s_addc_u32 s5, s1, -1
	s_add_i32 s42, s35, 0x100
	s_cmp_eq_u32 s34, 12
	s_cselect_b32 s11, s8, s5
	s_cselect_b32 s10, s9, s4
	s_cselect_b32 s5, s16, s33
	s_cselect_b32 s4, s17, s31
	s_add_i32 s44, s90, 0x100
	v_add_u32_e32 v168, s42, v177
	v_add_u32_e32 v188, s44, v177
	ds_read_b128 v[156:159], v168
	ds_read_b128 v[160:163], v168 offset:1024
	ds_read_b128 v[164:167], v168 offset:2048
	ds_read_b128 v[168:171], v168 offset:3072
	ds_read_b128 v[172:175], v188
	ds_read_b128 v[180:183], v188 offset:1024
	ds_read_b128 v[184:187], v188 offset:2048
	ds_read_b128 v[188:191], v188 offset:3072
	v_lshl_add_u64 v[230:231], s[0:1], 0, v[154:155]
	s_add_i32 m0, s67, 0xc000
	ds_read_b128 v[198:201], v179
	ds_read_b128 v[202:205], v179 offset:1024
	ds_read_b128 v[206:209], v179 offset:2048
	ds_read_b128 v[210:213], v179 offset:3072
	ds_read_b128 v[214:217], v179 offset:4096
	ds_read_b128 v[218:221], v179 offset:5120
	ds_read_b128 v[222:225], v179 offset:6144
	ds_read_b128 v[226:229], v179 offset:7168
	global_load_lds_dwordx4 v[230:231], off
	v_lshl_add_u64 v[230:231], s[0:1], 0, v[152:153]
	s_add_i32 m0, s67, 0xe000
	s_nop 0
	global_load_lds_dwordx4 v[230:231], off
	s_waitcnt vmcnt(8)
	s_waitcnt lgkmcnt(0)
	s_barrier
	s_setprio 1
	s_waitcnt lgkmcnt(0)
	v_mfma_f32_16x16x32_bf16 v[124:127], v[156:159], v[198:201], 0
	v_mfma_f32_16x16x32_bf16 v[120:123], v[164:167], v[198:201], 0
	v_mfma_f32_16x16x32_bf16 v[108:111], v[156:159], v[206:209], 0
	v_mfma_f32_16x16x32_bf16 v[104:107], v[164:167], v[206:209], 0
	v_mfma_f32_16x16x32_bf16 v[92:95], v[156:159], v[214:217], 0
	v_mfma_f32_16x16x32_bf16 v[88:91], v[164:167], v[214:217], 0
	v_mfma_f32_16x16x32_bf16 v[76:79], v[156:159], v[222:225], 0
	v_mfma_f32_16x16x32_bf16 v[72:75], v[164:167], v[222:225], 0
	v_mfma_f32_16x16x32_bf16 v[124:127], v[160:163], v[202:205], v[124:127]
	v_mfma_f32_16x16x32_bf16 v[120:123], v[168:171], v[202:205], v[120:123]
	v_mfma_f32_16x16x32_bf16 v[108:111], v[160:163], v[210:213], v[108:111]
	v_mfma_f32_16x16x32_bf16 v[104:107], v[168:171], v[210:213], v[104:107]
	v_mfma_f32_16x16x32_bf16 v[92:95], v[160:163], v[218:221], v[92:95]
	v_mfma_f32_16x16x32_bf16 v[88:91], v[168:171], v[218:221], v[88:91]
	v_mfma_f32_16x16x32_bf16 v[76:79], v[160:163], v[226:229], v[76:79]
	v_mfma_f32_16x16x32_bf16 v[72:75], v[168:171], v[226:229], v[72:75]
	s_setprio 0
	s_setprio 1
	v_mfma_f32_16x16x32_bf16 v[116:119], v[172:175], v[198:201], 0
	v_mfma_f32_16x16x32_bf16 v[112:115], v[184:187], v[198:201], 0
	v_mfma_f32_16x16x32_bf16 v[100:103], v[172:175], v[206:209], 0
	v_mfma_f32_16x16x32_bf16 v[96:99], v[184:187], v[206:209], 0
	v_mfma_f32_16x16x32_bf16 v[84:87], v[172:175], v[214:217], 0
	v_mfma_f32_16x16x32_bf16 v[80:83], v[184:187], v[214:217], 0
	v_mfma_f32_16x16x32_bf16 v[68:71], v[172:175], v[222:225], 0
	v_mfma_f32_16x16x32_bf16 v[64:67], v[184:187], v[222:225], 0
	v_mfma_f32_16x16x32_bf16 v[116:119], v[180:183], v[202:205], v[116:119]
	v_mfma_f32_16x16x32_bf16 v[112:115], v[188:191], v[202:205], v[112:115]
	v_mfma_f32_16x16x32_bf16 v[100:103], v[180:183], v[210:213], v[100:103]
	v_mfma_f32_16x16x32_bf16 v[96:99], v[188:191], v[210:213], v[96:99]
	v_mfma_f32_16x16x32_bf16 v[84:87], v[180:183], v[218:221], v[84:87]
	v_mfma_f32_16x16x32_bf16 v[80:83], v[188:191], v[218:221], v[80:83]
	v_mfma_f32_16x16x32_bf16 v[68:71], v[180:183], v[226:229], v[68:71]
	v_mfma_f32_16x16x32_bf16 v[64:67], v[188:191], v[226:229], v[64:67]
	s_setprio 0
	s_barrier
	s_add_i32 s42, s42, s66
	v_lshl_add_u64 v[230:231], s[4:5], 0, v[132:133]
	s_mov_b32 m0, s42
	ds_read_b128 v[198:201], v179 offset:16384
	ds_read_b128 v[202:205], v179 offset:17408
	ds_read_b128 v[206:209], v179 offset:18432
	ds_read_b128 v[210:213], v179 offset:19456
	ds_read_b128 v[214:217], v179 offset:20480
	ds_read_b128 v[218:221], v179 offset:21504
	ds_read_b128 v[222:225], v179 offset:22528
	ds_read_b128 v[226:229], v179 offset:23552
	global_load_lds_dwordx4 v[230:231], off
	s_add_i32 m0, s42, 0x2000
	s_add_u32 s42, s4, 0x40000
	v_lshl_add_u64 v[232:233], s[4:5], 0, v[128:129]
	s_addc_u32 s43, s5, 0
	s_add_i32 s44, s44, s66
	global_load_lds_dwordx4 v[232:233], off
	v_lshl_add_u64 v[234:235], s[42:43], 0, v[132:133]
	s_mov_b32 m0, s44
	v_lshl_add_u64 v[236:237], s[10:11], 0, v[130:131]
	global_load_lds_dwordx4 v[234:235], off
	v_lshl_add_u64 v[234:235], s[42:43], 0, v[128:129]
	s_add_i32 m0, s44, 0x2000
	s_nop 0
	global_load_lds_dwordx4 v[234:235], off
	v_lshl_add_u64 v[234:235], s[10:11], 0, v[134:135]
	s_mov_b32 m0, s67
	s_nop 0
	global_load_lds_dwordx4 v[234:235], off
	s_mov_b32 m0, s78
	s_nop 0
	global_load_lds_dwordx4 v[236:237], off
	s_waitcnt vmcnt(8)
	s_waitcnt lgkmcnt(0)
	s_barrier
; #define PG8_STAGE(bufoff, gbase, voff) do { _Pragma("unroll") for (int _i = 0; _i < 2; ++_i) \
;         __builtin_amdgcn_global_load_lds((const unsigned*)((const char*)(gbase) + (voff)[_i]), (PG8_LAS unsigned*)(lds + (bufoff) + ldsw + _i * 8192), 16, 0, 0); } while (0)
; #define PG8_LDA(dst, b, h) do { _Pragma("unroll") for (int m = 0; m < 4; ++m) _Pragma("unroll") for (int k = 0; k < 2; ++k) dst[m][k] = *(const PG8_LAS bf16x8*)(lds + PG8_SA(b, h) + aoff + m * 2048 + k * 1024); } while (0)
; #define PG8_LDB(dst, b, h) do { _Pragma("unroll") for (int n = 0; n < 2; ++n) _Pragma("unroll") for (int k = 0; k < 2; ++k) dst[n][k] = *(const PG8_LAS bf16x8*)(lds + PG8_SB(b, h) + boff + n * 2048 + k * 1024); } while (0)
; #define PG8_MMA(ai, bj, At, Bt) do { __builtin_amdgcn_s_setprio(1); _Pragma("unroll") for (int m = 0; m < 4; ++m) _Pragma("unroll") for (int n = 0; n < 2; ++n) _Pragma("unroll") for (int k = 0; k < 2; ++k) \
;         acc[ai][bj][m][n] = __builtin_amdgcn_mfma_f32_16x16x32_bf16(Bt[n][k], At[m][k], acc[ai][bj][m][n], 0, 0, 0); __builtin_amdgcn_s_setprio(0); } while (0)
; #define PG8_BAR __builtin_amdgcn_s_barrier()
; template <class Epi, class Sched, bool ALIGN_EPI = false, bool SP2 = false>
; __device__ __forceinline__ void gemm_phase(PG8_LAS unsigned char* lds, const Gemm g, const Sched& S, const Epi& E, int wave_in) {
;     ...
;             PG8_LDB(B0, 0, 0); PG8_LDB(B1, 0, 1); PG8_SCHED; PG8_LDA(At, 0, 0); PG8_STAGE(PG8_SA(1, 1), a1 + hstep, voffA);
;             PG8_WAIT_V(8); PG8_WAIT_L(0); PG8_BAR; PG8_MMA(0, 0, At, B0); PG8_MMA(0, 1, At, B1); PG8_BAR; PG8_SCHED;
;             PG8_LDA(At, 0, 1); PG8_STAGE(PG8_SB(0, 0), b2, voffB); PG8_STAGE(PG8_SB(0, 1), b2 + hstep, voffB); PG8_STAGE(PG8_SA(0, 0), a2, voffA);
;             PG8_WAIT_V(8); PG8_WAIT_L(0); PG8_BAR; PG8_MMA(1, 0, At, B0); PG8_MMA(1, 1, At, B1); PG8_BAR; PG8_SCHED;
;             PG8_LDB(B0, 1, 0); PG8_LDB(B1, 1, 1); PG8_SCHED; PG8_LDA(At, 1, 0); PG8_STAGE(PG8_SA(0, 1), a2 + hstep, voffA);
;             PG8_WAIT_V(8); PG8_WAIT_L(0); PG8_BAR; PG8_MMA(0, 0, At, B0); PG8_MMA(0, 1, At, B1); PG8_BAR; PG8_SCHED;
;             PG8_LDA(At, 1, 1); PG8_STAGE(PG8_SB(1, 0), b3, voffB); PG8_STAGE(PG8_SB(1, 1), b3 + hstep, voffB); PG8_STAGE(PG8_SA(1, 0), a3, voffA);
;             PG8_WAIT_V(8); PG8_WAIT_L(0); PG8_BAR; PG8_MMA(1, 0, At, B0); PG8_MMA(1, 1, At, B1); PG8_BAR; PG8_SCHED;
	s_setprio 1
	s_waitcnt lgkmcnt(0)
	v_mfma_f32_16x16x32_bf16 v[60:63], v[156:159], v[198:201], 0
	v_mfma_f32_16x16x32_bf16 v[56:59], v[164:167], v[198:201], 0
	v_mfma_f32_16x16x32_bf16 v[44:47], v[156:159], v[206:209], 0
	v_mfma_f32_16x16x32_bf16 v[40:43], v[164:167], v[206:209], 0
	v_mfma_f32_16x16x32_bf16 v[28:31], v[156:159], v[214:217], 0
	v_mfma_f32_16x16x32_bf16 v[24:27], v[164:167], v[214:217], 0
	v_mfma_f32_16x16x32_bf16 v[12:15], v[156:159], v[222:225], 0
	v_mfma_f32_16x16x32_bf16 v[8:11], v[164:167], v[222:225], 0
	v_mfma_f32_16x16x32_bf16 v[60:63], v[160:163], v[202:205], v[60:63]
	v_mfma_f32_16x16x32_bf16 v[56:59], v[168:171], v[202:205], v[56:59]
	v_mfma_f32_16x16x32_bf16 v[44:47], v[160:163], v[210:213], v[44:47]
	v_mfma_f32_16x16x32_bf16 v[40:43], v[168:171], v[210:213], v[40:43]
	v_mfma_f32_16x16x32_bf16 v[28:31], v[160:163], v[218:221], v[28:31]
	v_mfma_f32_16x16x32_bf16 v[24:27], v[168:171], v[218:221], v[24:27]
	v_mfma_f32_16x16x32_bf16 v[12:15], v[160:163], v[226:229], v[12:15]
	v_mfma_f32_16x16x32_bf16 v[8:11], v[168:171], v[226:229], v[8:11]
	s_setprio 0
	s_setprio 1
	v_mfma_f32_16x16x32_bf16 v[52:55], v[172:175], v[198:201], 0
	v_mfma_f32_16x16x32_bf16 v[48:51], v[184:187], v[198:201], 0
	v_mfma_f32_16x16x32_bf16 v[36:39], v[172:175], v[206:209], 0
	v_mfma_f32_16x16x32_bf16 v[32:35], v[184:187], v[206:209], 0
	v_mfma_f32_16x16x32_bf16 v[20:23], v[172:175], v[214:217], 0
	v_mfma_f32_16x16x32_bf16 v[16:19], v[184:187], v[214:217], 0
	v_mfma_f32_16x16x32_bf16 v[4:7], v[172:175], v[222:225], 0
	v_mfma_f32_16x16x32_bf16 v[0:3], v[184:187], v[222:225], 0
	v_mfma_f32_16x16x32_bf16 v[52:55], v[180:183], v[202:205], v[52:55]
	v_mfma_f32_16x16x32_bf16 v[48:51], v[188:191], v[202:205], v[48:51]
	v_mfma_f32_16x16x32_bf16 v[36:39], v[180:183], v[210:213], v[36:39]
	v_mfma_f32_16x16x32_bf16 v[32:35], v[188:191], v[210:213], v[32:35]
	v_mfma_f32_16x16x32_bf16 v[20:23], v[180:183], v[218:221], v[20:23]
	v_mfma_f32_16x16x32_bf16 v[16:19], v[188:191], v[218:221], v[16:19]
	v_mfma_f32_16x16x32_bf16 v[4:7], v[180:183], v[226:229], v[4:7]
	v_mfma_f32_16x16x32_bf16 v[0:3], v[188:191], v[226:229], v[0:3]
	s_setprio 0
	s_barrier
	s_add_i32 s42, s65, 0x100
	s_add_i32 s43, s52, 0x100
	v_add_u32_e32 v168, s42, v177
	v_add_u32_e32 v188, s43, v177
	ds_read_b128 v[156:159], v168
	ds_read_b128 v[160:163], v168 offset:1024
	ds_read_b128 v[164:167], v168 offset:2048
	ds_read_b128 v[168:171], v168 offset:3072
	ds_read_b128 v[172:175], v188
	ds_read_b128 v[180:183], v188 offset:1024
	ds_read_b128 v[184:187], v188 offset:2048
	ds_read_b128 v[188:191], v188 offset:3072
	s_add_u32 s10, s10, 0x40000
	s_addc_u32 s11, s11, 0
	s_mov_b32 m0, s79
	v_lshl_add_u64 v[238:239], s[10:11], 0, v[134:135]
	ds_read_b128 v[198:201], v179 offset:32768
	ds_read_b128 v[202:205], v179 offset:33792
	ds_read_b128 v[206:209], v179 offset:34816
	ds_read_b128 v[210:213], v179 offset:35840
	ds_read_b128 v[214:217], v179 offset:36864
	ds_read_b128 v[218:221], v179 offset:37888
	ds_read_b128 v[222:225], v179 offset:38912
	ds_read_b128 v[226:229], v179 offset:39936
	global_load_lds_dwordx4 v[238:239], off
	v_lshl_add_u64 v[238:239], s[10:11], 0, v[130:131]
	s_mov_b32 m0, s82
	s_nop 0
	global_load_lds_dwordx4 v[238:239], off
	s_waitcnt vmcnt(8)
	s_waitcnt lgkmcnt(0)
	s_barrier
	s_setprio 1
	s_waitcnt lgkmcnt(0)
	v_mfma_f32_16x16x32_bf16 v[124:127], v[156:159], v[198:201], v[124:127]
	v_mfma_f32_16x16x32_bf16 v[120:123], v[164:167], v[198:201], v[120:123]
	v_mfma_f32_16x16x32_bf16 v[108:111], v[156:159], v[206:209], v[108:111]
	v_mfma_f32_16x16x32_bf16 v[104:107], v[164:167], v[206:209], v[104:107]
	v_mfma_f32_16x16x32_bf16 v[92:95], v[156:159], v[214:217], v[92:95]
	v_mfma_f32_16x16x32_bf16 v[88:91], v[164:167], v[214:217], v[88:91]
	v_mfma_f32_16x16x32_bf16 v[76:79], v[156:159], v[222:225], v[76:79]
	v_mfma_f32_16x16x32_bf16 v[72:75], v[164:167], v[222:225], v[72:75]
	v_mfma_f32_16x16x32_bf16 v[124:127], v[160:163], v[202:205], v[124:127]
	v_mfma_f32_16x16x32_bf16 v[120:123], v[168:171], v[202:205], v[120:123]
	v_mfma_f32_16x16x32_bf16 v[108:111], v[160:163], v[210:213], v[108:111]
	v_mfma_f32_16x16x32_bf16 v[104:107], v[168:171], v[210:213], v[104:107]
	v_mfma_f32_16x16x32_bf16 v[92:95], v[160:163], v[218:221], v[92:95]
	v_mfma_f32_16x16x32_bf16 v[88:91], v[168:171], v[218:221], v[88:91]
	v_mfma_f32_16x16x32_bf16 v[76:79], v[160:163], v[226:229], v[76:79]
	v_mfma_f32_16x16x32_bf16 v[72:75], v[168:171], v[226:229], v[72:75]
	s_setprio 0
	s_setprio 1
	v_mfma_f32_16x16x32_bf16 v[116:119], v[172:175], v[198:201], v[116:119]
	v_mfma_f32_16x16x32_bf16 v[112:115], v[184:187], v[198:201], v[112:115]
	v_mfma_f32_16x16x32_bf16 v[100:103], v[172:175], v[206:209], v[100:103]
	v_mfma_f32_16x16x32_bf16 v[96:99], v[184:187], v[206:209], v[96:99]
	v_mfma_f32_16x16x32_bf16 v[84:87], v[172:175], v[214:217], v[84:87]
	v_mfma_f32_16x16x32_bf16 v[80:83], v[184:187], v[214:217], v[80:83]
	v_mfma_f32_16x16x32_bf16 v[68:71], v[172:175], v[222:225], v[68:71]
	v_mfma_f32_16x16x32_bf16 v[64:67], v[184:187], v[222:225], v[64:67]
	v_mfma_f32_16x16x32_bf16 v[116:119], v[180:183], v[202:205], v[116:119]
	v_mfma_f32_16x16x32_bf16 v[112:115], v[188:191], v[202:205], v[112:115]
	v_mfma_f32_16x16x32_bf16 v[100:103], v[180:183], v[210:213], v[100:103]
	v_mfma_f32_16x16x32_bf16 v[96:99], v[188:191], v[210:213], v[96:99]
	v_mfma_f32_16x16x32_bf16 v[84:87], v[180:183], v[218:221], v[84:87]
	v_mfma_f32_16x16x32_bf16 v[80:83], v[188:191], v[218:221], v[80:83]
	v_mfma_f32_16x16x32_bf16 v[68:71], v[180:183], v[226:229], v[68:71]
	v_mfma_f32_16x16x32_bf16 v[64:67], v[188:191], v[226:229], v[64:67]
	s_setprio 0
	s_barrier
; #define PG8_STAGE(bufoff, gbase, voff) do { _Pragma("unroll") for (int _i = 0; _i < 2; ++_i) \
;         __builtin_amdgcn_global_load_lds((const unsigned*)((const char*)(gbase) + (voff)[_i]), (PG8_LAS unsigned*)(lds + (bufoff) + ldsw + _i * 8192), 16, 0, 0); } while (0)
; #define PG8_LDA(dst, b, h) do { _Pragma("unroll") for (int m = 0; m < 4; ++m) _Pragma("unroll") for (int k = 0; k < 2; ++k) dst[m][k] = *(const PG8_LAS bf16x8*)(lds + PG8_SA(b, h) + aoff + m * 2048 + k * 1024); } while (0)
; #define PG8_WAIT_V(n) asm volatile("s_waitcnt vmcnt(" #n ")" ::: "memory")
; #define PG8_WAIT_L(n) asm volatile("s_waitcnt lgkmcnt(" #n ")" ::: "memory")
; #define PG8_BAR __builtin_amdgcn_s_barrier()
; template <class Epi, class Sched, bool ALIGN_EPI = false, bool SP2 = false>
; __device__ __forceinline__ void gemm_phase(PG8_LAS unsigned char* lds, const Gemm g, const Sched& S, const Epi& E, int wave_in) {
;     ...
;         for (int t = 0; t < nt; t += 2) {
;             const bool last = (t == nt - 2);
;             const char* a1 = cA + (size_t)(t + 1) * kstep;
;             const char* a2 = last ? nA : cA + (size_t)(t + 2) * kstep; const char* b2 = last ? nB : cB + (size_t)(t + 2) * kstep;
;             const char* a3 = a2 + kstep; const char* b3 = b2 + kstep;
;             if (last && has_next) S.a_ready(nxt);
;             if constexpr (SP2) {
;             PG8_LDB(B0, 0, 0); PG8_LDB(B1, 0, 1); PG8_SCHED; PG8_LDA(At, 0, 0); PG8_STAGE(PG8_SA(1, 1), a1 + hstep, voffA);
;             PG8_WAIT_V(8); PG8_WAIT_L(0); PG8_BAR; PG8_MMA(0, 0, At, B0); PG8_MMA(0, 1, At, B1); PG8_BAR; PG8_SCHED;
;             PG8_LDA(At, 0, 1); PG8_STAGE(PG8_SB(0, 0), b2, voffB); PG8_STAGE(PG8_SB(0, 1), b2 + hstep, voffB); PG8_STAGE(PG8_SA(0, 0), a2, voffA);
;             PG8_WAIT_V(8); PG8_WAIT_L(0); PG8_BAR; PG8_MMA(1, 0, At, B0); PG8_MMA(1, 1, At, B1); PG8_BAR; PG8_SCHED;
;             PG8_LDB(B0, 1, 0); PG8_LDB(B1, 1, 1); PG8_SCHED; PG8_LDA(At, 1, 0); PG8_STAGE(PG8_SA(0, 1), a2 + hstep, voffA);
;             PG8_WAIT_V(8); PG8_WAIT_L(0); PG8_BAR; PG8_MMA(0, 0, At, B0); PG8_MMA(0, 1, At, B1); PG8_BAR; PG8_SCHED;
;             PG8_LDA(At, 1, 1); PG8_STAGE(PG8_SB(1, 0), b3, voffB); PG8_STAGE(PG8_SB(1, 1), b3 + hstep, voffB); PG8_STAGE(PG8_SA(1, 0), a3, voffA);
;             PG8_WAIT_V(8); PG8_WAIT_L(0); PG8_BAR; PG8_MMA(1, 0, At, B0); PG8_MMA(1, 1, At, B1); PG8_BAR; PG8_SCHED;
	s_add_i32 s10, s42, s66
	v_lshl_add_u64 v[230:231], v[230:231], 0, s[88:89]
	s_mov_b32 m0, s10
	ds_read_b128 v[198:201], v179 offset:49152
	ds_read_b128 v[202:205], v179 offset:50176
	ds_read_b128 v[206:209], v179 offset:51200
	ds_read_b128 v[210:213], v179 offset:52224
	ds_read_b128 v[214:217], v179 offset:53248
	ds_read_b128 v[218:221], v179 offset:54272
	ds_read_b128 v[222:225], v179 offset:55296
	ds_read_b128 v[226:229], v179 offset:56320
	global_load_lds_dwordx4 v[230:231], off
	s_add_i32 m0, s10, 0x2000
	s_add_u32 s4, s4, 0x40080
	v_lshl_add_u64 v[230:231], v[232:233], 0, s[88:89]
	s_addc_u32 s5, s5, 0
	s_add_i32 s10, s43, s66
	global_load_lds_dwordx4 v[230:231], off
	v_lshl_add_u64 v[230:231], s[4:5], 0, v[132:133]
	s_mov_b32 m0, s10
	s_nop 0
	global_load_lds_dwordx4 v[230:231], off
	v_lshl_add_u64 v[230:231], s[4:5], 0, v[128:129]
	s_add_i32 m0, s10, 0x2000
	s_nop 0
	global_load_lds_dwordx4 v[230:231], off
	v_lshl_add_u64 v[230:231], v[234:235], 0, s[88:89]
	s_mov_b32 m0, s72
	s_nop 0
	global_load_lds_dwordx4 v[230:231], off
	v_lshl_add_u64 v[230:231], v[236:237], 0, s[88:89]
	s_mov_b32 m0, s73
	s_nop 0
	global_load_lds_dwordx4 v[230:231], off
	s_waitcnt vmcnt(8)
	s_waitcnt lgkmcnt(0)
	s_barrier
	s_setprio 1
	s_waitcnt lgkmcnt(0)
	v_mfma_f32_16x16x32_bf16 v[60:63], v[156:159], v[198:201], v[60:63]
	v_mfma_f32_16x16x32_bf16 v[56:59], v[164:167], v[198:201], v[56:59]
	v_mfma_f32_16x16x32_bf16 v[44:47], v[156:159], v[206:209], v[44:47]
	v_mfma_f32_16x16x32_bf16 v[40:43], v[164:167], v[206:209], v[40:43]
	v_mfma_f32_16x16x32_bf16 v[28:31], v[156:159], v[214:217], v[28:31]
	v_mfma_f32_16x16x32_bf16 v[24:27], v[164:167], v[214:217], v[24:27]
	v_mfma_f32_16x16x32_bf16 v[12:15], v[156:159], v[222:225], v[12:15]
	v_mfma_f32_16x16x32_bf16 v[8:11], v[164:167], v[222:225], v[8:11]
	v_mfma_f32_16x16x32_bf16 v[60:63], v[160:163], v[202:205], v[60:63]
	v_mfma_f32_16x16x32_bf16 v[56:59], v[168:171], v[202:205], v[56:59]
	v_mfma_f32_16x16x32_bf16 v[44:47], v[160:163], v[210:213], v[44:47]
	v_mfma_f32_16x16x32_bf16 v[40:43], v[168:171], v[210:213], v[40:43]
	v_mfma_f32_16x16x32_bf16 v[28:31], v[160:163], v[218:221], v[28:31]
	v_mfma_f32_16x16x32_bf16 v[24:27], v[168:171], v[218:221], v[24:27]
	v_mfma_f32_16x16x32_bf16 v[12:15], v[160:163], v[226:229], v[12:15]
	v_mfma_f32_16x16x32_bf16 v[8:11], v[168:171], v[226:229], v[8:11]
	s_setprio 0
	s_setprio 1
	v_mfma_f32_16x16x32_bf16 v[52:55], v[172:175], v[198:201], v[52:55]
	v_mfma_f32_16x16x32_bf16 v[48:51], v[184:187], v[198:201], v[48:51]
	v_mfma_f32_16x16x32_bf16 v[36:39], v[172:175], v[206:209], v[36:39]
	v_mfma_f32_16x16x32_bf16 v[32:35], v[184:187], v[206:209], v[32:35]
	v_mfma_f32_16x16x32_bf16 v[20:23], v[172:175], v[214:217], v[20:23]
	v_mfma_f32_16x16x32_bf16 v[16:19], v[184:187], v[214:217], v[16:19]
	v_mfma_f32_16x16x32_bf16 v[4:7], v[172:175], v[222:225], v[4:7]
	v_mfma_f32_16x16x32_bf16 v[0:3], v[184:187], v[222:225], v[0:3]
	v_mfma_f32_16x16x32_bf16 v[52:55], v[180:183], v[202:205], v[52:55]
	v_mfma_f32_16x16x32_bf16 v[48:51], v[188:191], v[202:205], v[48:51]
	v_mfma_f32_16x16x32_bf16 v[36:39], v[180:183], v[210:213], v[36:39]
	v_mfma_f32_16x16x32_bf16 v[32:35], v[188:191], v[210:213], v[32:35]
	v_mfma_f32_16x16x32_bf16 v[20:23], v[180:183], v[218:221], v[20:23]
	v_mfma_f32_16x16x32_bf16 v[16:19], v[188:191], v[218:221], v[16:19]
	v_mfma_f32_16x16x32_bf16 v[4:7], v[180:183], v[226:229], v[4:7]
	v_mfma_f32_16x16x32_bf16 v[0:3], v[188:191], v[226:229], v[0:3]
	s_setprio 0
	s_add_i32 s34, s34, 2
	s_add_u32 s31, s31, 0x100
	s_addc_u32 s33, s33, 0
	s_add_u32 s0, s0, 0x100
	s_addc_u32 s1, s1, 0
	s_cmp_gt_u32 s34, 13
	s_cbranch_scc1 .Lxbar_1
	s_add_u32 s4, s0, 0xfffc0080
	s_addc_u32 s5, s1, -1
	s_add_i32 s42, s35, 0x100
	s_cmp_eq_u32 s34, 12
	s_cselect_b32 s11, s8, s5
	s_cselect_b32 s10, s9, s4
	s_cselect_b32 s5, s16, s33
	s_cselect_b32 s4, s17, s31
	s_add_i32 s44, s90, 0x100
.Lhbar_1:
	s_barrier
.LBB0_273:
	v_add_u32_e32 v168, s42, v177
	v_add_u32_e32 v188, s44, v177
	ds_read_b128 v[156:159], v168
	ds_read_b128 v[160:163], v168 offset:1024
	ds_read_b128 v[164:167], v168 offset:2048
	ds_read_b128 v[168:171], v168 offset:3072
	ds_read_b128 v[172:175], v188
	ds_read_b128 v[180:183], v188 offset:1024
	ds_read_b128 v[184:187], v188 offset:2048
	ds_read_b128 v[188:191], v188 offset:3072
	v_lshl_add_u64 v[230:231], s[0:1], 0, v[154:155]
	s_add_i32 m0, s67, 0xc000
	ds_read_b128 v[198:201], v179
	ds_read_b128 v[202:205], v179 offset:1024
	ds_read_b128 v[206:209], v179 offset:2048
	ds_read_b128 v[210:213], v179 offset:3072
	ds_read_b128 v[214:217], v179 offset:4096
	ds_read_b128 v[218:221], v179 offset:5120
	ds_read_b128 v[222:225], v179 offset:6144
	ds_read_b128 v[226:229], v179 offset:7168
	global_load_lds_dwordx4 v[230:231], off
	v_lshl_add_u64 v[230:231], s[0:1], 0, v[152:153]
	s_add_i32 m0, s67, 0xe000
	s_nop 0
	global_load_lds_dwordx4 v[230:231], off
	s_waitcnt vmcnt(8)
	s_waitcnt lgkmcnt(0)
	s_barrier
; #define PG8_STAGE(bufoff, gbase, voff) do { _Pragma("unroll") for (int _i = 0; _i < 2; ++_i) \
;         __builtin_amdgcn_global_load_lds((const unsigned*)((const char*)(gbase) + (voff)[_i]), (PG8_LAS unsigned*)(lds + (bufoff) + ldsw + _i * 8192), 16, 0, 0); } while (0)
; #define PG8_LDA(dst, b, h) do { _Pragma("unroll") for (int m = 0; m < 4; ++m) _Pragma("unroll") for (int k = 0; k < 2; ++k) dst[m][k] = *(const PG8_LAS bf16x8*)(lds + PG8_SA(b, h) + aoff + m * 2048 + k * 1024); } while (0)
; #define PG8_LDB(dst, b, h) do { _Pragma("unroll") for (int n = 0; n < 2; ++n) _Pragma("unroll") for (int k = 0; k < 2; ++k) dst[n][k] = *(const PG8_LAS bf16x8*)(lds + PG8_SB(b, h) + boff + n * 2048 + k * 1024); } while (0)
; #define PG8_MMA(ai, bj, At, Bt) do { __builtin_amdgcn_s_setprio(1); _Pragma("unroll") for (int m = 0; m < 4; ++m) _Pragma("unroll") for (int n = 0; n < 2; ++n) _Pragma("unroll") for (int k = 0; k < 2; ++k) \
;         acc[ai][bj][m][n] = __builtin_amdgcn_mfma_f32_16x16x32_bf16(Bt[n][k], At[m][k], acc[ai][bj][m][n], 0, 0, 0); __builtin_amdgcn_s_setprio(0); } while (0)
; #define PG8_BAR __builtin_amdgcn_s_barrier()
; template <class Epi, class Sched, bool ALIGN_EPI = false, bool SP2 = false>
; __device__ __forceinline__ void gemm_phase(PG8_LAS unsigned char* lds, const Gemm g, const Sched& S, const Epi& E, int wave_in) {
;     ...
;             PG8_LDB(B0, 0, 0); PG8_LDB(B1, 0, 1); PG8_SCHED; PG8_LDA(At, 0, 0); PG8_STAGE(PG8_SA(1, 1), a1 + hstep, voffA);
;             PG8_WAIT_V(8); PG8_WAIT_L(0); PG8_BAR; PG8_MMA(0, 0, At, B0); PG8_MMA(0, 1, At, B1); PG8_BAR; PG8_SCHED;
;             PG8_LDA(At, 0, 1); PG8_STAGE(PG8_SB(0, 0), b2, voffB); PG8_STAGE(PG8_SB(0, 1), b2 + hstep, voffB); PG8_STAGE(PG8_SA(0, 0), a2, voffA);
;             PG8_WAIT_V(8); PG8_WAIT_L(0); PG8_BAR; PG8_MMA(1, 0, At, B0); PG8_MMA(1, 1, At, B1); PG8_BAR; PG8_SCHED;
;             PG8_LDB(B0, 1, 0); PG8_LDB(B1, 1, 1); PG8_SCHED; PG8_LDA(At, 1, 0); PG8_STAGE(PG8_SA(0, 1), a2 + hstep, voffA);
;             PG8_WAIT_V(8); PG8_WAIT_L(0); PG8_BAR; PG8_MMA(0, 0, At, B0); PG8_MMA(0, 1, At, B1); PG8_BAR; PG8_SCHED;
;             PG8_LDA(At, 1, 1); PG8_STAGE(PG8_SB(1, 0), b3, voffB); PG8_STAGE(PG8_SB(1, 1), b3 + hstep, voffB); PG8_STAGE(PG8_SA(1, 0), a3, voffA);
;             PG8_WAIT_V(8); PG8_WAIT_L(0); PG8_BAR; PG8_MMA(1, 0, At, B0); PG8_MMA(1, 1, At, B1); PG8_BAR; PG8_SCHED;
	s_setprio 1
	s_waitcnt lgkmcnt(0)
	v_mfma_f32_16x16x32_bf16 v[124:127], v[156:159], v[198:201], v[124:127]
	v_mfma_f32_16x16x32_bf16 v[120:123], v[164:167], v[198:201], v[120:123]
	v_mfma_f32_16x16x32_bf16 v[108:111], v[156:159], v[206:209], v[108:111]
	v_mfma_f32_16x16x32_bf16 v[104:107], v[164:167], v[206:209], v[104:107]
	v_mfma_f32_16x16x32_bf16 v[92:95], v[156:159], v[214:217], v[92:95]
	v_mfma_f32_16x16x32_bf16 v[88:91], v[164:167], v[214:217], v[88:91]
	v_mfma_f32_16x16x32_bf16 v[76:79], v[156:159], v[222:225], v[76:79]
	v_mfma_f32_16x16x32_bf16 v[72:75], v[164:167], v[222:225], v[72:75]
	v_mfma_f32_16x16x32_bf16 v[124:127], v[160:163], v[202:205], v[124:127]
	v_mfma_f32_16x16x32_bf16 v[120:123], v[168:171], v[202:205], v[120:123]
	v_mfma_f32_16x16x32_bf16 v[108:111], v[160:163], v[210:213], v[108:111]
	v_mfma_f32_16x16x32_bf16 v[104:107], v[168:171], v[210:213], v[104:107]
	v_mfma_f32_16x16x32_bf16 v[92:95], v[160:163], v[218:221], v[92:95]
	v_mfma_f32_16x16x32_bf16 v[88:91], v[168:171], v[218:221], v[88:91]
	v_mfma_f32_16x16x32_bf16 v[76:79], v[160:163], v[226:229], v[76:79]
	v_mfma_f32_16x16x32_bf16 v[72:75], v[168:171], v[226:229], v[72:75]
	s_setprio 0
	s_setprio 1
	v_mfma_f32_16x16x32_bf16 v[116:119], v[172:175], v[198:201], v[116:119]
	v_mfma_f32_16x16x32_bf16 v[112:115], v[184:187], v[198:201], v[112:115]
	v_mfma_f32_16x16x32_bf16 v[100:103], v[172:175], v[206:209], v[100:103]
	v_mfma_f32_16x16x32_bf16 v[96:99], v[184:187], v[206:209], v[96:99]
	v_mfma_f32_16x16x32_bf16 v[84:87], v[172:175], v[214:217], v[84:87]
	v_mfma_f32_16x16x32_bf16 v[80:83], v[184:187], v[214:217], v[80:83]
	v_mfma_f32_16x16x32_bf16 v[68:71], v[172:175], v[222:225], v[68:71]
	v_mfma_f32_16x16x32_bf16 v[64:67], v[184:187], v[222:225], v[64:67]
	v_mfma_f32_16x16x32_bf16 v[116:119], v[180:183], v[202:205], v[116:119]
	v_mfma_f32_16x16x32_bf16 v[112:115], v[188:191], v[202:205], v[112:115]
	v_mfma_f32_16x16x32_bf16 v[100:103], v[180:183], v[210:213], v[100:103]
	v_mfma_f32_16x16x32_bf16 v[96:99], v[188:191], v[210:213], v[96:99]
	v_mfma_f32_16x16x32_bf16 v[84:87], v[180:183], v[218:221], v[84:87]
	v_mfma_f32_16x16x32_bf16 v[80:83], v[188:191], v[218:221], v[80:83]
	v_mfma_f32_16x16x32_bf16 v[68:71], v[180:183], v[226:229], v[68:71]
	v_mfma_f32_16x16x32_bf16 v[64:67], v[188:191], v[226:229], v[64:67]
	s_setprio 0
	s_barrier
	s_add_i32 s42, s42, s66
	v_lshl_add_u64 v[230:231], s[4:5], 0, v[132:133]
	s_mov_b32 m0, s42
	ds_read_b128 v[198:201], v179 offset:16384
	ds_read_b128 v[202:205], v179 offset:17408
	ds_read_b128 v[206:209], v179 offset:18432
	ds_read_b128 v[210:213], v179 offset:19456
	ds_read_b128 v[214:217], v179 offset:20480
	ds_read_b128 v[218:221], v179 offset:21504
	ds_read_b128 v[222:225], v179 offset:22528
	ds_read_b128 v[226:229], v179 offset:23552
	global_load_lds_dwordx4 v[230:231], off
	s_add_i32 m0, s42, 0x2000
	s_add_u32 s42, s4, 0x40000
	v_lshl_add_u64 v[232:233], s[4:5], 0, v[128:129]
	s_addc_u32 s43, s5, 0
	s_add_i32 s44, s44, s66
	global_load_lds_dwordx4 v[232:233], off
	v_lshl_add_u64 v[234:235], s[42:43], 0, v[132:133]
	s_mov_b32 m0, s44
	v_lshl_add_u64 v[236:237], s[10:11], 0, v[130:131]
	global_load_lds_dwordx4 v[234:235], off
	v_lshl_add_u64 v[234:235], s[42:43], 0, v[128:129]
	s_add_i32 m0, s44, 0x2000
	s_nop 0
	global_load_lds_dwordx4 v[234:235], off
	v_lshl_add_u64 v[234:235], s[10:11], 0, v[134:135]
	s_mov_b32 m0, s67
	s_nop 0
	global_load_lds_dwordx4 v[234:235], off
	s_mov_b32 m0, s78
	s_nop 0
	global_load_lds_dwordx4 v[236:237], off
	s_waitcnt vmcnt(8)
	s_waitcnt lgkmcnt(0)
	s_barrier
	s_setprio 1
	s_waitcnt lgkmcnt(0)
	v_mfma_f32_16x16x32_bf16 v[60:63], v[156:159], v[198:201], v[60:63]
	v_mfma_f32_16x16x32_bf16 v[56:59], v[164:167], v[198:201], v[56:59]
	v_mfma_f32_16x16x32_bf16 v[44:47], v[156:159], v[206:209], v[44:47]
	v_mfma_f32_16x16x32_bf16 v[40:43], v[164:167], v[206:209], v[40:43]
	v_mfma_f32_16x16x32_bf16 v[28:31], v[156:159], v[214:217], v[28:31]
	v_mfma_f32_16x16x32_bf16 v[24:27], v[164:167], v[214:217], v[24:27]
	v_mfma_f32_16x16x32_bf16 v[12:15], v[156:159], v[222:225], v[12:15]
	v_mfma_f32_16x16x32_bf16 v[8:11], v[164:167], v[222:225], v[8:11]
	v_mfma_f32_16x16x32_bf16 v[60:63], v[160:163], v[202:205], v[60:63]
	v_mfma_f32_16x16x32_bf16 v[56:59], v[168:171], v[202:205], v[56:59]
	v_mfma_f32_16x16x32_bf16 v[44:47], v[160:163], v[210:213], v[44:47]
	v_mfma_f32_16x16x32_bf16 v[40:43], v[168:171], v[210:213], v[40:43]
	v_mfma_f32_16x16x32_bf16 v[28:31], v[160:163], v[218:221], v[28:31]
	v_mfma_f32_16x16x32_bf16 v[24:27], v[168:171], v[218:221], v[24:27]
	v_mfma_f32_16x16x32_bf16 v[12:15], v[160:163], v[226:229], v[12:15]
	v_mfma_f32_16x16x32_bf16 v[8:11], v[168:171], v[226:229], v[8:11]
	s_setprio 0
	s_setprio 1
	v_mfma_f32_16x16x32_bf16 v[52:55], v[172:175], v[198:201], v[52:55]
	v_mfma_f32_16x16x32_bf16 v[48:51], v[184:187], v[198:201], v[48:51]
	v_mfma_f32_16x16x32_bf16 v[36:39], v[172:175], v[206:209], v[36:39]
	v_mfma_f32_16x16x32_bf16 v[32:35], v[184:187], v[206:209], v[32:35]
	v_mfma_f32_16x16x32_bf16 v[20:23], v[172:175], v[214:217], v[20:23]
	v_mfma_f32_16x16x32_bf16 v[16:19], v[184:187], v[214:217], v[16:19]
	v_mfma_f32_16x16x32_bf16 v[4:7], v[172:175], v[222:225], v[4:7]
	v_mfma_f32_16x16x32_bf16 v[0:3], v[184:187], v[222:225], v[0:3]
	v_mfma_f32_16x16x32_bf16 v[52:55], v[180:183], v[202:205], v[52:55]
	v_mfma_f32_16x16x32_bf16 v[48:51], v[188:191], v[202:205], v[48:51]
	v_mfma_f32_16x16x32_bf16 v[36:39], v[180:183], v[210:213], v[36:39]
	v_mfma_f32_16x16x32_bf16 v[32:35], v[188:191], v[210:213], v[32:35]
	v_mfma_f32_16x16x32_bf16 v[20:23], v[180:183], v[218:221], v[20:23]
	v_mfma_f32_16x16x32_bf16 v[16:19], v[188:191], v[218:221], v[16:19]
	v_mfma_f32_16x16x32_bf16 v[4:7], v[180:183], v[226:229], v[4:7]
	v_mfma_f32_16x16x32_bf16 v[0:3], v[188:191], v[226:229], v[0:3]
	s_setprio 0
	s_barrier
; #define PG8_STAGE(bufoff, gbase, voff) do { _Pragma("unroll") for (int _i = 0; _i < 2; ++_i) \
;         __builtin_amdgcn_global_load_lds((const unsigned*)((const char*)(gbase) + (voff)[_i]), (PG8_LAS unsigned*)(lds + (bufoff) + ldsw + _i * 8192), 16, 0, 0); } while (0)
; #define PG8_LDA(dst, b, h) do { _Pragma("unroll") for (int m = 0; m < 4; ++m) _Pragma("unroll") for (int k = 0; k < 2; ++k) dst[m][k] = *(const PG8_LAS bf16x8*)(lds + PG8_SA(b, h) + aoff + m * 2048 + k * 1024); } while (0)
; #define PG8_LDB(dst, b, h) do { _Pragma("unroll") for (int n = 0; n < 2; ++n) _Pragma("unroll") for (int k = 0; k < 2; ++k) dst[n][k] = *(const PG8_LAS bf16x8*)(lds + PG8_SB(b, h) + boff + n * 2048 + k * 1024); } while (0)
; #define PG8_MMA(ai, bj, At, Bt) do { __builtin_amdgcn_s_setprio(1); _Pragma("unroll") for (int m = 0; m < 4; ++m) _Pragma("unroll") for (int n = 0; n < 2; ++n) _Pragma("unroll") for (int k = 0; k < 2; ++k) \
;         acc[ai][bj][m][n] = __builtin_amdgcn_mfma_f32_16x16x32_bf16(Bt[n][k], At[m][k], acc[ai][bj][m][n], 0, 0, 0); __builtin_amdgcn_s_setprio(0); } while (0)
; #define PG8_WAIT_V(n) asm volatile("s_waitcnt vmcnt(" #n ")" ::: "memory")
; #define PG8_WAIT_L(n) asm volatile("s_waitcnt lgkmcnt(" #n ")" ::: "memory")
; #define PG8_BAR __builtin_amdgcn_s_barrier()
; #define PG8_SCHED __builtin_amdgcn_sched_barrier(0)
; template <class Epi, class Sched, bool ALIGN_EPI = false, bool SP2 = false>
; __device__ __forceinline__ void gemm_phase(PG8_LAS unsigned char* lds, const Gemm g, const Sched& S, const Epi& E, int wave_in) {
;     ...
;             PG8_LDB(B0, 1, 0); PG8_LDB(B1, 1, 1); PG8_SCHED; PG8_LDA(At, 1, 0); PG8_STAGE(PG8_SA(0, 1), a2 + hstep, voffA);
;             PG8_WAIT_V(8); PG8_WAIT_L(0); PG8_BAR; PG8_MMA(0, 0, At, B0); PG8_MMA(0, 1, At, B1); PG8_BAR; PG8_SCHED;
;             PG8_LDA(At, 1, 1); PG8_STAGE(PG8_SB(1, 0), b3, voffB); PG8_STAGE(PG8_SB(1, 1), b3 + hstep, voffB); PG8_STAGE(PG8_SA(1, 0), a3, voffA);
;             PG8_WAIT_V(8); PG8_WAIT_L(0); PG8_BAR; PG8_MMA(1, 0, At, B0); PG8_MMA(1, 1, At, B1); PG8_BAR; PG8_SCHED;
	s_add_i32 s42, s65, 0x100
	s_add_i32 s43, s52, 0x100
	v_add_u32_e32 v168, s42, v177
	v_add_u32_e32 v188, s43, v177
	ds_read_b128 v[156:159], v168
	ds_read_b128 v[160:163], v168 offset:1024
	ds_read_b128 v[164:167], v168 offset:2048
	ds_read_b128 v[168:171], v168 offset:3072
	ds_read_b128 v[172:175], v188
	ds_read_b128 v[180:183], v188 offset:1024
	ds_read_b128 v[184:187], v188 offset:2048
	ds_read_b128 v[188:191], v188 offset:3072
	s_add_u32 s10, s10, 0x40000
	s_addc_u32 s11, s11, 0
	s_mov_b32 m0, s79
	v_lshl_add_u64 v[238:239], s[10:11], 0, v[134:135]
	ds_read_b128 v[198:201], v179 offset:32768
	ds_read_b128 v[202:205], v179 offset:33792
	ds_read_b128 v[206:209], v179 offset:34816
	ds_read_b128 v[210:213], v179 offset:35840
	ds_read_b128 v[214:217], v179 offset:36864
	ds_read_b128 v[218:221], v179 offset:37888
	ds_read_b128 v[222:225], v179 offset:38912
	ds_read_b128 v[226:229], v179 offset:39936
	global_load_lds_dwordx4 v[238:239], off
	v_lshl_add_u64 v[238:239], s[10:11], 0, v[130:131]
	s_mov_b32 m0, s82
	s_nop 0
	global_load_lds_dwordx4 v[238:239], off
	s_waitcnt vmcnt(8)
	s_waitcnt lgkmcnt(0)
	s_barrier
	s_setprio 1
	s_waitcnt lgkmcnt(0)
	v_mfma_f32_16x16x32_bf16 v[124:127], v[156:159], v[198:201], v[124:127]
	v_mfma_f32_16x16x32_bf16 v[120:123], v[164:167], v[198:201], v[120:123]
	v_mfma_f32_16x16x32_bf16 v[108:111], v[156:159], v[206:209], v[108:111]
	v_mfma_f32_16x16x32_bf16 v[104:107], v[164:167], v[206:209], v[104:107]
	v_mfma_f32_16x16x32_bf16 v[92:95], v[156:159], v[214:217], v[92:95]
	v_mfma_f32_16x16x32_bf16 v[88:91], v[164:167], v[214:217], v[88:91]
	v_mfma_f32_16x16x32_bf16 v[76:79], v[156:159], v[222:225], v[76:79]
	v_mfma_f32_16x16x32_bf16 v[72:75], v[164:167], v[222:225], v[72:75]
	v_mfma_f32_16x16x32_bf16 v[124:127], v[160:163], v[202:205], v[124:127]
	v_mfma_f32_16x16x32_bf16 v[120:123], v[168:171], v[202:205], v[120:123]
	v_mfma_f32_16x16x32_bf16 v[108:111], v[160:163], v[210:213], v[108:111]
	v_mfma_f32_16x16x32_bf16 v[104:107], v[168:171], v[210:213], v[104:107]
	v_mfma_f32_16x16x32_bf16 v[92:95], v[160:163], v[218:221], v[92:95]
	v_mfma_f32_16x16x32_bf16 v[88:91], v[168:171], v[218:221], v[88:91]
	v_mfma_f32_16x16x32_bf16 v[76:79], v[160:163], v[226:229], v[76:79]
	v_mfma_f32_16x16x32_bf16 v[72:75], v[168:171], v[226:229], v[72:75]
	s_setprio 0
	s_setprio 1
	v_mfma_f32_16x16x32_bf16 v[116:119], v[172:175], v[198:201], v[116:119]
	v_mfma_f32_16x16x32_bf16 v[112:115], v[184:187], v[198:201], v[112:115]
	v_mfma_f32_16x16x32_bf16 v[100:103], v[172:175], v[206:209], v[100:103]
	v_mfma_f32_16x16x32_bf16 v[96:99], v[184:187], v[206:209], v[96:99]
	v_mfma_f32_16x16x32_bf16 v[84:87], v[172:175], v[214:217], v[84:87]
	v_mfma_f32_16x16x32_bf16 v[80:83], v[184:187], v[214:217], v[80:83]
	v_mfma_f32_16x16x32_bf16 v[68:71], v[172:175], v[222:225], v[68:71]
	v_mfma_f32_16x16x32_bf16 v[64:67], v[184:187], v[222:225], v[64:67]
	v_mfma_f32_16x16x32_bf16 v[116:119], v[180:183], v[202:205], v[116:119]
	v_mfma_f32_16x16x32_bf16 v[112:115], v[188:191], v[202:205], v[112:115]
	v_mfma_f32_16x16x32_bf16 v[100:103], v[180:183], v[210:213], v[100:103]
	v_mfma_f32_16x16x32_bf16 v[96:99], v[188:191], v[210:213], v[96:99]
	v_mfma_f32_16x16x32_bf16 v[84:87], v[180:183], v[218:221], v[84:87]
	v_mfma_f32_16x16x32_bf16 v[80:83], v[188:191], v[218:221], v[80:83]
	v_mfma_f32_16x16x32_bf16 v[68:71], v[180:183], v[226:229], v[68:71]
	v_mfma_f32_16x16x32_bf16 v[64:67], v[188:191], v[226:229], v[64:67]
	s_setprio 0
	s_barrier
; #define PG8_STAGE(bufoff, gbase, voff) do { _Pragma("unroll") for (int _i = 0; _i < 2; ++_i) \
;         __builtin_amdgcn_global_load_lds((const unsigned*)((const char*)(gbase) + (voff)[_i]), (PG8_LAS unsigned*)(lds + (bufoff) + ldsw + _i * 8192), 16, 0, 0); } while (0)
; #define PG8_LDA(dst, b, h) do { _Pragma("unroll") for (int m = 0; m < 4; ++m) _Pragma("unroll") for (int k = 0; k < 2; ++k) dst[m][k] = *(const PG8_LAS bf16x8*)(lds + PG8_SA(b, h) + aoff + m * 2048 + k * 1024); } while (0)
; #define PG8_WAIT_V(n) asm volatile("s_waitcnt vmcnt(" #n ")" ::: "memory")
; #define PG8_WAIT_L(n) asm volatile("s_waitcnt lgkmcnt(" #n ")" ::: "memory")
; #define PG8_BAR __builtin_amdgcn_s_barrier()
; template <class Epi, class Sched, bool ALIGN_EPI = false, bool SP2 = false>
; __device__ __forceinline__ void gemm_phase(PG8_LAS unsigned char* lds, const Gemm g, const Sched& S, const Epi& E, int wave_in) {
;     ...
;         for (int t = 0; t < nt; t += 2) {
;             const bool last = (t == nt - 2);
;             const char* a1 = cA + (size_t)(t + 1) * kstep;
;             const char* a2 = last ? nA : cA + (size_t)(t + 2) * kstep; const char* b2 = last ? nB : cB + (size_t)(t + 2) * kstep;
;             const char* a3 = a2 + kstep; const char* b3 = b2 + kstep;
;             if (last && has_next) S.a_ready(nxt);
;             if constexpr (SP2) {
;             PG8_LDB(B0, 0, 0); PG8_LDB(B1, 0, 1); PG8_SCHED; PG8_LDA(At, 0, 0); PG8_STAGE(PG8_SA(1, 1), a1 + hstep, voffA);
;             PG8_WAIT_V(8); PG8_WAIT_L(0); PG8_BAR; PG8_MMA(0, 0, At, B0); PG8_MMA(0, 1, At, B1); PG8_BAR; PG8_SCHED;
;             PG8_LDA(At, 0, 1); PG8_STAGE(PG8_SB(0, 0), b2, voffB); PG8_STAGE(PG8_SB(0, 1), b2 + hstep, voffB); PG8_STAGE(PG8_SA(0, 0), a2, voffA);
;             PG8_WAIT_V(8); PG8_WAIT_L(0); PG8_BAR; PG8_MMA(1, 0, At, B0); PG8_MMA(1, 1, At, B1); PG8_BAR; PG8_SCHED;
;             PG8_LDB(B0, 1, 0); PG8_LDB(B1, 1, 1); PG8_SCHED; PG8_LDA(At, 1, 0); PG8_STAGE(PG8_SA(0, 1), a2 + hstep, voffA);
;             PG8_WAIT_V(8); PG8_WAIT_L(0); PG8_BAR; PG8_MMA(0, 0, At, B0); PG8_MMA(0, 1, At, B1); PG8_BAR; PG8_SCHED;
;             PG8_LDA(At, 1, 1); PG8_STAGE(PG8_SB(1, 0), b3, voffB); PG8_STAGE(PG8_SB(1, 1), b3 + hstep, voffB); PG8_STAGE(PG8_SA(1, 0), a3, voffA);
;             PG8_WAIT_V(8); PG8_WAIT_L(0); PG8_BAR; PG8_MMA(1, 0, At, B0); PG8_MMA(1, 1, At, B1); PG8_BAR; PG8_SCHED;
	s_add_i32 s10, s42, s66
	v_lshl_add_u64 v[230:231], v[230:231], 0, s[88:89]
	s_mov_b32 m0, s10
	ds_read_b128 v[198:201], v179 offset:49152
	ds_read_b128 v[202:205], v179 offset:50176
	ds_read_b128 v[206:209], v179 offset:51200
	ds_read_b128 v[210:213], v179 offset:52224
	ds_read_b128 v[214:217], v179 offset:53248
	ds_read_b128 v[218:221], v179 offset:54272
	ds_read_b128 v[222:225], v179 offset:55296
	ds_read_b128 v[226:229], v179 offset:56320
	global_load_lds_dwordx4 v[230:231], off
	s_add_i32 m0, s10, 0x2000
	s_add_u32 s4, s4, 0x40080
	v_lshl_add_u64 v[230:231], v[232:233], 0, s[88:89]
	s_addc_u32 s5, s5, 0
	s_add_i32 s10, s43, s66
	global_load_lds_dwordx4 v[230:231], off
	v_lshl_add_u64 v[230:231], s[4:5], 0, v[132:133]
	s_mov_b32 m0, s10
	s_nop 0
	global_load_lds_dwordx4 v[230:231], off
	v_lshl_add_u64 v[230:231], s[4:5], 0, v[128:129]
	s_add_i32 m0, s10, 0x2000
	s_nop 0
	global_load_lds_dwordx4 v[230:231], off
	v_lshl_add_u64 v[230:231], v[234:235], 0, s[88:89]
	s_mov_b32 m0, s72
	s_nop 0
	global_load_lds_dwordx4 v[230:231], off
	v_lshl_add_u64 v[230:231], v[236:237], 0, s[88:89]
	s_mov_b32 m0, s73
	s_nop 0
	global_load_lds_dwordx4 v[230:231], off
	s_waitcnt vmcnt(8)
	s_waitcnt lgkmcnt(0)
	s_barrier
	s_setprio 1
	s_waitcnt lgkmcnt(0)
	v_mfma_f32_16x16x32_bf16 v[60:63], v[156:159], v[198:201], v[60:63]
	v_mfma_f32_16x16x32_bf16 v[56:59], v[164:167], v[198:201], v[56:59]
	v_mfma_f32_16x16x32_bf16 v[44:47], v[156:159], v[206:209], v[44:47]
	v_mfma_f32_16x16x32_bf16 v[40:43], v[164:167], v[206:209], v[40:43]
	v_mfma_f32_16x16x32_bf16 v[28:31], v[156:159], v[214:217], v[28:31]
	v_mfma_f32_16x16x32_bf16 v[24:27], v[164:167], v[214:217], v[24:27]
	v_mfma_f32_16x16x32_bf16 v[12:15], v[156:159], v[222:225], v[12:15]
	v_mfma_f32_16x16x32_bf16 v[8:11], v[164:167], v[222:225], v[8:11]
	v_mfma_f32_16x16x32_bf16 v[60:63], v[160:163], v[202:205], v[60:63]
	v_mfma_f32_16x16x32_bf16 v[56:59], v[168:171], v[202:205], v[56:59]
	v_mfma_f32_16x16x32_bf16 v[44:47], v[160:163], v[210:213], v[44:47]
	v_mfma_f32_16x16x32_bf16 v[40:43], v[168:171], v[210:213], v[40:43]
	v_mfma_f32_16x16x32_bf16 v[28:31], v[160:163], v[218:221], v[28:31]
	v_mfma_f32_16x16x32_bf16 v[24:27], v[168:171], v[218:221], v[24:27]
	v_mfma_f32_16x16x32_bf16 v[12:15], v[160:163], v[226:229], v[12:15]
	v_mfma_f32_16x16x32_bf16 v[8:11], v[168:171], v[226:229], v[8:11]
	s_setprio 0
	s_setprio 1
	v_mfma_f32_16x16x32_bf16 v[52:55], v[172:175], v[198:201], v[52:55]
	v_mfma_f32_16x16x32_bf16 v[48:51], v[184:187], v[198:201], v[48:51]
	v_mfma_f32_16x16x32_bf16 v[36:39], v[172:175], v[206:209], v[36:39]
	v_mfma_f32_16x16x32_bf16 v[32:35], v[184:187], v[206:209], v[32:35]
	v_mfma_f32_16x16x32_bf16 v[20:23], v[172:175], v[214:217], v[20:23]
	v_mfma_f32_16x16x32_bf16 v[16:19], v[184:187], v[214:217], v[16:19]
	v_mfma_f32_16x16x32_bf16 v[4:7], v[172:175], v[222:225], v[4:7]
	v_mfma_f32_16x16x32_bf16 v[0:3], v[184:187], v[222:225], v[0:3]
	v_mfma_f32_16x16x32_bf16 v[52:55], v[180:183], v[202:205], v[52:55]
	v_mfma_f32_16x16x32_bf16 v[48:51], v[188:191], v[202:205], v[48:51]
	v_mfma_f32_16x16x32_bf16 v[36:39], v[180:183], v[210:213], v[36:39]
	v_mfma_f32_16x16x32_bf16 v[32:35], v[188:191], v[210:213], v[32:35]
	v_mfma_f32_16x16x32_bf16 v[20:23], v[180:183], v[218:221], v[20:23]
	v_mfma_f32_16x16x32_bf16 v[16:19], v[188:191], v[218:221], v[16:19]
	v_mfma_f32_16x16x32_bf16 v[4:7], v[180:183], v[226:229], v[4:7]
	v_mfma_f32_16x16x32_bf16 v[0:3], v[188:191], v[226:229], v[0:3]
	s_setprio 0
	s_add_i32 s34, s34, 2
	s_add_u32 s31, s31, 0x100
	s_addc_u32 s33, s33, 0
	s_add_u32 s0, s0, 0x100
	s_addc_u32 s1, s1, 0
	s_cmp_gt_u32 s34, 13
	s_cbranch_scc1 .Lxbar_1
	s_add_u32 s4, s0, 0xfffc0080
	s_addc_u32 s5, s1, -1
	s_add_i32 s42, s35, 0x100
	s_cmp_eq_u32 s34, 12
	s_cselect_b32 s11, s8, s5
	s_cselect_b32 s10, s9, s4
	s_cselect_b32 s5, s16, s33
	s_cselect_b32 s4, s17, s31
	s_add_i32 s44, s90, 0x100
	s_branch .Lhbar_1

; #define PG8_STAGE(bufoff, gbase, voff) do { _Pragma("unroll") for (int _i = 0; _i < 2; ++_i) \
;         __builtin_amdgcn_global_load_lds((const unsigned*)((const char*)(gbase) + (voff)[_i]), (PG8_LAS unsigned*)(lds + (bufoff) + ldsw + _i * 8192), 16, 0, 0); } while (0)
; #define PG8_WAIT_V(n) asm volatile("s_waitcnt vmcnt(" #n ")" ::: "memory")
; #define PG8_BAR __builtin_amdgcn_s_barrier()
; template <class Epi, class Sched, bool ALIGN_EPI = false, bool SP2 = false>
; __device__ __forceinline__ void gemm_phase(PG8_LAS unsigned char* lds, const Gemm g, const Sched& S, const Epi& E, int wave_in) {
;     ...
;         const bool has_next = S.next(ui + 1, nxt);
;         const char* nA = has_next ? (const char*)g.A + (size_t)(nxt.pm >> g.ash) * g.astride + (size_t)nxt.pm * tstep : cA; const char* nB = has_next ? (const char*)g.Bt + (size_t)(nxt.pm >> g.bsh) * g.bstride + (size_t)nxt.pn * tstep : cB;
;         for (int t = 0; t < nt; t += 2) {
;             const bool last = (t == nt - 2);
;             const char* a1 = cA + (size_t)(t + 1) * kstep;
;             const char* a2 = last ? nA : cA + (size_t)(t + 2) * kstep; const char* b2 = last ? nB : cB + (size_t)(t + 2) * kstep;
;             const char* a3 = a2 + kstep; const char* b3 = b2 + kstep;
;             if (last && has_next) S.a_ready(nxt);
;             if constexpr (SP2) {
;             PG8_LDB(B0, 0, 0); PG8_LDB(B1, 0, 1); PG8_SCHED; PG8_LDA(At, 0, 0); PG8_STAGE(PG8_SA(1, 1), a1 + hstep, voffA);
;             PG8_WAIT_V(8); PG8_WAIT_L(0); PG8_BAR; PG8_MMA(0, 0, At, B0); PG8_MMA(0, 1, At, B1); PG8_BAR; PG8_SCHED;
;             PG8_LDA(At, 0, 1); PG8_STAGE(PG8_SB(0, 0), b2, voffB); PG8_STAGE(PG8_SB(0, 1), b2 + hstep, voffB); PG8_STAGE(PG8_SA(0, 0), a2, voffA);
;             PG8_WAIT_V(8); PG8_WAIT_L(0); PG8_BAR; PG8_MMA(1, 0, At, B0); PG8_MMA(1, 1, At, B1); PG8_BAR; PG8_SCHED;
;             PG8_LDB(B0, 1, 0); PG8_LDB(B1, 1, 1); PG8_SCHED; PG8_LDA(At, 1, 0); PG8_STAGE(PG8_SA(0, 1), a2 + hstep, voffA);
;             PG8_WAIT_V(8); PG8_WAIT_L(0); PG8_BAR; PG8_MMA(0, 0, At, B0); PG8_MMA(0, 1, At, B1); PG8_BAR; PG8_SCHED;
;             PG8_LDA(At, 1, 1); PG8_STAGE(PG8_SB(1, 0), b3, voffB); PG8_STAGE(PG8_SB(1, 1), b3 + hstep, voffB); PG8_STAGE(PG8_SA(1, 0), a3, voffA);
;             PG8_WAIT_V(8); PG8_WAIT_L(0); PG8_BAR; PG8_MMA(1, 0, At, B0); PG8_MMA(1, 1, At, B1); PG8_BAR; PG8_SCHED;
.LBB0_589:
	s_ashr_i32 s15, s14, 31
	s_lshl_b64 s[20:21], s[14:15], 19
	s_add_u32 s20, s31, s20
	s_addc_u32 s21, s33, s21
	s_and_b64 s[26:27], s[44:45], exec
	s_cselect_b32 s15, s21, s23
	s_cselect_b32 s17, s20, s22
	s_add_u32 s34, s22, 0x100
	s_addc_u32 s44, s23, 0
	s_add_u32 s22, s24, 0x40080
	s_addc_u32 s23, s25, 0
	s_mov_b32 s45, -2
	s_add_u32 s24, s22, 0xfffc0080
	s_addc_u32 s25, s23, -1
	s_add_i32 s53, s35, 0x100
	s_cmp_eq_u32 s45, 12
	s_cselect_b32 s27, s19, s25
	s_cselect_b32 s26, s18, s24
	s_cselect_b32 s25, s15, s44
	s_cselect_b32 s24, s17, s34
	s_add_i32 s69, s90, 0x100
	v_add_u32_e32 v128, s53, v249
	v_add_u32_e32 v156, s69, v249
	ds_read_b128 v[112:115], v128
	ds_read_b128 v[120:123], v128 offset:1024
	ds_read_b128 v[124:127], v128 offset:2048
	ds_read_b128 v[128:131], v128 offset:3072
	ds_read_b128 v[136:139], v156
	ds_read_b128 v[140:143], v156 offset:1024
	ds_read_b128 v[144:147], v156 offset:2048
	ds_read_b128 v[156:159], v156 offset:3072
	v_lshl_add_u64 v[208:209], s[22:23], 0, v[206:207]
	s_add_i32 m0, s39, 0xc000
	ds_read_b128 v[160:163], v251
	ds_read_b128 v[164:167], v251 offset:1024
	ds_read_b128 v[168:171], v251 offset:2048
	ds_read_b128 v[172:175], v251 offset:3072
	ds_read_b128 v[176:179], v251 offset:4096
	ds_read_b128 v[180:183], v251 offset:5120
	ds_read_b128 v[184:187], v251 offset:6144
	ds_read_b128 v[188:191], v251 offset:7168
	global_load_lds_dwordx4 v[208:209], off
	v_lshl_add_u64 v[208:209], s[22:23], 0, v[204:205]
	s_add_i32 m0, s39, 0xe000
	s_nop 0
	global_load_lds_dwordx4 v[208:209], off
	s_waitcnt vmcnt(8)
	s_waitcnt lgkmcnt(0)
	s_barrier
	s_setprio 1
	s_waitcnt lgkmcnt(0)
	v_mfma_f32_16x16x32_bf16 v[152:155], v[112:115], v[160:163], 0
	v_mfma_f32_16x16x32_bf16 v[148:151], v[124:127], v[160:163], 0
	v_mfma_f32_16x16x32_bf16 v[108:111], v[112:115], v[168:171], 0
	v_mfma_f32_16x16x32_bf16 v[104:107], v[124:127], v[168:171], 0
	v_mfma_f32_16x16x32_bf16 v[92:95], v[112:115], v[176:179], 0
	v_mfma_f32_16x16x32_bf16 v[88:91], v[124:127], v[176:179], 0
	v_mfma_f32_16x16x32_bf16 v[76:79], v[112:115], v[184:187], 0
	v_mfma_f32_16x16x32_bf16 v[72:75], v[124:127], v[184:187], 0
	v_mfma_f32_16x16x32_bf16 v[152:155], v[120:123], v[164:167], v[152:155]
	v_mfma_f32_16x16x32_bf16 v[148:151], v[128:131], v[164:167], v[148:151]
	v_mfma_f32_16x16x32_bf16 v[108:111], v[120:123], v[172:175], v[108:111]
	v_mfma_f32_16x16x32_bf16 v[104:107], v[128:131], v[172:175], v[104:107]
	v_mfma_f32_16x16x32_bf16 v[92:95], v[120:123], v[180:183], v[92:95]
	v_mfma_f32_16x16x32_bf16 v[88:91], v[128:131], v[180:183], v[88:91]
	v_mfma_f32_16x16x32_bf16 v[76:79], v[120:123], v[188:191], v[76:79]
	v_mfma_f32_16x16x32_bf16 v[72:75], v[128:131], v[188:191], v[72:75]
	s_setprio 0
	s_setprio 1
	v_mfma_f32_16x16x32_bf16 v[132:135], v[136:139], v[160:163], 0
	v_mfma_f32_16x16x32_bf16 v[116:119], v[144:147], v[160:163], 0
	v_mfma_f32_16x16x32_bf16 v[100:103], v[136:139], v[168:171], 0
	v_mfma_f32_16x16x32_bf16 v[96:99], v[144:147], v[168:171], 0
	v_mfma_f32_16x16x32_bf16 v[84:87], v[136:139], v[176:179], 0
	v_mfma_f32_16x16x32_bf16 v[80:83], v[144:147], v[176:179], 0
	v_mfma_f32_16x16x32_bf16 v[68:71], v[136:139], v[184:187], 0
	v_mfma_f32_16x16x32_bf16 v[64:67], v[144:147], v[184:187], 0
	v_mfma_f32_16x16x32_bf16 v[132:135], v[140:143], v[164:167], v[132:135]
	v_mfma_f32_16x16x32_bf16 v[116:119], v[156:159], v[164:167], v[116:119]
	v_mfma_f32_16x16x32_bf16 v[100:103], v[140:143], v[172:175], v[100:103]
	v_mfma_f32_16x16x32_bf16 v[96:99], v[156:159], v[172:175], v[96:99]
	v_mfma_f32_16x16x32_bf16 v[84:87], v[140:143], v[180:183], v[84:87]
	v_mfma_f32_16x16x32_bf16 v[80:83], v[156:159], v[180:183], v[80:83]
	v_mfma_f32_16x16x32_bf16 v[68:71], v[140:143], v[188:191], v[68:71]
	v_mfma_f32_16x16x32_bf16 v[64:67], v[156:159], v[188:191], v[64:67]
	s_setprio 0
	s_barrier
	s_add_i32 s53, s53, s38
	v_lshl_add_u64 v[208:209], s[24:25], 0, v[192:193]
	s_mov_b32 m0, s53
	ds_read_b128 v[160:163], v251 offset:16384
	ds_read_b128 v[164:167], v251 offset:17408
	ds_read_b128 v[168:171], v251 offset:18432
	ds_read_b128 v[172:175], v251 offset:19456
	ds_read_b128 v[176:179], v251 offset:20480
	ds_read_b128 v[180:183], v251 offset:21504
	ds_read_b128 v[184:187], v251 offset:22528
	ds_read_b128 v[188:191], v251 offset:23552
	global_load_lds_dwordx4 v[208:209], off
	s_add_i32 m0, s53, 0x2000
	s_add_u32 s72, s24, 0x40000
	v_lshl_add_u64 v[210:211], s[24:25], 0, v[198:199]
	s_addc_u32 s73, s25, 0
	s_add_i32 s53, s69, s38
	global_load_lds_dwordx4 v[210:211], off
	v_lshl_add_u64 v[212:213], s[72:73], 0, v[192:193]
	s_mov_b32 m0, s53
	v_lshl_add_u64 v[214:215], s[26:27], 0, v[200:201]
	global_load_lds_dwordx4 v[212:213], off
	v_lshl_add_u64 v[212:213], s[72:73], 0, v[198:199]
	s_add_i32 m0, s53, 0x2000
	s_nop 0
	global_load_lds_dwordx4 v[212:213], off
	v_lshl_add_u64 v[212:213], s[26:27], 0, v[202:203]
	s_mov_b32 m0, s39
	s_nop 0
	global_load_lds_dwordx4 v[212:213], off
	s_mov_b32 m0, s46
	s_nop 0
	global_load_lds_dwordx4 v[214:215], off
	s_waitcnt vmcnt(8)
	s_waitcnt lgkmcnt(0)
	s_barrier
; #define PG8_STAGE(bufoff, gbase, voff) do { _Pragma("unroll") for (int _i = 0; _i < 2; ++_i) \
;         __builtin_amdgcn_global_load_lds((const unsigned*)((const char*)(gbase) + (voff)[_i]), (PG8_LAS unsigned*)(lds + (bufoff) + ldsw + _i * 8192), 16, 0, 0); } while (0)
; #define PG8_LDA(dst, b, h) do { _Pragma("unroll") for (int m = 0; m < 4; ++m) _Pragma("unroll") for (int k = 0; k < 2; ++k) dst[m][k] = *(const PG8_LAS bf16x8*)(lds + PG8_SA(b, h) + aoff + m * 2048 + k * 1024); } while (0)
; #define PG8_LDB(dst, b, h) do { _Pragma("unroll") for (int n = 0; n < 2; ++n) _Pragma("unroll") for (int k = 0; k < 2; ++k) dst[n][k] = *(const PG8_LAS bf16x8*)(lds + PG8_SB(b, h) + boff + n * 2048 + k * 1024); } while (0)
; #define PG8_MMA(ai, bj, At, Bt) do { __builtin_amdgcn_s_setprio(1); _Pragma("unroll") for (int m = 0; m < 4; ++m) _Pragma("unroll") for (int n = 0; n < 2; ++n) _Pragma("unroll") for (int k = 0; k < 2; ++k) \
;         acc[ai][bj][m][n] = __builtin_amdgcn_mfma_f32_16x16x32_bf16(Bt[n][k], At[m][k], acc[ai][bj][m][n], 0, 0, 0); __builtin_amdgcn_s_setprio(0); } while (0)
; #define PG8_BAR __builtin_amdgcn_s_barrier()
; template <class Epi, class Sched, bool ALIGN_EPI = false, bool SP2 = false>
; __device__ __forceinline__ void gemm_phase(PG8_LAS unsigned char* lds, const Gemm g, const Sched& S, const Epi& E, int wave_in) {
;     ...
;             PG8_LDB(B0, 0, 0); PG8_LDB(B1, 0, 1); PG8_SCHED; PG8_LDA(At, 0, 0); PG8_STAGE(PG8_SA(1, 1), a1 + hstep, voffA);
;             PG8_WAIT_V(8); PG8_WAIT_L(0); PG8_BAR; PG8_MMA(0, 0, At, B0); PG8_MMA(0, 1, At, B1); PG8_BAR; PG8_SCHED;
;             PG8_LDA(At, 0, 1); PG8_STAGE(PG8_SB(0, 0), b2, voffB); PG8_STAGE(PG8_SB(0, 1), b2 + hstep, voffB); PG8_STAGE(PG8_SA(0, 0), a2, voffA);
;             PG8_WAIT_V(8); PG8_WAIT_L(0); PG8_BAR; PG8_MMA(1, 0, At, B0); PG8_MMA(1, 1, At, B1); PG8_BAR; PG8_SCHED;
;             PG8_LDB(B0, 1, 0); PG8_LDB(B1, 1, 1); PG8_SCHED; PG8_LDA(At, 1, 0); PG8_STAGE(PG8_SA(0, 1), a2 + hstep, voffA);
;             PG8_WAIT_V(8); PG8_WAIT_L(0); PG8_BAR; PG8_MMA(0, 0, At, B0); PG8_MMA(0, 1, At, B1); PG8_BAR; PG8_SCHED;
;             PG8_LDA(At, 1, 1); PG8_STAGE(PG8_SB(1, 0), b3, voffB); PG8_STAGE(PG8_SB(1, 1), b3 + hstep, voffB); PG8_STAGE(PG8_SA(1, 0), a3, voffA);
;             PG8_WAIT_V(8); PG8_WAIT_L(0); PG8_BAR; PG8_MMA(1, 0, At, B0); PG8_MMA(1, 1, At, B1); PG8_BAR; PG8_SCHED;
	s_setprio 1
	s_waitcnt lgkmcnt(0)
	v_mfma_f32_16x16x32_bf16 v[60:63], v[112:115], v[160:163], 0
	v_mfma_f32_16x16x32_bf16 v[56:59], v[124:127], v[160:163], 0
	v_mfma_f32_16x16x32_bf16 v[44:47], v[112:115], v[168:171], 0
	v_mfma_f32_16x16x32_bf16 v[40:43], v[124:127], v[168:171], 0
	v_mfma_f32_16x16x32_bf16 v[28:31], v[112:115], v[176:179], 0
	v_mfma_f32_16x16x32_bf16 v[24:27], v[124:127], v[176:179], 0
	v_mfma_f32_16x16x32_bf16 v[12:15], v[112:115], v[184:187], 0
	v_mfma_f32_16x16x32_bf16 v[8:11], v[124:127], v[184:187], 0
	v_mfma_f32_16x16x32_bf16 v[60:63], v[120:123], v[164:167], v[60:63]
	v_mfma_f32_16x16x32_bf16 v[56:59], v[128:131], v[164:167], v[56:59]
	v_mfma_f32_16x16x32_bf16 v[44:47], v[120:123], v[172:175], v[44:47]
	v_mfma_f32_16x16x32_bf16 v[40:43], v[128:131], v[172:175], v[40:43]
	v_mfma_f32_16x16x32_bf16 v[28:31], v[120:123], v[180:183], v[28:31]
	v_mfma_f32_16x16x32_bf16 v[24:27], v[128:131], v[180:183], v[24:27]
	v_mfma_f32_16x16x32_bf16 v[12:15], v[120:123], v[188:191], v[12:15]
	v_mfma_f32_16x16x32_bf16 v[8:11], v[128:131], v[188:191], v[8:11]
	s_setprio 0
	s_setprio 1
	v_mfma_f32_16x16x32_bf16 v[52:55], v[136:139], v[160:163], 0
	v_mfma_f32_16x16x32_bf16 v[48:51], v[144:147], v[160:163], 0
	v_mfma_f32_16x16x32_bf16 v[36:39], v[136:139], v[168:171], 0
	v_mfma_f32_16x16x32_bf16 v[32:35], v[144:147], v[168:171], 0
	v_mfma_f32_16x16x32_bf16 v[20:23], v[136:139], v[176:179], 0
	v_mfma_f32_16x16x32_bf16 v[16:19], v[144:147], v[176:179], 0
	v_mfma_f32_16x16x32_bf16 v[4:7], v[136:139], v[184:187], 0
	v_mfma_f32_16x16x32_bf16 v[0:3], v[144:147], v[184:187], 0
	v_mfma_f32_16x16x32_bf16 v[52:55], v[140:143], v[164:167], v[52:55]
	v_mfma_f32_16x16x32_bf16 v[48:51], v[156:159], v[164:167], v[48:51]
	v_mfma_f32_16x16x32_bf16 v[36:39], v[140:143], v[172:175], v[36:39]
	v_mfma_f32_16x16x32_bf16 v[32:35], v[156:159], v[172:175], v[32:35]
	v_mfma_f32_16x16x32_bf16 v[20:23], v[140:143], v[180:183], v[20:23]
	v_mfma_f32_16x16x32_bf16 v[16:19], v[156:159], v[180:183], v[16:19]
	v_mfma_f32_16x16x32_bf16 v[4:7], v[140:143], v[188:191], v[4:7]
	v_mfma_f32_16x16x32_bf16 v[0:3], v[156:159], v[188:191], v[0:3]
	s_setprio 0
	s_barrier
	s_add_i32 s53, s65, 0x100
	s_add_i32 s69, s52, 0x100
	v_add_u32_e32 v128, s53, v249
	v_add_u32_e32 v156, s69, v249
	ds_read_b128 v[112:115], v128
	ds_read_b128 v[120:123], v128 offset:1024
	ds_read_b128 v[124:127], v128 offset:2048
	ds_read_b128 v[128:131], v128 offset:3072
	ds_read_b128 v[136:139], v156
	ds_read_b128 v[140:143], v156 offset:1024
	ds_read_b128 v[144:147], v156 offset:2048
	ds_read_b128 v[156:159], v156 offset:3072
	s_add_u32 s26, s26, 0x40000
	s_addc_u32 s27, s27, 0
	s_mov_b32 m0, s47
	v_lshl_add_u64 v[216:217], s[26:27], 0, v[202:203]
	ds_read_b128 v[160:163], v251 offset:32768
	ds_read_b128 v[164:167], v251 offset:33792
	ds_read_b128 v[168:171], v251 offset:34816
	ds_read_b128 v[172:175], v251 offset:35840
	ds_read_b128 v[176:179], v251 offset:36864
	ds_read_b128 v[180:183], v251 offset:37888
	ds_read_b128 v[184:187], v251 offset:38912
	ds_read_b128 v[188:191], v251 offset:39936
	global_load_lds_dwordx4 v[216:217], off
	v_lshl_add_u64 v[216:217], s[26:27], 0, v[200:201]
	s_mov_b32 m0, s60
	s_nop 0
	global_load_lds_dwordx4 v[216:217], off
	s_waitcnt vmcnt(8)
	s_waitcnt lgkmcnt(0)
	s_barrier
	s_setprio 1
	s_waitcnt lgkmcnt(0)
	v_mfma_f32_16x16x32_bf16 v[152:155], v[112:115], v[160:163], v[152:155]
	v_mfma_f32_16x16x32_bf16 v[148:151], v[124:127], v[160:163], v[148:151]
	v_mfma_f32_16x16x32_bf16 v[108:111], v[112:115], v[168:171], v[108:111]
	v_mfma_f32_16x16x32_bf16 v[104:107], v[124:127], v[168:171], v[104:107]
	v_mfma_f32_16x16x32_bf16 v[92:95], v[112:115], v[176:179], v[92:95]
	v_mfma_f32_16x16x32_bf16 v[88:91], v[124:127], v[176:179], v[88:91]
	v_mfma_f32_16x16x32_bf16 v[76:79], v[112:115], v[184:187], v[76:79]
	v_mfma_f32_16x16x32_bf16 v[72:75], v[124:127], v[184:187], v[72:75]
	v_mfma_f32_16x16x32_bf16 v[152:155], v[120:123], v[164:167], v[152:155]
	v_mfma_f32_16x16x32_bf16 v[148:151], v[128:131], v[164:167], v[148:151]
	v_mfma_f32_16x16x32_bf16 v[108:111], v[120:123], v[172:175], v[108:111]
	v_mfma_f32_16x16x32_bf16 v[104:107], v[128:131], v[172:175], v[104:107]
	v_mfma_f32_16x16x32_bf16 v[92:95], v[120:123], v[180:183], v[92:95]
	v_mfma_f32_16x16x32_bf16 v[88:91], v[128:131], v[180:183], v[88:91]
	v_mfma_f32_16x16x32_bf16 v[76:79], v[120:123], v[188:191], v[76:79]
	v_mfma_f32_16x16x32_bf16 v[72:75], v[128:131], v[188:191], v[72:75]
	s_setprio 0
	s_setprio 1
	v_mfma_f32_16x16x32_bf16 v[132:135], v[136:139], v[160:163], v[132:135]
	v_mfma_f32_16x16x32_bf16 v[116:119], v[144:147], v[160:163], v[116:119]
	v_mfma_f32_16x16x32_bf16 v[100:103], v[136:139], v[168:171], v[100:103]
	v_mfma_f32_16x16x32_bf16 v[96:99], v[144:147], v[168:171], v[96:99]
	v_mfma_f32_16x16x32_bf16 v[84:87], v[136:139], v[176:179], v[84:87]
	v_mfma_f32_16x16x32_bf16 v[80:83], v[144:147], v[176:179], v[80:83]
	v_mfma_f32_16x16x32_bf16 v[68:71], v[136:139], v[184:187], v[68:71]
	v_mfma_f32_16x16x32_bf16 v[64:67], v[144:147], v[184:187], v[64:67]
	v_mfma_f32_16x16x32_bf16 v[132:135], v[140:143], v[164:167], v[132:135]
	v_mfma_f32_16x16x32_bf16 v[116:119], v[156:159], v[164:167], v[116:119]
	v_mfma_f32_16x16x32_bf16 v[100:103], v[140:143], v[172:175], v[100:103]
	v_mfma_f32_16x16x32_bf16 v[96:99], v[156:159], v[172:175], v[96:99]
	v_mfma_f32_16x16x32_bf16 v[84:87], v[140:143], v[180:183], v[84:87]
	v_mfma_f32_16x16x32_bf16 v[80:83], v[156:159], v[180:183], v[80:83]
	v_mfma_f32_16x16x32_bf16 v[68:71], v[140:143], v[188:191], v[68:71]
	v_mfma_f32_16x16x32_bf16 v[64:67], v[156:159], v[188:191], v[64:67]
	s_setprio 0
	s_barrier
; #define PG8_STAGE(bufoff, gbase, voff) do { _Pragma("unroll") for (int _i = 0; _i < 2; ++_i) \
;         __builtin_amdgcn_global_load_lds((const unsigned*)((const char*)(gbase) + (voff)[_i]), (PG8_LAS unsigned*)(lds + (bufoff) + ldsw + _i * 8192), 16, 0, 0); } while (0)
; #define PG8_LDA(dst, b, h) do { _Pragma("unroll") for (int m = 0; m < 4; ++m) _Pragma("unroll") for (int k = 0; k < 2; ++k) dst[m][k] = *(const PG8_LAS bf16x8*)(lds + PG8_SA(b, h) + aoff + m * 2048 + k * 1024); } while (0)
; #define PG8_WAIT_V(n) asm volatile("s_waitcnt vmcnt(" #n ")" ::: "memory")
; #define PG8_WAIT_L(n) asm volatile("s_waitcnt lgkmcnt(" #n ")" ::: "memory")
; #define PG8_BAR __builtin_amdgcn_s_barrier()
; template <class Epi, class Sched, bool ALIGN_EPI = false, bool SP2 = false>
; __device__ __forceinline__ void gemm_phase(PG8_LAS unsigned char* lds, const Gemm g, const Sched& S, const Epi& E, int wave_in) {
;     ...
;         for (int t = 0; t < nt; t += 2) {
;             const bool last = (t == nt - 2);
;             const char* a1 = cA + (size_t)(t + 1) * kstep;
;             const char* a2 = last ? nA : cA + (size_t)(t + 2) * kstep; const char* b2 = last ? nB : cB + (size_t)(t + 2) * kstep;
;             const char* a3 = a2 + kstep; const char* b3 = b2 + kstep;
;             if (last && has_next) S.a_ready(nxt);
;             if constexpr (SP2) {
;             PG8_LDB(B0, 0, 0); PG8_LDB(B1, 0, 1); PG8_SCHED; PG8_LDA(At, 0, 0); PG8_STAGE(PG8_SA(1, 1), a1 + hstep, voffA);
;             PG8_WAIT_V(8); PG8_WAIT_L(0); PG8_BAR; PG8_MMA(0, 0, At, B0); PG8_MMA(0, 1, At, B1); PG8_BAR; PG8_SCHED;
;             PG8_LDA(At, 0, 1); PG8_STAGE(PG8_SB(0, 0), b2, voffB); PG8_STAGE(PG8_SB(0, 1), b2 + hstep, voffB); PG8_STAGE(PG8_SA(0, 0), a2, voffA);
;             PG8_WAIT_V(8); PG8_WAIT_L(0); PG8_BAR; PG8_MMA(1, 0, At, B0); PG8_MMA(1, 1, At, B1); PG8_BAR; PG8_SCHED;
;             PG8_LDB(B0, 1, 0); PG8_LDB(B1, 1, 1); PG8_SCHED; PG8_LDA(At, 1, 0); PG8_STAGE(PG8_SA(0, 1), a2 + hstep, voffA);
;             PG8_WAIT_V(8); PG8_WAIT_L(0); PG8_BAR; PG8_MMA(0, 0, At, B0); PG8_MMA(0, 1, At, B1); PG8_BAR; PG8_SCHED;
;             PG8_LDA(At, 1, 1); PG8_STAGE(PG8_SB(1, 0), b3, voffB); PG8_STAGE(PG8_SB(1, 1), b3 + hstep, voffB); PG8_STAGE(PG8_SA(1, 0), a3, voffA);
;             PG8_WAIT_V(8); PG8_WAIT_L(0); PG8_BAR; PG8_MMA(1, 0, At, B0); PG8_MMA(1, 1, At, B1); PG8_BAR; PG8_SCHED;
	s_add_i32 s26, s53, s38
	v_lshl_add_u64 v[208:209], v[208:209], 0, s[88:89]
	s_mov_b32 m0, s26
	ds_read_b128 v[160:163], v251 offset:49152
	ds_read_b128 v[164:167], v251 offset:50176
	ds_read_b128 v[168:171], v251 offset:51200
	ds_read_b128 v[172:175], v251 offset:52224
	ds_read_b128 v[176:179], v251 offset:53248
	ds_read_b128 v[180:183], v251 offset:54272
	ds_read_b128 v[184:187], v251 offset:55296
	ds_read_b128 v[188:191], v251 offset:56320
	global_load_lds_dwordx4 v[208:209], off
	s_add_i32 m0, s26, 0x2000
	s_add_u32 s24, s24, 0x40080
	v_lshl_add_u64 v[208:209], v[210:211], 0, s[88:89]
	s_addc_u32 s25, s25, 0
	s_add_i32 s26, s69, s38
	global_load_lds_dwordx4 v[208:209], off
	v_lshl_add_u64 v[208:209], s[24:25], 0, v[192:193]
	s_mov_b32 m0, s26
	s_nop 0
	global_load_lds_dwordx4 v[208:209], off
	v_lshl_add_u64 v[208:209], s[24:25], 0, v[198:199]
	s_add_i32 m0, s26, 0x2000
	s_nop 0
	global_load_lds_dwordx4 v[208:209], off
	v_lshl_add_u64 v[208:209], v[212:213], 0, s[88:89]
	s_mov_b32 m0, s62
	s_nop 0
	global_load_lds_dwordx4 v[208:209], off
	v_lshl_add_u64 v[208:209], v[214:215], 0, s[88:89]
	s_mov_b32 m0, s63
	s_nop 0
	global_load_lds_dwordx4 v[208:209], off
	s_waitcnt vmcnt(8)
	s_waitcnt lgkmcnt(0)
	s_barrier
	s_setprio 1
	s_waitcnt lgkmcnt(0)
	v_mfma_f32_16x16x32_bf16 v[60:63], v[112:115], v[160:163], v[60:63]
	v_mfma_f32_16x16x32_bf16 v[56:59], v[124:127], v[160:163], v[56:59]
	v_mfma_f32_16x16x32_bf16 v[44:47], v[112:115], v[168:171], v[44:47]
	v_mfma_f32_16x16x32_bf16 v[40:43], v[124:127], v[168:171], v[40:43]
	v_mfma_f32_16x16x32_bf16 v[28:31], v[112:115], v[176:179], v[28:31]
	v_mfma_f32_16x16x32_bf16 v[24:27], v[124:127], v[176:179], v[24:27]
	v_mfma_f32_16x16x32_bf16 v[12:15], v[112:115], v[184:187], v[12:15]
	v_mfma_f32_16x16x32_bf16 v[8:11], v[124:127], v[184:187], v[8:11]
	v_mfma_f32_16x16x32_bf16 v[60:63], v[120:123], v[164:167], v[60:63]
	v_mfma_f32_16x16x32_bf16 v[56:59], v[128:131], v[164:167], v[56:59]
	v_mfma_f32_16x16x32_bf16 v[44:47], v[120:123], v[172:175], v[44:47]
	v_mfma_f32_16x16x32_bf16 v[40:43], v[128:131], v[172:175], v[40:43]
	v_mfma_f32_16x16x32_bf16 v[28:31], v[120:123], v[180:183], v[28:31]
	v_mfma_f32_16x16x32_bf16 v[24:27], v[128:131], v[180:183], v[24:27]
	v_mfma_f32_16x16x32_bf16 v[12:15], v[120:123], v[188:191], v[12:15]
	v_mfma_f32_16x16x32_bf16 v[8:11], v[128:131], v[188:191], v[8:11]
	s_setprio 0
	s_setprio 1
	v_mfma_f32_16x16x32_bf16 v[52:55], v[136:139], v[160:163], v[52:55]
	v_mfma_f32_16x16x32_bf16 v[48:51], v[144:147], v[160:163], v[48:51]
	v_mfma_f32_16x16x32_bf16 v[36:39], v[136:139], v[168:171], v[36:39]
	v_mfma_f32_16x16x32_bf16 v[32:35], v[144:147], v[168:171], v[32:35]
	v_mfma_f32_16x16x32_bf16 v[20:23], v[136:139], v[176:179], v[20:23]
	v_mfma_f32_16x16x32_bf16 v[16:19], v[144:147], v[176:179], v[16:19]
	v_mfma_f32_16x16x32_bf16 v[4:7], v[136:139], v[184:187], v[4:7]
	v_mfma_f32_16x16x32_bf16 v[0:3], v[144:147], v[184:187], v[0:3]
	v_mfma_f32_16x16x32_bf16 v[52:55], v[140:143], v[164:167], v[52:55]
	v_mfma_f32_16x16x32_bf16 v[48:51], v[156:159], v[164:167], v[48:51]
	v_mfma_f32_16x16x32_bf16 v[36:39], v[140:143], v[172:175], v[36:39]
	v_mfma_f32_16x16x32_bf16 v[32:35], v[156:159], v[172:175], v[32:35]
	v_mfma_f32_16x16x32_bf16 v[20:23], v[140:143], v[180:183], v[20:23]
	v_mfma_f32_16x16x32_bf16 v[16:19], v[156:159], v[180:183], v[16:19]
	v_mfma_f32_16x16x32_bf16 v[4:7], v[140:143], v[188:191], v[4:7]
	v_mfma_f32_16x16x32_bf16 v[0:3], v[156:159], v[188:191], v[0:3]
	s_setprio 0
	s_add_i32 s45, s45, 2
	s_add_u32 s34, s34, 0x100
	s_addc_u32 s44, s44, 0
	s_add_u32 s22, s22, 0x100
	s_addc_u32 s23, s23, 0
	s_cmp_gt_u32 s45, 13
	s_cbranch_scc1 .Lxbar_3
	s_add_u32 s24, s22, 0xfffc0080
	s_addc_u32 s25, s23, -1
	s_add_i32 s53, s35, 0x100
	s_cmp_eq_u32 s45, 12
	s_cselect_b32 s27, s19, s25
	s_cselect_b32 s26, s18, s24
	s_cselect_b32 s25, s15, s44
	s_cselect_b32 s24, s17, s34
	s_add_i32 s69, s90, 0x100

; #define PG8_STAGE(bufoff, gbase, voff) do { _Pragma("unroll") for (int _i = 0; _i < 2; ++_i) \
;         __builtin_amdgcn_global_load_lds((const unsigned*)((const char*)(gbase) + (voff)[_i]), (PG8_LAS unsigned*)(lds + (bufoff) + ldsw + _i * 8192), 16, 0, 0); } while (0)
; #define PG8_LDA(dst, b, h) do { _Pragma("unroll") for (int m = 0; m < 4; ++m) _Pragma("unroll") for (int k = 0; k < 2; ++k) dst[m][k] = *(const PG8_LAS bf16x8*)(lds + PG8_SA(b, h) + aoff + m * 2048 + k * 1024); } while (0)
; #define PG8_LDB(dst, b, h) do { _Pragma("unroll") for (int n = 0; n < 2; ++n) _Pragma("unroll") for (int k = 0; k < 2; ++k) dst[n][k] = *(const PG8_LAS bf16x8*)(lds + PG8_SB(b, h) + boff + n * 2048 + k * 1024); } while (0)
; #define PG8_MMA(ai, bj, At, Bt) do { __builtin_amdgcn_s_setprio(1); _Pragma("unroll") for (int m = 0; m < 4; ++m) _Pragma("unroll") for (int n = 0; n < 2; ++n) _Pragma("unroll") for (int k = 0; k < 2; ++k) \
;         acc[ai][bj][m][n] = __builtin_amdgcn_mfma_f32_16x16x32_bf16(Bt[n][k], At[m][k], acc[ai][bj][m][n], 0, 0, 0); __builtin_amdgcn_s_setprio(0); } while (0)
; #define PG8_WAIT_V(n) asm volatile("s_waitcnt vmcnt(" #n ")" ::: "memory")
; #define PG8_WAIT_L(n) asm volatile("s_waitcnt lgkmcnt(" #n ")" ::: "memory")
; #define PG8_BAR __builtin_amdgcn_s_barrier()
; #define PG8_SCHED __builtin_amdgcn_sched_barrier(0)
; template <class Epi, class Sched, bool ALIGN_EPI = false, bool SP2 = false>
; __device__ __forceinline__ void gemm_phase(PG8_LAS unsigned char* lds, const Gemm g, const Sched& S, const Epi& E, int wave_in) {
;     ...
;             PG8_LDB(B0, 0, 0); PG8_LDB(B1, 0, 1); PG8_SCHED; PG8_LDA(At, 0, 0); PG8_STAGE(PG8_SA(1, 1), a1 + hstep, voffA);
;             PG8_WAIT_V(8); PG8_WAIT_L(0); PG8_BAR; PG8_MMA(0, 0, At, B0); PG8_MMA(0, 1, At, B1); PG8_BAR; PG8_SCHED;
;             PG8_LDA(At, 0, 1); PG8_STAGE(PG8_SB(0, 0), b2, voffB); PG8_STAGE(PG8_SB(0, 1), b2 + hstep, voffB); PG8_STAGE(PG8_SA(0, 0), a2, voffA);
;             PG8_WAIT_V(8); PG8_WAIT_L(0); PG8_BAR; PG8_MMA(1, 0, At, B0); PG8_MMA(1, 1, At, B1); PG8_BAR; PG8_SCHED;
.LBB0_590:
	v_add_u32_e32 v128, s53, v249
	v_add_u32_e32 v156, s69, v249
	ds_read_b128 v[112:115], v128
	ds_read_b128 v[120:123], v128 offset:1024
	ds_read_b128 v[124:127], v128 offset:2048
	ds_read_b128 v[128:131], v128 offset:3072
	ds_read_b128 v[136:139], v156
	ds_read_b128 v[140:143], v156 offset:1024
	ds_read_b128 v[144:147], v156 offset:2048
	ds_read_b128 v[156:159], v156 offset:3072
	v_lshl_add_u64 v[208:209], s[22:23], 0, v[206:207]
	s_add_i32 m0, s39, 0xc000
	ds_read_b128 v[160:163], v251
	ds_read_b128 v[164:167], v251 offset:1024
	ds_read_b128 v[168:171], v251 offset:2048
	ds_read_b128 v[172:175], v251 offset:3072
	ds_read_b128 v[176:179], v251 offset:4096
	ds_read_b128 v[180:183], v251 offset:5120
	ds_read_b128 v[184:187], v251 offset:6144
	ds_read_b128 v[188:191], v251 offset:7168
	global_load_lds_dwordx4 v[208:209], off
	v_lshl_add_u64 v[208:209], s[22:23], 0, v[204:205]
	s_add_i32 m0, s39, 0xe000
	s_nop 0
	global_load_lds_dwordx4 v[208:209], off
	s_waitcnt vmcnt(8)
	s_waitcnt lgkmcnt(0)
	s_barrier
	s_setprio 1
	s_waitcnt lgkmcnt(0)
	v_mfma_f32_16x16x32_bf16 v[152:155], v[112:115], v[160:163], v[152:155]
	v_mfma_f32_16x16x32_bf16 v[148:151], v[124:127], v[160:163], v[148:151]
	v_mfma_f32_16x16x32_bf16 v[108:111], v[112:115], v[168:171], v[108:111]
	v_mfma_f32_16x16x32_bf16 v[104:107], v[124:127], v[168:171], v[104:107]
	v_mfma_f32_16x16x32_bf16 v[92:95], v[112:115], v[176:179], v[92:95]
	v_mfma_f32_16x16x32_bf16 v[88:91], v[124:127], v[176:179], v[88:91]
	v_mfma_f32_16x16x32_bf16 v[76:79], v[112:115], v[184:187], v[76:79]
	v_mfma_f32_16x16x32_bf16 v[72:75], v[124:127], v[184:187], v[72:75]
	v_mfma_f32_16x16x32_bf16 v[152:155], v[120:123], v[164:167], v[152:155]
	v_mfma_f32_16x16x32_bf16 v[148:151], v[128:131], v[164:167], v[148:151]
	v_mfma_f32_16x16x32_bf16 v[108:111], v[120:123], v[172:175], v[108:111]
	v_mfma_f32_16x16x32_bf16 v[104:107], v[128:131], v[172:175], v[104:107]
	v_mfma_f32_16x16x32_bf16 v[92:95], v[120:123], v[180:183], v[92:95]
	v_mfma_f32_16x16x32_bf16 v[88:91], v[128:131], v[180:183], v[88:91]
	v_mfma_f32_16x16x32_bf16 v[76:79], v[120:123], v[188:191], v[76:79]
	v_mfma_f32_16x16x32_bf16 v[72:75], v[128:131], v[188:191], v[72:75]
	s_setprio 0
	s_setprio 1
	v_mfma_f32_16x16x32_bf16 v[132:135], v[136:139], v[160:163], v[132:135]
	v_mfma_f32_16x16x32_bf16 v[116:119], v[144:147], v[160:163], v[116:119]
	v_mfma_f32_16x16x32_bf16 v[100:103], v[136:139], v[168:171], v[100:103]
	v_mfma_f32_16x16x32_bf16 v[96:99], v[144:147], v[168:171], v[96:99]
	v_mfma_f32_16x16x32_bf16 v[84:87], v[136:139], v[176:179], v[84:87]
	v_mfma_f32_16x16x32_bf16 v[80:83], v[144:147], v[176:179], v[80:83]
	v_mfma_f32_16x16x32_bf16 v[68:71], v[136:139], v[184:187], v[68:71]
	v_mfma_f32_16x16x32_bf16 v[64:67], v[144:147], v[184:187], v[64:67]
	v_mfma_f32_16x16x32_bf16 v[132:135], v[140:143], v[164:167], v[132:135]
	v_mfma_f32_16x16x32_bf16 v[116:119], v[156:159], v[164:167], v[116:119]
	v_mfma_f32_16x16x32_bf16 v[100:103], v[140:143], v[172:175], v[100:103]
	v_mfma_f32_16x16x32_bf16 v[96:99], v[156:159], v[172:175], v[96:99]
	v_mfma_f32_16x16x32_bf16 v[84:87], v[140:143], v[180:183], v[84:87]
	v_mfma_f32_16x16x32_bf16 v[80:83], v[156:159], v[180:183], v[80:83]
	v_mfma_f32_16x16x32_bf16 v[68:71], v[140:143], v[188:191], v[68:71]
	v_mfma_f32_16x16x32_bf16 v[64:67], v[156:159], v[188:191], v[64:67]
	s_setprio 0
	s_barrier
	s_add_i32 s53, s53, s38
	v_lshl_add_u64 v[208:209], s[24:25], 0, v[192:193]
	s_mov_b32 m0, s53
	ds_read_b128 v[160:163], v251 offset:16384
	ds_read_b128 v[164:167], v251 offset:17408
	ds_read_b128 v[168:171], v251 offset:18432
	ds_read_b128 v[172:175], v251 offset:19456
	ds_read_b128 v[176:179], v251 offset:20480
	ds_read_b128 v[180:183], v251 offset:21504
	ds_read_b128 v[184:187], v251 offset:22528
	ds_read_b128 v[188:191], v251 offset:23552
	global_load_lds_dwordx4 v[208:209], off
	s_add_i32 m0, s53, 0x2000
	s_add_u32 s72, s24, 0x40000
	v_lshl_add_u64 v[210:211], s[24:25], 0, v[198:199]
	s_addc_u32 s73, s25, 0
	s_add_i32 s53, s69, s38
	global_load_lds_dwordx4 v[210:211], off
	v_lshl_add_u64 v[212:213], s[72:73], 0, v[192:193]
	s_mov_b32 m0, s53
	v_lshl_add_u64 v[214:215], s[26:27], 0, v[200:201]
	global_load_lds_dwordx4 v[212:213], off
	v_lshl_add_u64 v[212:213], s[72:73], 0, v[198:199]
	s_add_i32 m0, s53, 0x2000
	s_nop 0
	global_load_lds_dwordx4 v[212:213], off
	v_lshl_add_u64 v[212:213], s[26:27], 0, v[202:203]
	s_mov_b32 m0, s39
	s_nop 0
	global_load_lds_dwordx4 v[212:213], off
	s_mov_b32 m0, s46
	s_nop 0
	global_load_lds_dwordx4 v[214:215], off
	s_waitcnt vmcnt(8)
	s_waitcnt lgkmcnt(0)
	s_barrier
; #define PG8_STAGE(bufoff, gbase, voff) do { _Pragma("unroll") for (int _i = 0; _i < 2; ++_i) \
;         __builtin_amdgcn_global_load_lds((const unsigned*)((const char*)(gbase) + (voff)[_i]), (PG8_LAS unsigned*)(lds + (bufoff) + ldsw + _i * 8192), 16, 0, 0); } while (0)
; #define PG8_LDA(dst, b, h) do { _Pragma("unroll") for (int m = 0; m < 4; ++m) _Pragma("unroll") for (int k = 0; k < 2; ++k) dst[m][k] = *(const PG8_LAS bf16x8*)(lds + PG8_SA(b, h) + aoff + m * 2048 + k * 1024); } while (0)
; #define PG8_LDB(dst, b, h) do { _Pragma("unroll") for (int n = 0; n < 2; ++n) _Pragma("unroll") for (int k = 0; k < 2; ++k) dst[n][k] = *(const PG8_LAS bf16x8*)(lds + PG8_SB(b, h) + boff + n * 2048 + k * 1024); } while (0)
; #define PG8_MMA(ai, bj, At, Bt) do { __builtin_amdgcn_s_setprio(1); _Pragma("unroll") for (int m = 0; m < 4; ++m) _Pragma("unroll") for (int n = 0; n < 2; ++n) _Pragma("unroll") for (int k = 0; k < 2; ++k) \
;         acc[ai][bj][m][n] = __builtin_amdgcn_mfma_f32_16x16x32_bf16(Bt[n][k], At[m][k], acc[ai][bj][m][n], 0, 0, 0); __builtin_amdgcn_s_setprio(0); } while (0)
; #define PG8_WAIT_V(n) asm volatile("s_waitcnt vmcnt(" #n ")" ::: "memory")
; #define PG8_WAIT_L(n) asm volatile("s_waitcnt lgkmcnt(" #n ")" ::: "memory")
; #define PG8_BAR __builtin_amdgcn_s_barrier()
; #define PG8_SCHED __builtin_amdgcn_sched_barrier(0)
; template <class Epi, class Sched, bool ALIGN_EPI = false, bool SP2 = false>
; __device__ __forceinline__ void gemm_phase(PG8_LAS unsigned char* lds, const Gemm g, const Sched& S, const Epi& E, int wave_in) {
;     ...
;             PG8_WAIT_V(8); PG8_WAIT_L(0); PG8_BAR; PG8_MMA(1, 0, At, B0); PG8_MMA(1, 1, At, B1); PG8_BAR; PG8_SCHED;
;             PG8_LDB(B0, 1, 0); PG8_LDB(B1, 1, 1); PG8_SCHED; PG8_LDA(At, 1, 0); PG8_STAGE(PG8_SA(0, 1), a2 + hstep, voffA);
;             PG8_WAIT_V(8); PG8_WAIT_L(0); PG8_BAR; PG8_MMA(0, 0, At, B0); PG8_MMA(0, 1, At, B1); PG8_BAR; PG8_SCHED;
	s_setprio 1
	s_waitcnt lgkmcnt(0)
	v_mfma_f32_16x16x32_bf16 v[60:63], v[112:115], v[160:163], v[60:63]
	v_mfma_f32_16x16x32_bf16 v[56:59], v[124:127], v[160:163], v[56:59]
	v_mfma_f32_16x16x32_bf16 v[44:47], v[112:115], v[168:171], v[44:47]
	v_mfma_f32_16x16x32_bf16 v[40:43], v[124:127], v[168:171], v[40:43]
	v_mfma_f32_16x16x32_bf16 v[28:31], v[112:115], v[176:179], v[28:31]
	v_mfma_f32_16x16x32_bf16 v[24:27], v[124:127], v[176:179], v[24:27]
	v_mfma_f32_16x16x32_bf16 v[12:15], v[112:115], v[184:187], v[12:15]
	v_mfma_f32_16x16x32_bf16 v[8:11], v[124:127], v[184:187], v[8:11]
	v_mfma_f32_16x16x32_bf16 v[60:63], v[120:123], v[164:167], v[60:63]
	v_mfma_f32_16x16x32_bf16 v[56:59], v[128:131], v[164:167], v[56:59]
	v_mfma_f32_16x16x32_bf16 v[44:47], v[120:123], v[172:175], v[44:47]
	v_mfma_f32_16x16x32_bf16 v[40:43], v[128:131], v[172:175], v[40:43]
	v_mfma_f32_16x16x32_bf16 v[28:31], v[120:123], v[180:183], v[28:31]
	v_mfma_f32_16x16x32_bf16 v[24:27], v[128:131], v[180:183], v[24:27]
	v_mfma_f32_16x16x32_bf16 v[12:15], v[120:123], v[188:191], v[12:15]
	v_mfma_f32_16x16x32_bf16 v[8:11], v[128:131], v[188:191], v[8:11]
	s_setprio 0
	s_setprio 1
	v_mfma_f32_16x16x32_bf16 v[52:55], v[136:139], v[160:163], v[52:55]
	v_mfma_f32_16x16x32_bf16 v[48:51], v[144:147], v[160:163], v[48:51]
	v_mfma_f32_16x16x32_bf16 v[36:39], v[136:139], v[168:171], v[36:39]
	v_mfma_f32_16x16x32_bf16 v[32:35], v[144:147], v[168:171], v[32:35]
	v_mfma_f32_16x16x32_bf16 v[20:23], v[136:139], v[176:179], v[20:23]
	v_mfma_f32_16x16x32_bf16 v[16:19], v[144:147], v[176:179], v[16:19]
	v_mfma_f32_16x16x32_bf16 v[4:7], v[136:139], v[184:187], v[4:7]
	v_mfma_f32_16x16x32_bf16 v[0:3], v[144:147], v[184:187], v[0:3]
	v_mfma_f32_16x16x32_bf16 v[52:55], v[140:143], v[164:167], v[52:55]
	v_mfma_f32_16x16x32_bf16 v[48:51], v[156:159], v[164:167], v[48:51]
	v_mfma_f32_16x16x32_bf16 v[36:39], v[140:143], v[172:175], v[36:39]
	v_mfma_f32_16x16x32_bf16 v[32:35], v[156:159], v[172:175], v[32:35]
	v_mfma_f32_16x16x32_bf16 v[20:23], v[140:143], v[180:183], v[20:23]
	v_mfma_f32_16x16x32_bf16 v[16:19], v[156:159], v[180:183], v[16:19]
	v_mfma_f32_16x16x32_bf16 v[4:7], v[140:143], v[188:191], v[4:7]
	v_mfma_f32_16x16x32_bf16 v[0:3], v[156:159], v[188:191], v[0:3]
	s_setprio 0
	s_barrier
	s_add_i32 s53, s65, 0x100
	s_add_i32 s69, s52, 0x100
	v_add_u32_e32 v128, s53, v249
	v_add_u32_e32 v156, s69, v249
	ds_read_b128 v[112:115], v128
	ds_read_b128 v[120:123], v128 offset:1024
	ds_read_b128 v[124:127], v128 offset:2048
	ds_read_b128 v[128:131], v128 offset:3072
	ds_read_b128 v[136:139], v156
	ds_read_b128 v[140:143], v156 offset:1024
	ds_read_b128 v[144:147], v156 offset:2048
	ds_read_b128 v[156:159], v156 offset:3072
	s_add_u32 s26, s26, 0x40000
	s_addc_u32 s27, s27, 0
	s_mov_b32 m0, s47
	v_lshl_add_u64 v[216:217], s[26:27], 0, v[202:203]
	ds_read_b128 v[160:163], v251 offset:32768
	ds_read_b128 v[164:167], v251 offset:33792
	ds_read_b128 v[168:171], v251 offset:34816
	ds_read_b128 v[172:175], v251 offset:35840
	ds_read_b128 v[176:179], v251 offset:36864
	ds_read_b128 v[180:183], v251 offset:37888
	ds_read_b128 v[184:187], v251 offset:38912
	ds_read_b128 v[188:191], v251 offset:39936
	global_load_lds_dwordx4 v[216:217], off
	v_lshl_add_u64 v[216:217], s[26:27], 0, v[200:201]
	s_mov_b32 m0, s60
	s_nop 0
	global_load_lds_dwordx4 v[216:217], off
	s_waitcnt vmcnt(8)
	s_waitcnt lgkmcnt(0)
	s_barrier
	s_setprio 1
	s_waitcnt lgkmcnt(0)
	v_mfma_f32_16x16x32_bf16 v[152:155], v[112:115], v[160:163], v[152:155]
	v_mfma_f32_16x16x32_bf16 v[148:151], v[124:127], v[160:163], v[148:151]
	v_mfma_f32_16x16x32_bf16 v[108:111], v[112:115], v[168:171], v[108:111]
	v_mfma_f32_16x16x32_bf16 v[104:107], v[124:127], v[168:171], v[104:107]
	v_mfma_f32_16x16x32_bf16 v[92:95], v[112:115], v[176:179], v[92:95]
	v_mfma_f32_16x16x32_bf16 v[88:91], v[124:127], v[176:179], v[88:91]
	v_mfma_f32_16x16x32_bf16 v[76:79], v[112:115], v[184:187], v[76:79]
	v_mfma_f32_16x16x32_bf16 v[72:75], v[124:127], v[184:187], v[72:75]
	v_mfma_f32_16x16x32_bf16 v[152:155], v[120:123], v[164:167], v[152:155]
	v_mfma_f32_16x16x32_bf16 v[148:151], v[128:131], v[164:167], v[148:151]
	v_mfma_f32_16x16x32_bf16 v[108:111], v[120:123], v[172:175], v[108:111]
	v_mfma_f32_16x16x32_bf16 v[104:107], v[128:131], v[172:175], v[104:107]
	v_mfma_f32_16x16x32_bf16 v[92:95], v[120:123], v[180:183], v[92:95]
	v_mfma_f32_16x16x32_bf16 v[88:91], v[128:131], v[180:183], v[88:91]
	v_mfma_f32_16x16x32_bf16 v[76:79], v[120:123], v[188:191], v[76:79]
	v_mfma_f32_16x16x32_bf16 v[72:75], v[128:131], v[188:191], v[72:75]
	s_setprio 0
	s_setprio 1
	v_mfma_f32_16x16x32_bf16 v[132:135], v[136:139], v[160:163], v[132:135]
	v_mfma_f32_16x16x32_bf16 v[116:119], v[144:147], v[160:163], v[116:119]
	v_mfma_f32_16x16x32_bf16 v[100:103], v[136:139], v[168:171], v[100:103]
	v_mfma_f32_16x16x32_bf16 v[96:99], v[144:147], v[168:171], v[96:99]
	v_mfma_f32_16x16x32_bf16 v[84:87], v[136:139], v[176:179], v[84:87]
	v_mfma_f32_16x16x32_bf16 v[80:83], v[144:147], v[176:179], v[80:83]
	v_mfma_f32_16x16x32_bf16 v[68:71], v[136:139], v[184:187], v[68:71]
	v_mfma_f32_16x16x32_bf16 v[64:67], v[144:147], v[184:187], v[64:67]
	v_mfma_f32_16x16x32_bf16 v[132:135], v[140:143], v[164:167], v[132:135]
	v_mfma_f32_16x16x32_bf16 v[116:119], v[156:159], v[164:167], v[116:119]
	v_mfma_f32_16x16x32_bf16 v[100:103], v[140:143], v[172:175], v[100:103]
	v_mfma_f32_16x16x32_bf16 v[96:99], v[156:159], v[172:175], v[96:99]
	v_mfma_f32_16x16x32_bf16 v[84:87], v[140:143], v[180:183], v[84:87]
	v_mfma_f32_16x16x32_bf16 v[80:83], v[156:159], v[180:183], v[80:83]
	v_mfma_f32_16x16x32_bf16 v[68:71], v[140:143], v[188:191], v[68:71]
	v_mfma_f32_16x16x32_bf16 v[64:67], v[156:159], v[188:191], v[64:67]
	s_setprio 0
	s_barrier
; #define PG8_STAGE(bufoff, gbase, voff) do { _Pragma("unroll") for (int _i = 0; _i < 2; ++_i) \
;         __builtin_amdgcn_global_load_lds((const unsigned*)((const char*)(gbase) + (voff)[_i]), (PG8_LAS unsigned*)(lds + (bufoff) + ldsw + _i * 8192), 16, 0, 0); } while (0)
; #define PG8_LDA(dst, b, h) do { _Pragma("unroll") for (int m = 0; m < 4; ++m) _Pragma("unroll") for (int k = 0; k < 2; ++k) dst[m][k] = *(const PG8_LAS bf16x8*)(lds + PG8_SA(b, h) + aoff + m * 2048 + k * 1024); } while (0)
; #define PG8_WAIT_V(n) asm volatile("s_waitcnt vmcnt(" #n ")" ::: "memory")
; #define PG8_WAIT_L(n) asm volatile("s_waitcnt lgkmcnt(" #n ")" ::: "memory")
; #define PG8_BAR __builtin_amdgcn_s_barrier()
; template <class Epi, class Sched, bool ALIGN_EPI = false, bool SP2 = false>
; __device__ __forceinline__ void gemm_phase(PG8_LAS unsigned char* lds, const Gemm g, const Sched& S, const Epi& E, int wave_in) {
;     ...
;         for (int t = 0; t < nt; t += 2) {
;             const bool last = (t == nt - 2);
;             const char* a1 = cA + (size_t)(t + 1) * kstep;
;             const char* a2 = last ? nA : cA + (size_t)(t + 2) * kstep; const char* b2 = last ? nB : cB + (size_t)(t + 2) * kstep;
;             const char* a3 = a2 + kstep; const char* b3 = b2 + kstep;
;             if (last && has_next) S.a_ready(nxt);
;             if constexpr (SP2) {
;             PG8_LDB(B0, 0, 0); PG8_LDB(B1, 0, 1); PG8_SCHED; PG8_LDA(At, 0, 0); PG8_STAGE(PG8_SA(1, 1), a1 + hstep, voffA);
;             PG8_WAIT_V(8); PG8_WAIT_L(0); PG8_BAR; PG8_MMA(0, 0, At, B0); PG8_MMA(0, 1, At, B1); PG8_BAR; PG8_SCHED;
;             PG8_LDA(At, 0, 1); PG8_STAGE(PG8_SB(0, 0), b2, voffB); PG8_STAGE(PG8_SB(0, 1), b2 + hstep, voffB); PG8_STAGE(PG8_SA(0, 0), a2, voffA);
;             PG8_WAIT_V(8); PG8_WAIT_L(0); PG8_BAR; PG8_MMA(1, 0, At, B0); PG8_MMA(1, 1, At, B1); PG8_BAR; PG8_SCHED;
;             PG8_LDB(B0, 1, 0); PG8_LDB(B1, 1, 1); PG8_SCHED; PG8_LDA(At, 1, 0); PG8_STAGE(PG8_SA(0, 1), a2 + hstep, voffA);
;             PG8_WAIT_V(8); PG8_WAIT_L(0); PG8_BAR; PG8_MMA(0, 0, At, B0); PG8_MMA(0, 1, At, B1); PG8_BAR; PG8_SCHED;
;             PG8_LDA(At, 1, 1); PG8_STAGE(PG8_SB(1, 0), b3, voffB); PG8_STAGE(PG8_SB(1, 1), b3 + hstep, voffB); PG8_STAGE(PG8_SA(1, 0), a3, voffA);
;             PG8_WAIT_V(8); PG8_WAIT_L(0); PG8_BAR; PG8_MMA(1, 0, At, B0); PG8_MMA(1, 1, At, B1); PG8_BAR; PG8_SCHED;
	s_add_i32 s26, s53, s38
	v_lshl_add_u64 v[208:209], v[208:209], 0, s[88:89]
	s_mov_b32 m0, s26
	ds_read_b128 v[160:163], v251 offset:49152
	ds_read_b128 v[164:167], v251 offset:50176
	ds_read_b128 v[168:171], v251 offset:51200
	ds_read_b128 v[172:175], v251 offset:52224
	ds_read_b128 v[176:179], v251 offset:53248
	ds_read_b128 v[180:183], v251 offset:54272
	ds_read_b128 v[184:187], v251 offset:55296
	ds_read_b128 v[188:191], v251 offset:56320
	global_load_lds_dwordx4 v[208:209], off
	s_add_i32 m0, s26, 0x2000
	s_add_u32 s24, s24, 0x40080
	v_lshl_add_u64 v[208:209], v[210:211], 0, s[88:89]
	s_addc_u32 s25, s25, 0
	s_add_i32 s26, s69, s38
	global_load_lds_dwordx4 v[208:209], off
	v_lshl_add_u64 v[208:209], s[24:25], 0, v[192:193]
	s_mov_b32 m0, s26
	s_nop 0
	global_load_lds_dwordx4 v[208:209], off
	v_lshl_add_u64 v[208:209], s[24:25], 0, v[198:199]
	s_add_i32 m0, s26, 0x2000
	s_nop 0
	global_load_lds_dwordx4 v[208:209], off
	v_lshl_add_u64 v[208:209], v[212:213], 0, s[88:89]
	s_mov_b32 m0, s62
	s_nop 0
	global_load_lds_dwordx4 v[208:209], off
	v_lshl_add_u64 v[208:209], v[214:215], 0, s[88:89]
	s_mov_b32 m0, s63
	s_nop 0
	global_load_lds_dwordx4 v[208:209], off
	s_waitcnt vmcnt(8)
	s_waitcnt lgkmcnt(0)
	s_barrier
	s_setprio 1
	s_waitcnt lgkmcnt(0)
	v_mfma_f32_16x16x32_bf16 v[60:63], v[112:115], v[160:163], v[60:63]
	v_mfma_f32_16x16x32_bf16 v[56:59], v[124:127], v[160:163], v[56:59]
	v_mfma_f32_16x16x32_bf16 v[44:47], v[112:115], v[168:171], v[44:47]
	v_mfma_f32_16x16x32_bf16 v[40:43], v[124:127], v[168:171], v[40:43]
	v_mfma_f32_16x16x32_bf16 v[28:31], v[112:115], v[176:179], v[28:31]
	v_mfma_f32_16x16x32_bf16 v[24:27], v[124:127], v[176:179], v[24:27]
	v_mfma_f32_16x16x32_bf16 v[12:15], v[112:115], v[184:187], v[12:15]
	v_mfma_f32_16x16x32_bf16 v[8:11], v[124:127], v[184:187], v[8:11]
	v_mfma_f32_16x16x32_bf16 v[60:63], v[120:123], v[164:167], v[60:63]
	v_mfma_f32_16x16x32_bf16 v[56:59], v[128:131], v[164:167], v[56:59]
	v_mfma_f32_16x16x32_bf16 v[44:47], v[120:123], v[172:175], v[44:47]
	v_mfma_f32_16x16x32_bf16 v[40:43], v[128:131], v[172:175], v[40:43]
	v_mfma_f32_16x16x32_bf16 v[28:31], v[120:123], v[180:183], v[28:31]
	v_mfma_f32_16x16x32_bf16 v[24:27], v[128:131], v[180:183], v[24:27]
	v_mfma_f32_16x16x32_bf16 v[12:15], v[120:123], v[188:191], v[12:15]
	v_mfma_f32_16x16x32_bf16 v[8:11], v[128:131], v[188:191], v[8:11]
	s_setprio 0
	s_setprio 1
	v_mfma_f32_16x16x32_bf16 v[52:55], v[136:139], v[160:163], v[52:55]
	v_mfma_f32_16x16x32_bf16 v[48:51], v[144:147], v[160:163], v[48:51]
	v_mfma_f32_16x16x32_bf16 v[36:39], v[136:139], v[168:171], v[36:39]
	v_mfma_f32_16x16x32_bf16 v[32:35], v[144:147], v[168:171], v[32:35]
	v_mfma_f32_16x16x32_bf16 v[20:23], v[136:139], v[176:179], v[20:23]
	v_mfma_f32_16x16x32_bf16 v[16:19], v[144:147], v[176:179], v[16:19]
	v_mfma_f32_16x16x32_bf16 v[4:7], v[136:139], v[184:187], v[4:7]
	v_mfma_f32_16x16x32_bf16 v[0:3], v[144:147], v[184:187], v[0:3]
	v_mfma_f32_16x16x32_bf16 v[52:55], v[140:143], v[164:167], v[52:55]
	v_mfma_f32_16x16x32_bf16 v[48:51], v[156:159], v[164:167], v[48:51]
	v_mfma_f32_16x16x32_bf16 v[36:39], v[140:143], v[172:175], v[36:39]
	v_mfma_f32_16x16x32_bf16 v[32:35], v[156:159], v[172:175], v[32:35]
	v_mfma_f32_16x16x32_bf16 v[20:23], v[140:143], v[180:183], v[20:23]
	v_mfma_f32_16x16x32_bf16 v[16:19], v[156:159], v[180:183], v[16:19]
	v_mfma_f32_16x16x32_bf16 v[4:7], v[140:143], v[188:191], v[4:7]
	v_mfma_f32_16x16x32_bf16 v[0:3], v[156:159], v[188:191], v[0:3]
	s_setprio 0
	s_add_i32 s45, s45, 2
	s_add_u32 s34, s34, 0x100
	s_addc_u32 s44, s44, 0
	s_add_u32 s22, s22, 0x100
	s_addc_u32 s23, s23, 0
	s_cmp_gt_u32 s45, 13
	s_cbranch_scc1 .Lxbar_3
	s_add_u32 s24, s22, 0xfffc0080
	s_addc_u32 s25, s23, -1
	s_add_i32 s53, s35, 0x100
	s_cmp_eq_u32 s45, 12
	s_cselect_b32 s27, s19, s25
	s_cselect_b32 s26, s18, s24
	s_cselect_b32 s25, s15, s44
	s_cselect_b32 s24, s17, s34
	s_add_i32 s69, s90, 0x100
	s_branch .Lhbar_3

; #define PG8_STAGE(bufoff, gbase, voff) do { _Pragma("unroll") for (int _i = 0; _i < 2; ++_i) \
;         __builtin_amdgcn_global_load_lds((const unsigned*)((const char*)(gbase) + (voff)[_i]), (PG8_LAS unsigned*)(lds + (bufoff) + ldsw + _i * 8192), 16, 0, 0); } while (0)
; #define PG8_LDA(dst, b, h) do { _Pragma("unroll") for (int m = 0; m < 4; ++m) _Pragma("unroll") for (int k = 0; k < 2; ++k) dst[m][k] = *(const PG8_LAS bf16x8*)(lds + PG8_SA(b, h) + aoff + m * 2048 + k * 1024); } while (0)
; #define PG8_LDB(dst, b, h) do { _Pragma("unroll") for (int n = 0; n < 2; ++n) _Pragma("unroll") for (int k = 0; k < 2; ++k) dst[n][k] = *(const PG8_LAS bf16x8*)(lds + PG8_SB(b, h) + boff + n * 2048 + k * 1024); } while (0)
; #define PG8_WAIT_V(n) asm volatile("s_waitcnt vmcnt(" #n ")" ::: "memory")
; #define PG8_WAIT_L(n) asm volatile("s_waitcnt lgkmcnt(" #n ")" ::: "memory")
; #define PG8_BAR __builtin_amdgcn_s_barrier()
; #define PG8_SCHED __builtin_amdgcn_sched_barrier(0)
; template <class Epi, class Sched, bool ALIGN_EPI = false, bool SP2 = false>
; __device__ __forceinline__ void gemm_phase(PG8_LAS unsigned char* lds, const Gemm g, const Sched& S, const Epi& E, int wave_in) {
;     ...
;         const bool has_next = S.next(ui + 1, nxt);
;         const char* nA = has_next ? (const char*)g.A + (size_t)(nxt.pm >> g.ash) * g.astride + (size_t)nxt.pm * tstep : cA; const char* nB = has_next ? (const char*)g.Bt + (size_t)(nxt.pm >> g.bsh) * g.bstride + (size_t)nxt.pn * tstep : cB;
;         for (int t = 0; t < nt; t += 2) {
;             const bool last = (t == nt - 2);
;             const char* a1 = cA + (size_t)(t + 1) * kstep;
;             const char* a2 = last ? nA : cA + (size_t)(t + 2) * kstep; const char* b2 = last ? nB : cB + (size_t)(t + 2) * kstep;
;             const char* a3 = a2 + kstep; const char* b3 = b2 + kstep;
;             if (last && has_next) S.a_ready(nxt);
;             if constexpr (SP2) {
;             PG8_LDB(B0, 0, 0); PG8_LDB(B1, 0, 1); PG8_SCHED; PG8_LDA(At, 0, 0); PG8_STAGE(PG8_SA(1, 1), a1 + hstep, voffA);
;             PG8_WAIT_V(8); PG8_WAIT_L(0); PG8_BAR; PG8_MMA(0, 0, At, B0); PG8_MMA(0, 1, At, B1); PG8_BAR; PG8_SCHED;
;             PG8_LDA(At, 0, 1); PG8_STAGE(PG8_SB(0, 0), b2, voffB); PG8_STAGE(PG8_SB(0, 1), b2 + hstep, voffB); PG8_STAGE(PG8_SA(0, 0), a2, voffA);
.LBB0_686:
	s_ashr_i32 s17, s16, 31
	s_lshl_b64 s[18:19], s[16:17], 19
	s_add_u32 s18, s8, s18
	s_addc_u32 s19, s9, s19
	s_and_b64 s[20:21], s[42:43], exec
	s_cselect_b32 s17, s19, s25
	s_cselect_b32 s69, s18, s24
	s_ashr_i32 s20, s16, 5
	s_ashr_i32 s21, s20, 31
	s_lshl_b64 s[20:21], s[20:21], 21
	s_add_u32 s26, s31, s20
	s_addc_u32 s27, s33, s21
	s_ashr_i32 s13, s12, 31
	s_lshl_b64 s[20:21], s[12:13], 19
	s_add_u32 s20, s26, s20
	s_addc_u32 s21, s27, s21
	s_and_b64 s[26:27], s[42:43], exec
	s_cselect_b32 s13, s21, s23
	s_cselect_b32 s34, s20, s22
	s_add_u32 s53, s22, 0x100
	s_addc_u32 s71, s23, 0
	s_add_u32 s22, s24, 0x40080
	s_addc_u32 s23, s25, 0
	s_mov_b32 s72, -2
	s_add_u32 s24, s22, 0xfffc0080
	s_addc_u32 s25, s23, -1
	s_add_i32 s73, s35, 0x100
	s_cmp_eq_u32 s72, 12
	s_cselect_b32 s27, s17, s25
	s_cselect_b32 s26, s69, s24
	s_cselect_b32 s25, s13, s71
	s_cselect_b32 s24, s34, s53
	s_add_i32 s76, s90, 0x100
	v_add_u32_e32 v140, s73, v212
	v_add_u32_e32 v168, s76, v212
	ds_read_b128 v[128:131], v140
	ds_read_b128 v[132:135], v140 offset:1024
	ds_read_b128 v[136:139], v140 offset:2048
	ds_read_b128 v[140:143], v140 offset:3072
	ds_read_b128 v[156:159], v168
	ds_read_b128 v[160:163], v168 offset:1024
	ds_read_b128 v[164:167], v168 offset:2048
	ds_read_b128 v[168:171], v168 offset:3072
	v_lshl_add_u64 v[194:195], s[22:23], 0, v[154:155]
	s_add_i32 m0, s39, 0xc000
	ds_read_b128 v[172:175], v227
	ds_read_b128 v[176:179], v227 offset:1024
	ds_read_b128 v[180:183], v227 offset:2048
	ds_read_b128 v[184:187], v227 offset:3072
	ds_read_b128 v[188:191], v227 offset:4096
	ds_read_b128 v[198:201], v227 offset:5120
	ds_read_b128 v[202:205], v227 offset:6144
	ds_read_b128 v[206:209], v227 offset:7168
	global_load_lds_dwordx4 v[194:195], off
	v_lshl_add_u64 v[194:195], s[22:23], 0, v[152:153]
	s_add_i32 m0, s39, 0xe000
	s_nop 0
	global_load_lds_dwordx4 v[194:195], off
	s_waitcnt vmcnt(8)
	s_waitcnt lgkmcnt(0)
	s_barrier
	s_setprio 1
	s_waitcnt lgkmcnt(0)
	v_mfma_f32_16x16x32_bf16 v[124:127], v[128:131], v[172:175], 0
	v_mfma_f32_16x16x32_bf16 v[120:123], v[136:139], v[172:175], 0
	v_mfma_f32_16x16x32_bf16 v[108:111], v[128:131], v[180:183], 0
	v_mfma_f32_16x16x32_bf16 v[104:107], v[136:139], v[180:183], 0
	v_mfma_f32_16x16x32_bf16 v[96:99], v[128:131], v[188:191], 0
	v_mfma_f32_16x16x32_bf16 v[88:91], v[136:139], v[188:191], 0
	v_mfma_f32_16x16x32_bf16 v[80:83], v[128:131], v[202:205], 0
	v_mfma_f32_16x16x32_bf16 v[72:75], v[136:139], v[202:205], 0
	v_mfma_f32_16x16x32_bf16 v[124:127], v[132:135], v[176:179], v[124:127]
	v_mfma_f32_16x16x32_bf16 v[120:123], v[140:143], v[176:179], v[120:123]
	v_mfma_f32_16x16x32_bf16 v[108:111], v[132:135], v[184:187], v[108:111]
	v_mfma_f32_16x16x32_bf16 v[104:107], v[140:143], v[184:187], v[104:107]
	v_mfma_f32_16x16x32_bf16 v[96:99], v[132:135], v[198:201], v[96:99]
	v_mfma_f32_16x16x32_bf16 v[88:91], v[140:143], v[198:201], v[88:91]
	v_mfma_f32_16x16x32_bf16 v[80:83], v[132:135], v[206:209], v[80:83]
	v_mfma_f32_16x16x32_bf16 v[72:75], v[140:143], v[206:209], v[72:75]
	s_setprio 0
	s_setprio 1
	v_mfma_f32_16x16x32_bf16 v[116:119], v[156:159], v[172:175], 0
	v_mfma_f32_16x16x32_bf16 v[112:115], v[164:167], v[172:175], 0
	v_mfma_f32_16x16x32_bf16 v[100:103], v[156:159], v[180:183], 0
	v_mfma_f32_16x16x32_bf16 v[92:95], v[164:167], v[180:183], 0
	v_mfma_f32_16x16x32_bf16 v[84:87], v[156:159], v[188:191], 0
	v_mfma_f32_16x16x32_bf16 v[76:79], v[164:167], v[188:191], 0
	v_mfma_f32_16x16x32_bf16 v[68:71], v[156:159], v[202:205], 0
	v_mfma_f32_16x16x32_bf16 v[64:67], v[164:167], v[202:205], 0
	v_mfma_f32_16x16x32_bf16 v[116:119], v[160:163], v[176:179], v[116:119]
	v_mfma_f32_16x16x32_bf16 v[112:115], v[168:171], v[176:179], v[112:115]
	v_mfma_f32_16x16x32_bf16 v[100:103], v[160:163], v[184:187], v[100:103]
	v_mfma_f32_16x16x32_bf16 v[92:95], v[168:171], v[184:187], v[92:95]
	v_mfma_f32_16x16x32_bf16 v[84:87], v[160:163], v[198:201], v[84:87]
	v_mfma_f32_16x16x32_bf16 v[76:79], v[168:171], v[198:201], v[76:79]
	v_mfma_f32_16x16x32_bf16 v[68:71], v[160:163], v[206:209], v[68:71]
	v_mfma_f32_16x16x32_bf16 v[64:67], v[168:171], v[206:209], v[64:67]
	s_setprio 0
	s_barrier
	s_add_i32 s73, s73, s38
	v_lshl_add_u64 v[194:195], s[24:25], 0, v[148:149]
	s_mov_b32 m0, s73
	ds_read_b128 v[172:175], v227 offset:16384
	ds_read_b128 v[176:179], v227 offset:17408
	ds_read_b128 v[180:183], v227 offset:18432
	ds_read_b128 v[184:187], v227 offset:19456
	ds_read_b128 v[188:191], v227 offset:20480
	ds_read_b128 v[198:201], v227 offset:21504
	ds_read_b128 v[202:205], v227 offset:22528
	ds_read_b128 v[206:209], v227 offset:23552
	global_load_lds_dwordx4 v[194:195], off
	s_add_i32 m0, s73, 0x2000
	s_add_u32 s74, s24, 0x40000
	v_lshl_add_u64 v[196:197], s[24:25], 0, v[144:145]
	s_addc_u32 s75, s25, 0
	s_add_i32 s73, s76, s38
	global_load_lds_dwordx4 v[196:197], off
	v_lshl_add_u64 v[234:235], s[74:75], 0, v[148:149]
	s_mov_b32 m0, s73
	v_lshl_add_u64 v[236:237], s[26:27], 0, v[146:147]
	global_load_lds_dwordx4 v[234:235], off
	v_lshl_add_u64 v[234:235], s[74:75], 0, v[144:145]
	s_add_i32 m0, s73, 0x2000
	s_nop 0
	global_load_lds_dwordx4 v[234:235], off
	v_lshl_add_u64 v[234:235], s[26:27], 0, v[150:151]
	s_mov_b32 m0, s39
	s_nop 0
	global_load_lds_dwordx4 v[234:235], off
	s_mov_b32 m0, s44
	s_nop 0
	global_load_lds_dwordx4 v[236:237], off
	s_waitcnt vmcnt(8)
	s_waitcnt lgkmcnt(0)
	s_barrier
; #define PG8_STAGE(bufoff, gbase, voff) do { _Pragma("unroll") for (int _i = 0; _i < 2; ++_i) \
;         __builtin_amdgcn_global_load_lds((const unsigned*)((const char*)(gbase) + (voff)[_i]), (PG8_LAS unsigned*)(lds + (bufoff) + ldsw + _i * 8192), 16, 0, 0); } while (0)
; #define PG8_LDA(dst, b, h) do { _Pragma("unroll") for (int m = 0; m < 4; ++m) _Pragma("unroll") for (int k = 0; k < 2; ++k) dst[m][k] = *(const PG8_LAS bf16x8*)(lds + PG8_SA(b, h) + aoff + m * 2048 + k * 1024); } while (0)
; #define PG8_LDB(dst, b, h) do { _Pragma("unroll") for (int n = 0; n < 2; ++n) _Pragma("unroll") for (int k = 0; k < 2; ++k) dst[n][k] = *(const PG8_LAS bf16x8*)(lds + PG8_SB(b, h) + boff + n * 2048 + k * 1024); } while (0)
; #define PG8_MMA(ai, bj, At, Bt) do { __builtin_amdgcn_s_setprio(1); _Pragma("unroll") for (int m = 0; m < 4; ++m) _Pragma("unroll") for (int n = 0; n < 2; ++n) _Pragma("unroll") for (int k = 0; k < 2; ++k) \
;         acc[ai][bj][m][n] = __builtin_amdgcn_mfma_f32_16x16x32_bf16(Bt[n][k], At[m][k], acc[ai][bj][m][n], 0, 0, 0); __builtin_amdgcn_s_setprio(0); } while (0)
; #define PG8_WAIT_V(n) asm volatile("s_waitcnt vmcnt(" #n ")" ::: "memory")
; #define PG8_WAIT_L(n) asm volatile("s_waitcnt lgkmcnt(" #n ")" ::: "memory")
; #define PG8_BAR __builtin_amdgcn_s_barrier()
; #define PG8_SCHED __builtin_amdgcn_sched_barrier(0)
; template <class Epi, class Sched, bool ALIGN_EPI = false, bool SP2 = false>
; __device__ __forceinline__ void gemm_phase(PG8_LAS unsigned char* lds, const Gemm g, const Sched& S, const Epi& E, int wave_in) {
;     ...
;             PG8_WAIT_V(8); PG8_WAIT_L(0); PG8_BAR; PG8_MMA(1, 0, At, B0); PG8_MMA(1, 1, At, B1); PG8_BAR; PG8_SCHED;
;             PG8_LDB(B0, 1, 0); PG8_LDB(B1, 1, 1); PG8_SCHED; PG8_LDA(At, 1, 0); PG8_STAGE(PG8_SA(0, 1), a2 + hstep, voffA);
;             PG8_WAIT_V(8); PG8_WAIT_L(0); PG8_BAR; PG8_MMA(0, 0, At, B0); PG8_MMA(0, 1, At, B1); PG8_BAR; PG8_SCHED;
	s_setprio 1
	s_waitcnt lgkmcnt(0)
	v_mfma_f32_16x16x32_bf16 v[60:63], v[128:131], v[172:175], 0
	v_mfma_f32_16x16x32_bf16 v[56:59], v[136:139], v[172:175], 0
	v_mfma_f32_16x16x32_bf16 v[48:51], v[128:131], v[180:183], 0
	v_mfma_f32_16x16x32_bf16 v[40:43], v[136:139], v[180:183], 0
	v_mfma_f32_16x16x32_bf16 v[32:35], v[128:131], v[188:191], 0
	v_mfma_f32_16x16x32_bf16 v[24:27], v[136:139], v[188:191], 0
	v_mfma_f32_16x16x32_bf16 v[16:19], v[128:131], v[202:205], 0
	v_mfma_f32_16x16x32_bf16 v[8:11], v[136:139], v[202:205], 0
	v_mfma_f32_16x16x32_bf16 v[60:63], v[132:135], v[176:179], v[60:63]
	v_mfma_f32_16x16x32_bf16 v[56:59], v[140:143], v[176:179], v[56:59]
	v_mfma_f32_16x16x32_bf16 v[48:51], v[132:135], v[184:187], v[48:51]
	v_mfma_f32_16x16x32_bf16 v[40:43], v[140:143], v[184:187], v[40:43]
	v_mfma_f32_16x16x32_bf16 v[32:35], v[132:135], v[198:201], v[32:35]
	v_mfma_f32_16x16x32_bf16 v[24:27], v[140:143], v[198:201], v[24:27]
	v_mfma_f32_16x16x32_bf16 v[16:19], v[132:135], v[206:209], v[16:19]
	v_mfma_f32_16x16x32_bf16 v[8:11], v[140:143], v[206:209], v[8:11]
	s_setprio 0
	s_setprio 1
	v_mfma_f32_16x16x32_bf16 v[52:55], v[156:159], v[172:175], 0
	v_mfma_f32_16x16x32_bf16 v[44:47], v[164:167], v[172:175], 0
	v_mfma_f32_16x16x32_bf16 v[36:39], v[156:159], v[180:183], 0
	v_mfma_f32_16x16x32_bf16 v[28:31], v[164:167], v[180:183], 0
	v_mfma_f32_16x16x32_bf16 v[20:23], v[156:159], v[188:191], 0
	v_mfma_f32_16x16x32_bf16 v[12:15], v[164:167], v[188:191], 0
	v_mfma_f32_16x16x32_bf16 v[4:7], v[156:159], v[202:205], 0
	v_mfma_f32_16x16x32_bf16 v[0:3], v[164:167], v[202:205], 0
	v_mfma_f32_16x16x32_bf16 v[52:55], v[160:163], v[176:179], v[52:55]
	v_mfma_f32_16x16x32_bf16 v[44:47], v[168:171], v[176:179], v[44:47]
	v_mfma_f32_16x16x32_bf16 v[36:39], v[160:163], v[184:187], v[36:39]
	v_mfma_f32_16x16x32_bf16 v[28:31], v[168:171], v[184:187], v[28:31]
	v_mfma_f32_16x16x32_bf16 v[20:23], v[160:163], v[198:201], v[20:23]
	v_mfma_f32_16x16x32_bf16 v[12:15], v[168:171], v[198:201], v[12:15]
	v_mfma_f32_16x16x32_bf16 v[4:7], v[160:163], v[206:209], v[4:7]
	v_mfma_f32_16x16x32_bf16 v[0:3], v[168:171], v[206:209], v[0:3]
	s_setprio 0
	s_barrier
	s_add_i32 s73, s65, 0x100
	s_add_i32 s74, s52, 0x100
	v_add_u32_e32 v140, s73, v212
	v_add_u32_e32 v168, s74, v212
	ds_read_b128 v[128:131], v140
	ds_read_b128 v[132:135], v140 offset:1024
	ds_read_b128 v[136:139], v140 offset:2048
	ds_read_b128 v[140:143], v140 offset:3072
	ds_read_b128 v[156:159], v168
	ds_read_b128 v[160:163], v168 offset:1024
	ds_read_b128 v[164:167], v168 offset:2048
	ds_read_b128 v[168:171], v168 offset:3072
	s_add_u32 s26, s26, 0x40000
	s_addc_u32 s27, s27, 0
	s_mov_b32 m0, s45
	v_lshl_add_u64 v[238:239], s[26:27], 0, v[150:151]
	ds_read_b128 v[172:175], v227 offset:32768
	ds_read_b128 v[176:179], v227 offset:33792
	ds_read_b128 v[180:183], v227 offset:34816
	ds_read_b128 v[184:187], v227 offset:35840
	ds_read_b128 v[188:191], v227 offset:36864
	ds_read_b128 v[198:201], v227 offset:37888
	ds_read_b128 v[202:205], v227 offset:38912
	ds_read_b128 v[206:209], v227 offset:39936
	global_load_lds_dwordx4 v[238:239], off
	v_lshl_add_u64 v[238:239], s[26:27], 0, v[146:147]
	s_mov_b32 m0, s46
	s_nop 0
	global_load_lds_dwordx4 v[238:239], off
	s_waitcnt vmcnt(8)
	s_waitcnt lgkmcnt(0)
	s_barrier
	s_setprio 1
	s_waitcnt lgkmcnt(0)
	v_mfma_f32_16x16x32_bf16 v[124:127], v[128:131], v[172:175], v[124:127]
	v_mfma_f32_16x16x32_bf16 v[120:123], v[136:139], v[172:175], v[120:123]
	v_mfma_f32_16x16x32_bf16 v[108:111], v[128:131], v[180:183], v[108:111]
	v_mfma_f32_16x16x32_bf16 v[104:107], v[136:139], v[180:183], v[104:107]
	v_mfma_f32_16x16x32_bf16 v[96:99], v[128:131], v[188:191], v[96:99]
	v_mfma_f32_16x16x32_bf16 v[88:91], v[136:139], v[188:191], v[88:91]
	v_mfma_f32_16x16x32_bf16 v[80:83], v[128:131], v[202:205], v[80:83]
	v_mfma_f32_16x16x32_bf16 v[72:75], v[136:139], v[202:205], v[72:75]
	v_mfma_f32_16x16x32_bf16 v[124:127], v[132:135], v[176:179], v[124:127]
	v_mfma_f32_16x16x32_bf16 v[120:123], v[140:143], v[176:179], v[120:123]
	v_mfma_f32_16x16x32_bf16 v[108:111], v[132:135], v[184:187], v[108:111]
	v_mfma_f32_16x16x32_bf16 v[104:107], v[140:143], v[184:187], v[104:107]
	v_mfma_f32_16x16x32_bf16 v[96:99], v[132:135], v[198:201], v[96:99]
	v_mfma_f32_16x16x32_bf16 v[88:91], v[140:143], v[198:201], v[88:91]
	v_mfma_f32_16x16x32_bf16 v[80:83], v[132:135], v[206:209], v[80:83]
	v_mfma_f32_16x16x32_bf16 v[72:75], v[140:143], v[206:209], v[72:75]
	s_setprio 0
	s_setprio 1
	v_mfma_f32_16x16x32_bf16 v[116:119], v[156:159], v[172:175], v[116:119]
	v_mfma_f32_16x16x32_bf16 v[112:115], v[164:167], v[172:175], v[112:115]
	v_mfma_f32_16x16x32_bf16 v[100:103], v[156:159], v[180:183], v[100:103]
	v_mfma_f32_16x16x32_bf16 v[92:95], v[164:167], v[180:183], v[92:95]
	v_mfma_f32_16x16x32_bf16 v[84:87], v[156:159], v[188:191], v[84:87]
	v_mfma_f32_16x16x32_bf16 v[76:79], v[164:167], v[188:191], v[76:79]
	v_mfma_f32_16x16x32_bf16 v[68:71], v[156:159], v[202:205], v[68:71]
	v_mfma_f32_16x16x32_bf16 v[64:67], v[164:167], v[202:205], v[64:67]
	v_mfma_f32_16x16x32_bf16 v[116:119], v[160:163], v[176:179], v[116:119]
	v_mfma_f32_16x16x32_bf16 v[112:115], v[168:171], v[176:179], v[112:115]
	v_mfma_f32_16x16x32_bf16 v[100:103], v[160:163], v[184:187], v[100:103]
	v_mfma_f32_16x16x32_bf16 v[92:95], v[168:171], v[184:187], v[92:95]
	v_mfma_f32_16x16x32_bf16 v[84:87], v[160:163], v[198:201], v[84:87]
	v_mfma_f32_16x16x32_bf16 v[76:79], v[168:171], v[198:201], v[76:79]
	v_mfma_f32_16x16x32_bf16 v[68:71], v[160:163], v[206:209], v[68:71]
	v_mfma_f32_16x16x32_bf16 v[64:67], v[168:171], v[206:209], v[64:67]
	s_setprio 0
	s_barrier
; #define PG8_STAGE(bufoff, gbase, voff) do { _Pragma("unroll") for (int _i = 0; _i < 2; ++_i) \
;         __builtin_amdgcn_global_load_lds((const unsigned*)((const char*)(gbase) + (voff)[_i]), (PG8_LAS unsigned*)(lds + (bufoff) + ldsw + _i * 8192), 16, 0, 0); } while (0)
; #define PG8_LDA(dst, b, h) do { _Pragma("unroll") for (int m = 0; m < 4; ++m) _Pragma("unroll") for (int k = 0; k < 2; ++k) dst[m][k] = *(const PG8_LAS bf16x8*)(lds + PG8_SA(b, h) + aoff + m * 2048 + k * 1024); } while (0)
; #define PG8_WAIT_V(n) asm volatile("s_waitcnt vmcnt(" #n ")" ::: "memory")
; #define PG8_WAIT_L(n) asm volatile("s_waitcnt lgkmcnt(" #n ")" ::: "memory")
; #define PG8_BAR __builtin_amdgcn_s_barrier()
; template <class Epi, class Sched, bool ALIGN_EPI = false, bool SP2 = false>
; __device__ __forceinline__ void gemm_phase(PG8_LAS unsigned char* lds, const Gemm g, const Sched& S, const Epi& E, int wave_in) {
;     ...
;         for (int t = 0; t < nt; t += 2) {
;             const bool last = (t == nt - 2);
;             const char* a1 = cA + (size_t)(t + 1) * kstep;
;             const char* a2 = last ? nA : cA + (size_t)(t + 2) * kstep; const char* b2 = last ? nB : cB + (size_t)(t + 2) * kstep;
;             const char* a3 = a2 + kstep; const char* b3 = b2 + kstep;
;             if (last && has_next) S.a_ready(nxt);
;             if constexpr (SP2) {
;             PG8_LDB(B0, 0, 0); PG8_LDB(B1, 0, 1); PG8_SCHED; PG8_LDA(At, 0, 0); PG8_STAGE(PG8_SA(1, 1), a1 + hstep, voffA);
;             PG8_WAIT_V(8); PG8_WAIT_L(0); PG8_BAR; PG8_MMA(0, 0, At, B0); PG8_MMA(0, 1, At, B1); PG8_BAR; PG8_SCHED;
;             PG8_LDA(At, 0, 1); PG8_STAGE(PG8_SB(0, 0), b2, voffB); PG8_STAGE(PG8_SB(0, 1), b2 + hstep, voffB); PG8_STAGE(PG8_SA(0, 0), a2, voffA);
;             PG8_WAIT_V(8); PG8_WAIT_L(0); PG8_BAR; PG8_MMA(1, 0, At, B0); PG8_MMA(1, 1, At, B1); PG8_BAR; PG8_SCHED;
;             PG8_LDB(B0, 1, 0); PG8_LDB(B1, 1, 1); PG8_SCHED; PG8_LDA(At, 1, 0); PG8_STAGE(PG8_SA(0, 1), a2 + hstep, voffA);
;             PG8_WAIT_V(8); PG8_WAIT_L(0); PG8_BAR; PG8_MMA(0, 0, At, B0); PG8_MMA(0, 1, At, B1); PG8_BAR; PG8_SCHED;
;             PG8_LDA(At, 1, 1); PG8_STAGE(PG8_SB(1, 0), b3, voffB); PG8_STAGE(PG8_SB(1, 1), b3 + hstep, voffB); PG8_STAGE(PG8_SA(1, 0), a3, voffA);
;             PG8_WAIT_V(8); PG8_WAIT_L(0); PG8_BAR; PG8_MMA(1, 0, At, B0); PG8_MMA(1, 1, At, B1); PG8_BAR; PG8_SCHED;
	s_add_i32 s26, s73, s38
	v_lshl_add_u64 v[194:195], v[194:195], 0, s[88:89]
	s_mov_b32 m0, s26
	ds_read_b128 v[172:175], v227 offset:49152
	ds_read_b128 v[176:179], v227 offset:50176
	ds_read_b128 v[180:183], v227 offset:51200
	ds_read_b128 v[184:187], v227 offset:52224
	ds_read_b128 v[188:191], v227 offset:53248
	ds_read_b128 v[198:201], v227 offset:54272
	ds_read_b128 v[202:205], v227 offset:55296
	ds_read_b128 v[206:209], v227 offset:56320
	global_load_lds_dwordx4 v[194:195], off
	s_add_i32 m0, s26, 0x2000
	s_add_u32 s24, s24, 0x40080
	v_lshl_add_u64 v[194:195], v[196:197], 0, s[88:89]
	s_addc_u32 s25, s25, 0
	s_add_i32 s26, s74, s38
	global_load_lds_dwordx4 v[194:195], off
	v_lshl_add_u64 v[194:195], s[24:25], 0, v[148:149]
	s_mov_b32 m0, s26
	s_nop 0
	global_load_lds_dwordx4 v[194:195], off
	v_lshl_add_u64 v[194:195], s[24:25], 0, v[144:145]
	s_add_i32 m0, s26, 0x2000
	s_nop 0
	global_load_lds_dwordx4 v[194:195], off
	v_lshl_add_u64 v[194:195], v[234:235], 0, s[88:89]
	s_mov_b32 m0, s61
	s_nop 0
	global_load_lds_dwordx4 v[194:195], off
	v_lshl_add_u64 v[194:195], v[236:237], 0, s[88:89]
	s_mov_b32 m0, s62
	s_nop 0
	global_load_lds_dwordx4 v[194:195], off
	s_waitcnt vmcnt(8)
	s_waitcnt lgkmcnt(0)
	s_barrier
	s_setprio 1
	s_waitcnt lgkmcnt(0)
	v_mfma_f32_16x16x32_bf16 v[60:63], v[128:131], v[172:175], v[60:63]
	v_mfma_f32_16x16x32_bf16 v[56:59], v[136:139], v[172:175], v[56:59]
	v_mfma_f32_16x16x32_bf16 v[48:51], v[128:131], v[180:183], v[48:51]
	v_mfma_f32_16x16x32_bf16 v[40:43], v[136:139], v[180:183], v[40:43]
	v_mfma_f32_16x16x32_bf16 v[32:35], v[128:131], v[188:191], v[32:35]
	v_mfma_f32_16x16x32_bf16 v[24:27], v[136:139], v[188:191], v[24:27]
	v_mfma_f32_16x16x32_bf16 v[16:19], v[128:131], v[202:205], v[16:19]
	v_mfma_f32_16x16x32_bf16 v[8:11], v[136:139], v[202:205], v[8:11]
	v_mfma_f32_16x16x32_bf16 v[60:63], v[132:135], v[176:179], v[60:63]
	v_mfma_f32_16x16x32_bf16 v[56:59], v[140:143], v[176:179], v[56:59]
	v_mfma_f32_16x16x32_bf16 v[48:51], v[132:135], v[184:187], v[48:51]
	v_mfma_f32_16x16x32_bf16 v[40:43], v[140:143], v[184:187], v[40:43]
	v_mfma_f32_16x16x32_bf16 v[32:35], v[132:135], v[198:201], v[32:35]
	v_mfma_f32_16x16x32_bf16 v[24:27], v[140:143], v[198:201], v[24:27]
	v_mfma_f32_16x16x32_bf16 v[16:19], v[132:135], v[206:209], v[16:19]
	v_mfma_f32_16x16x32_bf16 v[8:11], v[140:143], v[206:209], v[8:11]
	s_setprio 0
	s_setprio 1
	v_mfma_f32_16x16x32_bf16 v[52:55], v[156:159], v[172:175], v[52:55]
	v_mfma_f32_16x16x32_bf16 v[44:47], v[164:167], v[172:175], v[44:47]
	v_mfma_f32_16x16x32_bf16 v[36:39], v[156:159], v[180:183], v[36:39]
	v_mfma_f32_16x16x32_bf16 v[28:31], v[164:167], v[180:183], v[28:31]
	v_mfma_f32_16x16x32_bf16 v[20:23], v[156:159], v[188:191], v[20:23]
	v_mfma_f32_16x16x32_bf16 v[12:15], v[164:167], v[188:191], v[12:15]
	v_mfma_f32_16x16x32_bf16 v[4:7], v[156:159], v[202:205], v[4:7]
	v_mfma_f32_16x16x32_bf16 v[0:3], v[164:167], v[202:205], v[0:3]
	v_mfma_f32_16x16x32_bf16 v[52:55], v[160:163], v[176:179], v[52:55]
	v_mfma_f32_16x16x32_bf16 v[44:47], v[168:171], v[176:179], v[44:47]
	v_mfma_f32_16x16x32_bf16 v[36:39], v[160:163], v[184:187], v[36:39]
	v_mfma_f32_16x16x32_bf16 v[28:31], v[168:171], v[184:187], v[28:31]
	v_mfma_f32_16x16x32_bf16 v[20:23], v[160:163], v[198:201], v[20:23]
	v_mfma_f32_16x16x32_bf16 v[12:15], v[168:171], v[198:201], v[12:15]
	v_mfma_f32_16x16x32_bf16 v[4:7], v[160:163], v[206:209], v[4:7]
	v_mfma_f32_16x16x32_bf16 v[0:3], v[168:171], v[206:209], v[0:3]
	s_setprio 0
	s_add_i32 s72, s72, 2
	s_add_u32 s53, s53, 0x100
	s_addc_u32 s71, s71, 0
	s_add_u32 s22, s22, 0x100
	s_addc_u32 s23, s23, 0
	s_cmp_gt_u32 s72, 13
	s_cbranch_scc1 .Lxbar_4
	s_add_u32 s24, s22, 0xfffc0080
	s_addc_u32 s25, s23, -1
	s_add_i32 s73, s35, 0x100
	s_cmp_eq_u32 s72, 12
	s_cselect_b32 s27, s17, s25
	s_cselect_b32 s26, s69, s24
	s_cselect_b32 s25, s13, s71
	s_cselect_b32 s24, s34, s53
	s_add_i32 s76, s90, 0x100

; #define PG8_STAGE(bufoff, gbase, voff) do { _Pragma("unroll") for (int _i = 0; _i < 2; ++_i) \
;         __builtin_amdgcn_global_load_lds((const unsigned*)((const char*)(gbase) + (voff)[_i]), (PG8_LAS unsigned*)(lds + (bufoff) + ldsw + _i * 8192), 16, 0, 0); } while (0)
; #define PG8_LDA(dst, b, h) do { _Pragma("unroll") for (int m = 0; m < 4; ++m) _Pragma("unroll") for (int k = 0; k < 2; ++k) dst[m][k] = *(const PG8_LAS bf16x8*)(lds + PG8_SA(b, h) + aoff + m * 2048 + k * 1024); } while (0)
; #define PG8_LDB(dst, b, h) do { _Pragma("unroll") for (int n = 0; n < 2; ++n) _Pragma("unroll") for (int k = 0; k < 2; ++k) dst[n][k] = *(const PG8_LAS bf16x8*)(lds + PG8_SB(b, h) + boff + n * 2048 + k * 1024); } while (0)
; #define PG8_MMA(ai, bj, At, Bt) do { __builtin_amdgcn_s_setprio(1); _Pragma("unroll") for (int m = 0; m < 4; ++m) _Pragma("unroll") for (int n = 0; n < 2; ++n) _Pragma("unroll") for (int k = 0; k < 2; ++k) \
;         acc[ai][bj][m][n] = __builtin_amdgcn_mfma_f32_16x16x32_bf16(Bt[n][k], At[m][k], acc[ai][bj][m][n], 0, 0, 0); __builtin_amdgcn_s_setprio(0); } while (0)
; #define PG8_WAIT_V(n) asm volatile("s_waitcnt vmcnt(" #n ")" ::: "memory")
; #define PG8_WAIT_L(n) asm volatile("s_waitcnt lgkmcnt(" #n ")" ::: "memory")
; #define PG8_BAR __builtin_amdgcn_s_barrier()
; #define PG8_SCHED __builtin_amdgcn_sched_barrier(0)
; template <class Epi, class Sched, bool ALIGN_EPI = false, bool SP2 = false>
; __device__ __forceinline__ void gemm_phase(PG8_LAS unsigned char* lds, const Gemm g, const Sched& S, const Epi& E, int wave_in) {
;     ...
;             PG8_LDB(B0, 0, 0); PG8_LDB(B1, 0, 1); PG8_SCHED; PG8_LDA(At, 0, 0); PG8_STAGE(PG8_SA(1, 1), a1 + hstep, voffA);
;             PG8_WAIT_V(8); PG8_WAIT_L(0); PG8_BAR; PG8_MMA(0, 0, At, B0); PG8_MMA(0, 1, At, B1); PG8_BAR; PG8_SCHED;
;             PG8_LDA(At, 0, 1); PG8_STAGE(PG8_SB(0, 0), b2, voffB); PG8_STAGE(PG8_SB(0, 1), b2 + hstep, voffB); PG8_STAGE(PG8_SA(0, 0), a2, voffA);
;             PG8_WAIT_V(8); PG8_WAIT_L(0); PG8_BAR; PG8_MMA(1, 0, At, B0); PG8_MMA(1, 1, At, B1); PG8_BAR; PG8_SCHED;
.LBB0_687:
	v_add_u32_e32 v140, s73, v212
	v_add_u32_e32 v168, s76, v212
	ds_read_b128 v[128:131], v140
	ds_read_b128 v[132:135], v140 offset:1024
	ds_read_b128 v[136:139], v140 offset:2048
	ds_read_b128 v[140:143], v140 offset:3072
	ds_read_b128 v[156:159], v168
	ds_read_b128 v[160:163], v168 offset:1024
	ds_read_b128 v[164:167], v168 offset:2048
	ds_read_b128 v[168:171], v168 offset:3072
	v_lshl_add_u64 v[194:195], s[22:23], 0, v[154:155]
	s_add_i32 m0, s39, 0xc000
	ds_read_b128 v[172:175], v227
	ds_read_b128 v[176:179], v227 offset:1024
	ds_read_b128 v[180:183], v227 offset:2048
	ds_read_b128 v[184:187], v227 offset:3072
	ds_read_b128 v[188:191], v227 offset:4096
	ds_read_b128 v[198:201], v227 offset:5120
	ds_read_b128 v[202:205], v227 offset:6144
	ds_read_b128 v[206:209], v227 offset:7168
	global_load_lds_dwordx4 v[194:195], off
	v_lshl_add_u64 v[194:195], s[22:23], 0, v[152:153]
	s_add_i32 m0, s39, 0xe000
	s_nop 0
	global_load_lds_dwordx4 v[194:195], off
	s_waitcnt vmcnt(8)
	s_waitcnt lgkmcnt(0)
	s_barrier
	s_setprio 1
	s_waitcnt lgkmcnt(0)
	v_mfma_f32_16x16x32_bf16 v[124:127], v[128:131], v[172:175], v[124:127]
	v_mfma_f32_16x16x32_bf16 v[120:123], v[136:139], v[172:175], v[120:123]
	v_mfma_f32_16x16x32_bf16 v[108:111], v[128:131], v[180:183], v[108:111]
	v_mfma_f32_16x16x32_bf16 v[104:107], v[136:139], v[180:183], v[104:107]
	v_mfma_f32_16x16x32_bf16 v[96:99], v[128:131], v[188:191], v[96:99]
	v_mfma_f32_16x16x32_bf16 v[88:91], v[136:139], v[188:191], v[88:91]
	v_mfma_f32_16x16x32_bf16 v[80:83], v[128:131], v[202:205], v[80:83]
	v_mfma_f32_16x16x32_bf16 v[72:75], v[136:139], v[202:205], v[72:75]
	v_mfma_f32_16x16x32_bf16 v[124:127], v[132:135], v[176:179], v[124:127]
	v_mfma_f32_16x16x32_bf16 v[120:123], v[140:143], v[176:179], v[120:123]
	v_mfma_f32_16x16x32_bf16 v[108:111], v[132:135], v[184:187], v[108:111]
	v_mfma_f32_16x16x32_bf16 v[104:107], v[140:143], v[184:187], v[104:107]
	v_mfma_f32_16x16x32_bf16 v[96:99], v[132:135], v[198:201], v[96:99]
	v_mfma_f32_16x16x32_bf16 v[88:91], v[140:143], v[198:201], v[88:91]
	v_mfma_f32_16x16x32_bf16 v[80:83], v[132:135], v[206:209], v[80:83]
	v_mfma_f32_16x16x32_bf16 v[72:75], v[140:143], v[206:209], v[72:75]
	s_setprio 0
	s_setprio 1
	v_mfma_f32_16x16x32_bf16 v[116:119], v[156:159], v[172:175], v[116:119]
	v_mfma_f32_16x16x32_bf16 v[112:115], v[164:167], v[172:175], v[112:115]
	v_mfma_f32_16x16x32_bf16 v[100:103], v[156:159], v[180:183], v[100:103]
	v_mfma_f32_16x16x32_bf16 v[92:95], v[164:167], v[180:183], v[92:95]
	v_mfma_f32_16x16x32_bf16 v[84:87], v[156:159], v[188:191], v[84:87]
	v_mfma_f32_16x16x32_bf16 v[76:79], v[164:167], v[188:191], v[76:79]
	v_mfma_f32_16x16x32_bf16 v[68:71], v[156:159], v[202:205], v[68:71]
	v_mfma_f32_16x16x32_bf16 v[64:67], v[164:167], v[202:205], v[64:67]
	v_mfma_f32_16x16x32_bf16 v[116:119], v[160:163], v[176:179], v[116:119]
	v_mfma_f32_16x16x32_bf16 v[112:115], v[168:171], v[176:179], v[112:115]
	v_mfma_f32_16x16x32_bf16 v[100:103], v[160:163], v[184:187], v[100:103]
	v_mfma_f32_16x16x32_bf16 v[92:95], v[168:171], v[184:187], v[92:95]
	v_mfma_f32_16x16x32_bf16 v[84:87], v[160:163], v[198:201], v[84:87]
	v_mfma_f32_16x16x32_bf16 v[76:79], v[168:171], v[198:201], v[76:79]
	v_mfma_f32_16x16x32_bf16 v[68:71], v[160:163], v[206:209], v[68:71]
	v_mfma_f32_16x16x32_bf16 v[64:67], v[168:171], v[206:209], v[64:67]
	s_setprio 0
	s_barrier
	s_add_i32 s73, s73, s38
	v_lshl_add_u64 v[194:195], s[24:25], 0, v[148:149]
	s_mov_b32 m0, s73
	ds_read_b128 v[172:175], v227 offset:16384
	ds_read_b128 v[176:179], v227 offset:17408
	ds_read_b128 v[180:183], v227 offset:18432
	ds_read_b128 v[184:187], v227 offset:19456
	ds_read_b128 v[188:191], v227 offset:20480
	ds_read_b128 v[198:201], v227 offset:21504
	ds_read_b128 v[202:205], v227 offset:22528
	ds_read_b128 v[206:209], v227 offset:23552
	global_load_lds_dwordx4 v[194:195], off
	s_add_i32 m0, s73, 0x2000
	s_add_u32 s74, s24, 0x40000
	v_lshl_add_u64 v[196:197], s[24:25], 0, v[144:145]
	s_addc_u32 s75, s25, 0
	s_add_i32 s73, s76, s38
	global_load_lds_dwordx4 v[196:197], off
	v_lshl_add_u64 v[234:235], s[74:75], 0, v[148:149]
	s_mov_b32 m0, s73
	v_lshl_add_u64 v[236:237], s[26:27], 0, v[146:147]
	global_load_lds_dwordx4 v[234:235], off
	v_lshl_add_u64 v[234:235], s[74:75], 0, v[144:145]
	s_add_i32 m0, s73, 0x2000
	s_nop 0
	global_load_lds_dwordx4 v[234:235], off
	v_lshl_add_u64 v[234:235], s[26:27], 0, v[150:151]
	s_mov_b32 m0, s39
	s_nop 0
	global_load_lds_dwordx4 v[234:235], off
	s_mov_b32 m0, s44
	s_nop 0
	global_load_lds_dwordx4 v[236:237], off
	s_waitcnt vmcnt(8)
	s_waitcnt lgkmcnt(0)
	s_barrier
; #define PG8_STAGE(bufoff, gbase, voff) do { _Pragma("unroll") for (int _i = 0; _i < 2; ++_i) \
;         __builtin_amdgcn_global_load_lds((const unsigned*)((const char*)(gbase) + (voff)[_i]), (PG8_LAS unsigned*)(lds + (bufoff) + ldsw + _i * 8192), 16, 0, 0); } while (0)
; #define PG8_LDA(dst, b, h) do { _Pragma("unroll") for (int m = 0; m < 4; ++m) _Pragma("unroll") for (int k = 0; k < 2; ++k) dst[m][k] = *(const PG8_LAS bf16x8*)(lds + PG8_SA(b, h) + aoff + m * 2048 + k * 1024); } while (0)
; #define PG8_LDB(dst, b, h) do { _Pragma("unroll") for (int n = 0; n < 2; ++n) _Pragma("unroll") for (int k = 0; k < 2; ++k) dst[n][k] = *(const PG8_LAS bf16x8*)(lds + PG8_SB(b, h) + boff + n * 2048 + k * 1024); } while (0)
; #define PG8_MMA(ai, bj, At, Bt) do { __builtin_amdgcn_s_setprio(1); _Pragma("unroll") for (int m = 0; m < 4; ++m) _Pragma("unroll") for (int n = 0; n < 2; ++n) _Pragma("unroll") for (int k = 0; k < 2; ++k) \
;         acc[ai][bj][m][n] = __builtin_amdgcn_mfma_f32_16x16x32_bf16(Bt[n][k], At[m][k], acc[ai][bj][m][n], 0, 0, 0); __builtin_amdgcn_s_setprio(0); } while (0)
; #define PG8_WAIT_V(n) asm volatile("s_waitcnt vmcnt(" #n ")" ::: "memory")
; #define PG8_WAIT_L(n) asm volatile("s_waitcnt lgkmcnt(" #n ")" ::: "memory")
; #define PG8_BAR __builtin_amdgcn_s_barrier()
; #define PG8_SCHED __builtin_amdgcn_sched_barrier(0)
; template <class Epi, class Sched, bool ALIGN_EPI = false, bool SP2 = false>
; __device__ __forceinline__ void gemm_phase(PG8_LAS unsigned char* lds, const Gemm g, const Sched& S, const Epi& E, int wave_in) {
;     ...
;             PG8_WAIT_V(8); PG8_WAIT_L(0); PG8_BAR; PG8_MMA(1, 0, At, B0); PG8_MMA(1, 1, At, B1); PG8_BAR; PG8_SCHED;
;             PG8_LDB(B0, 1, 0); PG8_LDB(B1, 1, 1); PG8_SCHED; PG8_LDA(At, 1, 0); PG8_STAGE(PG8_SA(0, 1), a2 + hstep, voffA);
;             PG8_WAIT_V(8); PG8_WAIT_L(0); PG8_BAR; PG8_MMA(0, 0, At, B0); PG8_MMA(0, 1, At, B1); PG8_BAR; PG8_SCHED;
	s_setprio 1
	s_waitcnt lgkmcnt(0)
	v_mfma_f32_16x16x32_bf16 v[60:63], v[128:131], v[172:175], v[60:63]
	v_mfma_f32_16x16x32_bf16 v[56:59], v[136:139], v[172:175], v[56:59]
	v_mfma_f32_16x16x32_bf16 v[48:51], v[128:131], v[180:183], v[48:51]
	v_mfma_f32_16x16x32_bf16 v[40:43], v[136:139], v[180:183], v[40:43]
	v_mfma_f32_16x16x32_bf16 v[32:35], v[128:131], v[188:191], v[32:35]
	v_mfma_f32_16x16x32_bf16 v[24:27], v[136:139], v[188:191], v[24:27]
	v_mfma_f32_16x16x32_bf16 v[16:19], v[128:131], v[202:205], v[16:19]
	v_mfma_f32_16x16x32_bf16 v[8:11], v[136:139], v[202:205], v[8:11]
	v_mfma_f32_16x16x32_bf16 v[60:63], v[132:135], v[176:179], v[60:63]
	v_mfma_f32_16x16x32_bf16 v[56:59], v[140:143], v[176:179], v[56:59]
	v_mfma_f32_16x16x32_bf16 v[48:51], v[132:135], v[184:187], v[48:51]
	v_mfma_f32_16x16x32_bf16 v[40:43], v[140:143], v[184:187], v[40:43]
	v_mfma_f32_16x16x32_bf16 v[32:35], v[132:135], v[198:201], v[32:35]
	v_mfma_f32_16x16x32_bf16 v[24:27], v[140:143], v[198:201], v[24:27]
	v_mfma_f32_16x16x32_bf16 v[16:19], v[132:135], v[206:209], v[16:19]
	v_mfma_f32_16x16x32_bf16 v[8:11], v[140:143], v[206:209], v[8:11]
	s_setprio 0
	s_setprio 1
	v_mfma_f32_16x16x32_bf16 v[52:55], v[156:159], v[172:175], v[52:55]
	v_mfma_f32_16x16x32_bf16 v[44:47], v[164:167], v[172:175], v[44:47]
	v_mfma_f32_16x16x32_bf16 v[36:39], v[156:159], v[180:183], v[36:39]
	v_mfma_f32_16x16x32_bf16 v[28:31], v[164:167], v[180:183], v[28:31]
	v_mfma_f32_16x16x32_bf16 v[20:23], v[156:159], v[188:191], v[20:23]
	v_mfma_f32_16x16x32_bf16 v[12:15], v[164:167], v[188:191], v[12:15]
	v_mfma_f32_16x16x32_bf16 v[4:7], v[156:159], v[202:205], v[4:7]
	v_mfma_f32_16x16x32_bf16 v[0:3], v[164:167], v[202:205], v[0:3]
	v_mfma_f32_16x16x32_bf16 v[52:55], v[160:163], v[176:179], v[52:55]
	v_mfma_f32_16x16x32_bf16 v[44:47], v[168:171], v[176:179], v[44:47]
	v_mfma_f32_16x16x32_bf16 v[36:39], v[160:163], v[184:187], v[36:39]
	v_mfma_f32_16x16x32_bf16 v[28:31], v[168:171], v[184:187], v[28:31]
	v_mfma_f32_16x16x32_bf16 v[20:23], v[160:163], v[198:201], v[20:23]
	v_mfma_f32_16x16x32_bf16 v[12:15], v[168:171], v[198:201], v[12:15]
	v_mfma_f32_16x16x32_bf16 v[4:7], v[160:163], v[206:209], v[4:7]
	v_mfma_f32_16x16x32_bf16 v[0:3], v[168:171], v[206:209], v[0:3]
	s_setprio 0
	s_barrier
	s_add_i32 s73, s65, 0x100
	s_add_i32 s74, s52, 0x100
	v_add_u32_e32 v140, s73, v212
	v_add_u32_e32 v168, s74, v212
	ds_read_b128 v[128:131], v140
	ds_read_b128 v[132:135], v140 offset:1024
	ds_read_b128 v[136:139], v140 offset:2048
	ds_read_b128 v[140:143], v140 offset:3072
	ds_read_b128 v[156:159], v168
	ds_read_b128 v[160:163], v168 offset:1024
	ds_read_b128 v[164:167], v168 offset:2048
	ds_read_b128 v[168:171], v168 offset:3072
	s_add_u32 s26, s26, 0x40000
	s_addc_u32 s27, s27, 0
	s_mov_b32 m0, s45
	v_lshl_add_u64 v[238:239], s[26:27], 0, v[150:151]
	ds_read_b128 v[172:175], v227 offset:32768
	ds_read_b128 v[176:179], v227 offset:33792
	ds_read_b128 v[180:183], v227 offset:34816
	ds_read_b128 v[184:187], v227 offset:35840
	ds_read_b128 v[188:191], v227 offset:36864
	ds_read_b128 v[198:201], v227 offset:37888
	ds_read_b128 v[202:205], v227 offset:38912
	ds_read_b128 v[206:209], v227 offset:39936
	global_load_lds_dwordx4 v[238:239], off
	v_lshl_add_u64 v[238:239], s[26:27], 0, v[146:147]
	s_mov_b32 m0, s46
	s_nop 0
	global_load_lds_dwordx4 v[238:239], off
	s_waitcnt vmcnt(8)
	s_waitcnt lgkmcnt(0)
	s_barrier
	s_setprio 1
	s_waitcnt lgkmcnt(0)
	v_mfma_f32_16x16x32_bf16 v[124:127], v[128:131], v[172:175], v[124:127]
	v_mfma_f32_16x16x32_bf16 v[120:123], v[136:139], v[172:175], v[120:123]
	v_mfma_f32_16x16x32_bf16 v[108:111], v[128:131], v[180:183], v[108:111]
	v_mfma_f32_16x16x32_bf16 v[104:107], v[136:139], v[180:183], v[104:107]
	v_mfma_f32_16x16x32_bf16 v[96:99], v[128:131], v[188:191], v[96:99]
	v_mfma_f32_16x16x32_bf16 v[88:91], v[136:139], v[188:191], v[88:91]
	v_mfma_f32_16x16x32_bf16 v[80:83], v[128:131], v[202:205], v[80:83]
	v_mfma_f32_16x16x32_bf16 v[72:75], v[136:139], v[202:205], v[72:75]
	v_mfma_f32_16x16x32_bf16 v[124:127], v[132:135], v[176:179], v[124:127]
	v_mfma_f32_16x16x32_bf16 v[120:123], v[140:143], v[176:179], v[120:123]
	v_mfma_f32_16x16x32_bf16 v[108:111], v[132:135], v[184:187], v[108:111]
	v_mfma_f32_16x16x32_bf16 v[104:107], v[140:143], v[184:187], v[104:107]
	v_mfma_f32_16x16x32_bf16 v[96:99], v[132:135], v[198:201], v[96:99]
	v_mfma_f32_16x16x32_bf16 v[88:91], v[140:143], v[198:201], v[88:91]
	v_mfma_f32_16x16x32_bf16 v[80:83], v[132:135], v[206:209], v[80:83]
	v_mfma_f32_16x16x32_bf16 v[72:75], v[140:143], v[206:209], v[72:75]
	s_setprio 0
	s_setprio 1
	v_mfma_f32_16x16x32_bf16 v[116:119], v[156:159], v[172:175], v[116:119]
	v_mfma_f32_16x16x32_bf16 v[112:115], v[164:167], v[172:175], v[112:115]
	v_mfma_f32_16x16x32_bf16 v[100:103], v[156:159], v[180:183], v[100:103]
	v_mfma_f32_16x16x32_bf16 v[92:95], v[164:167], v[180:183], v[92:95]
	v_mfma_f32_16x16x32_bf16 v[84:87], v[156:159], v[188:191], v[84:87]
	v_mfma_f32_16x16x32_bf16 v[76:79], v[164:167], v[188:191], v[76:79]
	v_mfma_f32_16x16x32_bf16 v[68:71], v[156:159], v[202:205], v[68:71]
	v_mfma_f32_16x16x32_bf16 v[64:67], v[164:167], v[202:205], v[64:67]
	v_mfma_f32_16x16x32_bf16 v[116:119], v[160:163], v[176:179], v[116:119]
	v_mfma_f32_16x16x32_bf16 v[112:115], v[168:171], v[176:179], v[112:115]
	v_mfma_f32_16x16x32_bf16 v[100:103], v[160:163], v[184:187], v[100:103]
	v_mfma_f32_16x16x32_bf16 v[92:95], v[168:171], v[184:187], v[92:95]
	v_mfma_f32_16x16x32_bf16 v[84:87], v[160:163], v[198:201], v[84:87]
	v_mfma_f32_16x16x32_bf16 v[76:79], v[168:171], v[198:201], v[76:79]
	v_mfma_f32_16x16x32_bf16 v[68:71], v[160:163], v[206:209], v[68:71]
	v_mfma_f32_16x16x32_bf16 v[64:67], v[168:171], v[206:209], v[64:67]
	s_setprio 0
	s_barrier
; #define PG8_STAGE(bufoff, gbase, voff) do { _Pragma("unroll") for (int _i = 0; _i < 2; ++_i) \
;         __builtin_amdgcn_global_load_lds((const unsigned*)((const char*)(gbase) + (voff)[_i]), (PG8_LAS unsigned*)(lds + (bufoff) + ldsw + _i * 8192), 16, 0, 0); } while (0)
; #define PG8_LDA(dst, b, h) do { _Pragma("unroll") for (int m = 0; m < 4; ++m) _Pragma("unroll") for (int k = 0; k < 2; ++k) dst[m][k] = *(const PG8_LAS bf16x8*)(lds + PG8_SA(b, h) + aoff + m * 2048 + k * 1024); } while (0)
; #define PG8_WAIT_V(n) asm volatile("s_waitcnt vmcnt(" #n ")" ::: "memory")
; #define PG8_WAIT_L(n) asm volatile("s_waitcnt lgkmcnt(" #n ")" ::: "memory")
; #define PG8_BAR __builtin_amdgcn_s_barrier()
; template <class Epi, class Sched, bool ALIGN_EPI = false, bool SP2 = false>
; __device__ __forceinline__ void gemm_phase(PG8_LAS unsigned char* lds, const Gemm g, const Sched& S, const Epi& E, int wave_in) {
;     ...
;         for (int t = 0; t < nt; t += 2) {
;             const bool last = (t == nt - 2);
;             const char* a1 = cA + (size_t)(t + 1) * kstep;
;             const char* a2 = last ? nA : cA + (size_t)(t + 2) * kstep; const char* b2 = last ? nB : cB + (size_t)(t + 2) * kstep;
;             const char* a3 = a2 + kstep; const char* b3 = b2 + kstep;
;             if (last && has_next) S.a_ready(nxt);
;             if constexpr (SP2) {
;             PG8_LDB(B0, 0, 0); PG8_LDB(B1, 0, 1); PG8_SCHED; PG8_LDA(At, 0, 0); PG8_STAGE(PG8_SA(1, 1), a1 + hstep, voffA);
;             PG8_WAIT_V(8); PG8_WAIT_L(0); PG8_BAR; PG8_MMA(0, 0, At, B0); PG8_MMA(0, 1, At, B1); PG8_BAR; PG8_SCHED;
;             PG8_LDA(At, 0, 1); PG8_STAGE(PG8_SB(0, 0), b2, voffB); PG8_STAGE(PG8_SB(0, 1), b2 + hstep, voffB); PG8_STAGE(PG8_SA(0, 0), a2, voffA);
;             PG8_WAIT_V(8); PG8_WAIT_L(0); PG8_BAR; PG8_MMA(1, 0, At, B0); PG8_MMA(1, 1, At, B1); PG8_BAR; PG8_SCHED;
;             PG8_LDB(B0, 1, 0); PG8_LDB(B1, 1, 1); PG8_SCHED; PG8_LDA(At, 1, 0); PG8_STAGE(PG8_SA(0, 1), a2 + hstep, voffA);
;             PG8_WAIT_V(8); PG8_WAIT_L(0); PG8_BAR; PG8_MMA(0, 0, At, B0); PG8_MMA(0, 1, At, B1); PG8_BAR; PG8_SCHED;
;             PG8_LDA(At, 1, 1); PG8_STAGE(PG8_SB(1, 0), b3, voffB); PG8_STAGE(PG8_SB(1, 1), b3 + hstep, voffB); PG8_STAGE(PG8_SA(1, 0), a3, voffA);
;             PG8_WAIT_V(8); PG8_WAIT_L(0); PG8_BAR; PG8_MMA(1, 0, At, B0); PG8_MMA(1, 1, At, B1); PG8_BAR; PG8_SCHED;
	s_add_i32 s26, s73, s38
	v_lshl_add_u64 v[194:195], v[194:195], 0, s[88:89]
	s_mov_b32 m0, s26
	ds_read_b128 v[172:175], v227 offset:49152
	ds_read_b128 v[176:179], v227 offset:50176
	ds_read_b128 v[180:183], v227 offset:51200
	ds_read_b128 v[184:187], v227 offset:52224
	ds_read_b128 v[188:191], v227 offset:53248
	ds_read_b128 v[198:201], v227 offset:54272
	ds_read_b128 v[202:205], v227 offset:55296
	ds_read_b128 v[206:209], v227 offset:56320
	global_load_lds_dwordx4 v[194:195], off
	s_add_i32 m0, s26, 0x2000
	s_add_u32 s24, s24, 0x40080
	v_lshl_add_u64 v[194:195], v[196:197], 0, s[88:89]
	s_addc_u32 s25, s25, 0
	s_add_i32 s26, s74, s38
	global_load_lds_dwordx4 v[194:195], off
	v_lshl_add_u64 v[194:195], s[24:25], 0, v[148:149]
	s_mov_b32 m0, s26
	s_nop 0
	global_load_lds_dwordx4 v[194:195], off
	v_lshl_add_u64 v[194:195], s[24:25], 0, v[144:145]
	s_add_i32 m0, s26, 0x2000
	s_nop 0
	global_load_lds_dwordx4 v[194:195], off
	v_lshl_add_u64 v[194:195], v[234:235], 0, s[88:89]
	s_mov_b32 m0, s61
	s_nop 0
	global_load_lds_dwordx4 v[194:195], off
	v_lshl_add_u64 v[194:195], v[236:237], 0, s[88:89]
	s_mov_b32 m0, s62
	s_nop 0
	global_load_lds_dwordx4 v[194:195], off
	s_waitcnt vmcnt(8)
	s_waitcnt lgkmcnt(0)
	s_barrier
	s_setprio 1
	s_waitcnt lgkmcnt(0)
	v_mfma_f32_16x16x32_bf16 v[60:63], v[128:131], v[172:175], v[60:63]
	v_mfma_f32_16x16x32_bf16 v[56:59], v[136:139], v[172:175], v[56:59]
	v_mfma_f32_16x16x32_bf16 v[48:51], v[128:131], v[180:183], v[48:51]
	v_mfma_f32_16x16x32_bf16 v[40:43], v[136:139], v[180:183], v[40:43]
	v_mfma_f32_16x16x32_bf16 v[32:35], v[128:131], v[188:191], v[32:35]
	v_mfma_f32_16x16x32_bf16 v[24:27], v[136:139], v[188:191], v[24:27]
	v_mfma_f32_16x16x32_bf16 v[16:19], v[128:131], v[202:205], v[16:19]
	v_mfma_f32_16x16x32_bf16 v[8:11], v[136:139], v[202:205], v[8:11]
	v_mfma_f32_16x16x32_bf16 v[60:63], v[132:135], v[176:179], v[60:63]
	v_mfma_f32_16x16x32_bf16 v[56:59], v[140:143], v[176:179], v[56:59]
	v_mfma_f32_16x16x32_bf16 v[48:51], v[132:135], v[184:187], v[48:51]
	v_mfma_f32_16x16x32_bf16 v[40:43], v[140:143], v[184:187], v[40:43]
	v_mfma_f32_16x16x32_bf16 v[32:35], v[132:135], v[198:201], v[32:35]
	v_mfma_f32_16x16x32_bf16 v[24:27], v[140:143], v[198:201], v[24:27]
	v_mfma_f32_16x16x32_bf16 v[16:19], v[132:135], v[206:209], v[16:19]
	v_mfma_f32_16x16x32_bf16 v[8:11], v[140:143], v[206:209], v[8:11]
	s_setprio 0
	s_setprio 1
	v_mfma_f32_16x16x32_bf16 v[52:55], v[156:159], v[172:175], v[52:55]
	v_mfma_f32_16x16x32_bf16 v[44:47], v[164:167], v[172:175], v[44:47]
	v_mfma_f32_16x16x32_bf16 v[36:39], v[156:159], v[180:183], v[36:39]
	v_mfma_f32_16x16x32_bf16 v[28:31], v[164:167], v[180:183], v[28:31]
	v_mfma_f32_16x16x32_bf16 v[20:23], v[156:159], v[188:191], v[20:23]
	v_mfma_f32_16x16x32_bf16 v[12:15], v[164:167], v[188:191], v[12:15]
	v_mfma_f32_16x16x32_bf16 v[4:7], v[156:159], v[202:205], v[4:7]
	v_mfma_f32_16x16x32_bf16 v[0:3], v[164:167], v[202:205], v[0:3]
	v_mfma_f32_16x16x32_bf16 v[52:55], v[160:163], v[176:179], v[52:55]
	v_mfma_f32_16x16x32_bf16 v[44:47], v[168:171], v[176:179], v[44:47]
	v_mfma_f32_16x16x32_bf16 v[36:39], v[160:163], v[184:187], v[36:39]
	v_mfma_f32_16x16x32_bf16 v[28:31], v[168:171], v[184:187], v[28:31]
	v_mfma_f32_16x16x32_bf16 v[20:23], v[160:163], v[198:201], v[20:23]
	v_mfma_f32_16x16x32_bf16 v[12:15], v[168:171], v[198:201], v[12:15]
	v_mfma_f32_16x16x32_bf16 v[4:7], v[160:163], v[206:209], v[4:7]
	v_mfma_f32_16x16x32_bf16 v[0:3], v[168:171], v[206:209], v[0:3]
	s_setprio 0
	s_add_i32 s72, s72, 2
	s_add_u32 s53, s53, 0x100
	s_addc_u32 s71, s71, 0
	s_add_u32 s22, s22, 0x100
	s_addc_u32 s23, s23, 0
	s_cmp_gt_u32 s72, 13
	s_cbranch_scc1 .Lxbar_4
	s_add_u32 s24, s22, 0xfffc0080
	s_addc_u32 s25, s23, -1
	s_add_i32 s73, s35, 0x100
	s_cmp_eq_u32 s72, 12
	s_cselect_b32 s27, s17, s25
	s_cselect_b32 s26, s69, s24
	s_cselect_b32 s25, s13, s71
	s_cselect_b32 s24, s34, s53
	s_add_i32 s76, s90, 0x100
	s_branch .Lhbar_4

; #define PG8_STAGE(bufoff, gbase, voff) do { _Pragma("unroll") for (int _i = 0; _i < 2; ++_i) \
;         __builtin_amdgcn_global_load_lds((const unsigned*)((const char*)(gbase) + (voff)[_i]), (PG8_LAS unsigned*)(lds + (bufoff) + ldsw + _i * 8192), 16, 0, 0); } while (0)
; #define PG8_LDA(dst, b, h) do { _Pragma("unroll") for (int m = 0; m < 4; ++m) _Pragma("unroll") for (int k = 0; k < 2; ++k) dst[m][k] = *(const PG8_LAS bf16x8*)(lds + PG8_SA(b, h) + aoff + m * 2048 + k * 1024); } while (0)
; #define PG8_LDB(dst, b, h) do { _Pragma("unroll") for (int n = 0; n < 2; ++n) _Pragma("unroll") for (int k = 0; k < 2; ++k) dst[n][k] = *(const PG8_LAS bf16x8*)(lds + PG8_SB(b, h) + boff + n * 2048 + k * 1024); } while (0)
; #define PG8_MMA(ai, bj, At, Bt) do { __builtin_amdgcn_s_setprio(1); _Pragma("unroll") for (int m = 0; m < 4; ++m) _Pragma("unroll") for (int n = 0; n < 2; ++n) _Pragma("unroll") for (int k = 0; k < 2; ++k) \
;         acc[ai][bj][m][n] = __builtin_amdgcn_mfma_f32_16x16x32_bf16(Bt[n][k], At[m][k], acc[ai][bj][m][n], 0, 0, 0); __builtin_amdgcn_s_setprio(0); } while (0)
; #define PG8_WAIT_V(n) asm volatile("s_waitcnt vmcnt(" #n ")" ::: "memory")
; #define PG8_WAIT_L(n) asm volatile("s_waitcnt lgkmcnt(" #n ")" ::: "memory")
; #define PG8_BAR __builtin_amdgcn_s_barrier()
; #define PG8_SCHED __builtin_amdgcn_sched_barrier(0)
; template <class Epi, class Sched, bool ALIGN_EPI = false, bool SP2 = false>
; __device__ __forceinline__ void gemm_phase(PG8_LAS unsigned char* lds, const Gemm g, const Sched& S, const Epi& E, int wave_in) {
;     ...
;         for (int t = 0; t < nt; t += 2) {
;             const bool last = (t == nt - 2);
;             const char* a1 = cA + (size_t)(t + 1) * kstep;
;             const char* a2 = last ? nA : cA + (size_t)(t + 2) * kstep; const char* b2 = last ? nB : cB + (size_t)(t + 2) * kstep;
;             const char* a3 = a2 + kstep; const char* b3 = b2 + kstep;
;             if (last && has_next) S.a_ready(nxt);
;             if constexpr (SP2) {
;             PG8_LDB(B0, 0, 0); PG8_LDB(B1, 0, 1); PG8_SCHED; PG8_LDA(At, 0, 0); PG8_STAGE(PG8_SA(1, 1), a1 + hstep, voffA);
;             PG8_WAIT_V(8); PG8_WAIT_L(0); PG8_BAR; PG8_MMA(0, 0, At, B0); PG8_MMA(0, 1, At, B1); PG8_BAR; PG8_SCHED;
;             PG8_LDA(At, 0, 1); PG8_STAGE(PG8_SB(0, 0), b2, voffB); PG8_STAGE(PG8_SB(0, 1), b2 + hstep, voffB); PG8_STAGE(PG8_SA(0, 0), a2, voffA);
.LBB0_803:
	s_add_u32 s15, s22, 0x100
	s_addc_u32 s17, s23, 0
	s_add_u32 s22, s24, 0x40080
	s_addc_u32 s23, s25, 0
	s_mov_b32 s34, -2
	s_add_u32 s24, s22, 0xfffc0080
	s_addc_u32 s25, s23, -1
	s_add_i32 s44, s35, 0x100
	s_cmp_eq_u32 s34, 12
	s_cselect_b32 s27, s19, s25
	s_cselect_b32 s26, s18, s24
	s_cselect_b32 s25, s21, s17
	s_cselect_b32 s24, s20, s15
	s_add_i32 s53, s90, 0x100
	v_add_u32_e32 v128, s44, v249
	v_add_u32_e32 v156, s53, v249
	ds_read_b128 v[112:115], v128
	ds_read_b128 v[120:123], v128 offset:1024
	ds_read_b128 v[124:127], v128 offset:2048
	ds_read_b128 v[128:131], v128 offset:3072
	ds_read_b128 v[136:139], v156
	ds_read_b128 v[140:143], v156 offset:1024
	ds_read_b128 v[144:147], v156 offset:2048
	ds_read_b128 v[156:159], v156 offset:3072
	v_lshl_add_u64 v[194:195], s[22:23], 0, v[206:207]
	s_add_i32 m0, s39, 0xc000
	ds_read_b128 v[160:163], v251
	ds_read_b128 v[164:167], v251 offset:1024
	ds_read_b128 v[168:171], v251 offset:2048
	ds_read_b128 v[172:175], v251 offset:3072
	ds_read_b128 v[176:179], v251 offset:4096
	ds_read_b128 v[180:183], v251 offset:5120
	ds_read_b128 v[184:187], v251 offset:6144
	ds_read_b128 v[188:191], v251 offset:7168
	global_load_lds_dwordx4 v[194:195], off
	v_lshl_add_u64 v[194:195], s[22:23], 0, v[204:205]
	s_add_i32 m0, s39, 0xe000
	s_nop 0
	global_load_lds_dwordx4 v[194:195], off
	s_waitcnt vmcnt(8)
	s_waitcnt lgkmcnt(0)
	s_barrier
	s_setprio 1
	s_waitcnt lgkmcnt(0)
	v_mfma_f32_16x16x32_bf16 v[152:155], v[112:115], v[160:163], 0
	v_mfma_f32_16x16x32_bf16 v[148:151], v[124:127], v[160:163], 0
	v_mfma_f32_16x16x32_bf16 v[108:111], v[112:115], v[168:171], 0
	v_mfma_f32_16x16x32_bf16 v[104:107], v[124:127], v[168:171], 0
	v_mfma_f32_16x16x32_bf16 v[92:95], v[112:115], v[176:179], 0
	v_mfma_f32_16x16x32_bf16 v[88:91], v[124:127], v[176:179], 0
	v_mfma_f32_16x16x32_bf16 v[76:79], v[112:115], v[184:187], 0
	v_mfma_f32_16x16x32_bf16 v[72:75], v[124:127], v[184:187], 0
	v_mfma_f32_16x16x32_bf16 v[152:155], v[120:123], v[164:167], v[152:155]
	v_mfma_f32_16x16x32_bf16 v[148:151], v[128:131], v[164:167], v[148:151]
	v_mfma_f32_16x16x32_bf16 v[108:111], v[120:123], v[172:175], v[108:111]
	v_mfma_f32_16x16x32_bf16 v[104:107], v[128:131], v[172:175], v[104:107]
	v_mfma_f32_16x16x32_bf16 v[92:95], v[120:123], v[180:183], v[92:95]
	v_mfma_f32_16x16x32_bf16 v[88:91], v[128:131], v[180:183], v[88:91]
	v_mfma_f32_16x16x32_bf16 v[76:79], v[120:123], v[188:191], v[76:79]
	v_mfma_f32_16x16x32_bf16 v[72:75], v[128:131], v[188:191], v[72:75]
	s_setprio 0
	s_setprio 1
	v_mfma_f32_16x16x32_bf16 v[132:135], v[136:139], v[160:163], 0
	v_mfma_f32_16x16x32_bf16 v[116:119], v[144:147], v[160:163], 0
	v_mfma_f32_16x16x32_bf16 v[100:103], v[136:139], v[168:171], 0
	v_mfma_f32_16x16x32_bf16 v[96:99], v[144:147], v[168:171], 0
	v_mfma_f32_16x16x32_bf16 v[84:87], v[136:139], v[176:179], 0
	v_mfma_f32_16x16x32_bf16 v[80:83], v[144:147], v[176:179], 0
	v_mfma_f32_16x16x32_bf16 v[68:71], v[136:139], v[184:187], 0
	v_mfma_f32_16x16x32_bf16 v[64:67], v[144:147], v[184:187], 0
	v_mfma_f32_16x16x32_bf16 v[132:135], v[140:143], v[164:167], v[132:135]
	v_mfma_f32_16x16x32_bf16 v[116:119], v[156:159], v[164:167], v[116:119]
	v_mfma_f32_16x16x32_bf16 v[100:103], v[140:143], v[172:175], v[100:103]
	v_mfma_f32_16x16x32_bf16 v[96:99], v[156:159], v[172:175], v[96:99]
	v_mfma_f32_16x16x32_bf16 v[84:87], v[140:143], v[180:183], v[84:87]
	v_mfma_f32_16x16x32_bf16 v[80:83], v[156:159], v[180:183], v[80:83]
	v_mfma_f32_16x16x32_bf16 v[68:71], v[140:143], v[188:191], v[68:71]
	v_mfma_f32_16x16x32_bf16 v[64:67], v[156:159], v[188:191], v[64:67]
	s_setprio 0
	s_barrier
	s_add_i32 s44, s44, s38
	v_lshl_add_u64 v[194:195], s[24:25], 0, v[192:193]
	s_mov_b32 m0, s44
	ds_read_b128 v[160:163], v251 offset:16384
	ds_read_b128 v[164:167], v251 offset:17408
	ds_read_b128 v[168:171], v251 offset:18432
	ds_read_b128 v[172:175], v251 offset:19456
	ds_read_b128 v[176:179], v251 offset:20480
	ds_read_b128 v[180:183], v251 offset:21504
	ds_read_b128 v[184:187], v251 offset:22528
	ds_read_b128 v[188:191], v251 offset:23552
	global_load_lds_dwordx4 v[194:195], off
	s_add_i32 m0, s44, 0x2000
	s_add_u32 s44, s24, 0x40000
	v_lshl_add_u64 v[196:197], s[24:25], 0, v[198:199]
	s_addc_u32 s45, s25, 0
	s_add_i32 s53, s53, s38
	global_load_lds_dwordx4 v[196:197], off
	v_lshl_add_u64 v[208:209], s[44:45], 0, v[192:193]
	s_mov_b32 m0, s53
	v_lshl_add_u64 v[210:211], s[26:27], 0, v[200:201]
	global_load_lds_dwordx4 v[208:209], off
	v_lshl_add_u64 v[208:209], s[44:45], 0, v[198:199]
	s_add_i32 m0, s53, 0x2000
	s_nop 0
	global_load_lds_dwordx4 v[208:209], off
	v_lshl_add_u64 v[208:209], s[26:27], 0, v[202:203]
	s_mov_b32 m0, s39
	s_nop 0
	global_load_lds_dwordx4 v[208:209], off
	s_mov_b32 m0, s46
	s_nop 0
	global_load_lds_dwordx4 v[210:211], off
	s_waitcnt vmcnt(8)
	s_waitcnt lgkmcnt(0)
	s_barrier
; #define PG8_STAGE(bufoff, gbase, voff) do { _Pragma("unroll") for (int _i = 0; _i < 2; ++_i) \
;         __builtin_amdgcn_global_load_lds((const unsigned*)((const char*)(gbase) + (voff)[_i]), (PG8_LAS unsigned*)(lds + (bufoff) + ldsw + _i * 8192), 16, 0, 0); } while (0)
; #define PG8_LDA(dst, b, h) do { _Pragma("unroll") for (int m = 0; m < 4; ++m) _Pragma("unroll") for (int k = 0; k < 2; ++k) dst[m][k] = *(const PG8_LAS bf16x8*)(lds + PG8_SA(b, h) + aoff + m * 2048 + k * 1024); } while (0)
; #define PG8_LDB(dst, b, h) do { _Pragma("unroll") for (int n = 0; n < 2; ++n) _Pragma("unroll") for (int k = 0; k < 2; ++k) dst[n][k] = *(const PG8_LAS bf16x8*)(lds + PG8_SB(b, h) + boff + n * 2048 + k * 1024); } while (0)
; #define PG8_MMA(ai, bj, At, Bt) do { __builtin_amdgcn_s_setprio(1); _Pragma("unroll") for (int m = 0; m < 4; ++m) _Pragma("unroll") for (int n = 0; n < 2; ++n) _Pragma("unroll") for (int k = 0; k < 2; ++k) \
;         acc[ai][bj][m][n] = __builtin_amdgcn_mfma_f32_16x16x32_bf16(Bt[n][k], At[m][k], acc[ai][bj][m][n], 0, 0, 0); __builtin_amdgcn_s_setprio(0); } while (0)
; #define PG8_WAIT_V(n) asm volatile("s_waitcnt vmcnt(" #n ")" ::: "memory")
; #define PG8_WAIT_L(n) asm volatile("s_waitcnt lgkmcnt(" #n ")" ::: "memory")
; #define PG8_BAR __builtin_amdgcn_s_barrier()
; #define PG8_SCHED __builtin_amdgcn_sched_barrier(0)
; template <class Epi, class Sched, bool ALIGN_EPI = false, bool SP2 = false>
; __device__ __forceinline__ void gemm_phase(PG8_LAS unsigned char* lds, const Gemm g, const Sched& S, const Epi& E, int wave_in) {
;     ...
;             PG8_WAIT_V(8); PG8_WAIT_L(0); PG8_BAR; PG8_MMA(1, 0, At, B0); PG8_MMA(1, 1, At, B1); PG8_BAR; PG8_SCHED;
;             PG8_LDB(B0, 1, 0); PG8_LDB(B1, 1, 1); PG8_SCHED; PG8_LDA(At, 1, 0); PG8_STAGE(PG8_SA(0, 1), a2 + hstep, voffA);
;             PG8_WAIT_V(8); PG8_WAIT_L(0); PG8_BAR; PG8_MMA(0, 0, At, B0); PG8_MMA(0, 1, At, B1); PG8_BAR; PG8_SCHED;
	s_setprio 1
	s_waitcnt lgkmcnt(0)
	v_mfma_f32_16x16x32_bf16 v[60:63], v[112:115], v[160:163], 0
	v_mfma_f32_16x16x32_bf16 v[56:59], v[124:127], v[160:163], 0
	v_mfma_f32_16x16x32_bf16 v[44:47], v[112:115], v[168:171], 0
	v_mfma_f32_16x16x32_bf16 v[40:43], v[124:127], v[168:171], 0
	v_mfma_f32_16x16x32_bf16 v[28:31], v[112:115], v[176:179], 0
	v_mfma_f32_16x16x32_bf16 v[24:27], v[124:127], v[176:179], 0
	v_mfma_f32_16x16x32_bf16 v[12:15], v[112:115], v[184:187], 0
	v_mfma_f32_16x16x32_bf16 v[8:11], v[124:127], v[184:187], 0
	v_mfma_f32_16x16x32_bf16 v[60:63], v[120:123], v[164:167], v[60:63]
	v_mfma_f32_16x16x32_bf16 v[56:59], v[128:131], v[164:167], v[56:59]
	v_mfma_f32_16x16x32_bf16 v[44:47], v[120:123], v[172:175], v[44:47]
	v_mfma_f32_16x16x32_bf16 v[40:43], v[128:131], v[172:175], v[40:43]
	v_mfma_f32_16x16x32_bf16 v[28:31], v[120:123], v[180:183], v[28:31]
	v_mfma_f32_16x16x32_bf16 v[24:27], v[128:131], v[180:183], v[24:27]
	v_mfma_f32_16x16x32_bf16 v[12:15], v[120:123], v[188:191], v[12:15]
	v_mfma_f32_16x16x32_bf16 v[8:11], v[128:131], v[188:191], v[8:11]
	s_setprio 0
	s_setprio 1
	v_mfma_f32_16x16x32_bf16 v[52:55], v[136:139], v[160:163], 0
	v_mfma_f32_16x16x32_bf16 v[48:51], v[144:147], v[160:163], 0
	v_mfma_f32_16x16x32_bf16 v[36:39], v[136:139], v[168:171], 0
	v_mfma_f32_16x16x32_bf16 v[32:35], v[144:147], v[168:171], 0
	v_mfma_f32_16x16x32_bf16 v[20:23], v[136:139], v[176:179], 0
	v_mfma_f32_16x16x32_bf16 v[16:19], v[144:147], v[176:179], 0
	v_mfma_f32_16x16x32_bf16 v[4:7], v[136:139], v[184:187], 0
	v_mfma_f32_16x16x32_bf16 v[0:3], v[144:147], v[184:187], 0
	v_mfma_f32_16x16x32_bf16 v[52:55], v[140:143], v[164:167], v[52:55]
	v_mfma_f32_16x16x32_bf16 v[48:51], v[156:159], v[164:167], v[48:51]
	v_mfma_f32_16x16x32_bf16 v[36:39], v[140:143], v[172:175], v[36:39]
	v_mfma_f32_16x16x32_bf16 v[32:35], v[156:159], v[172:175], v[32:35]
	v_mfma_f32_16x16x32_bf16 v[20:23], v[140:143], v[180:183], v[20:23]
	v_mfma_f32_16x16x32_bf16 v[16:19], v[156:159], v[180:183], v[16:19]
	v_mfma_f32_16x16x32_bf16 v[4:7], v[140:143], v[188:191], v[4:7]
	v_mfma_f32_16x16x32_bf16 v[0:3], v[156:159], v[188:191], v[0:3]
	s_setprio 0
	s_barrier
	s_add_i32 s44, s65, 0x100
	s_add_i32 s45, s52, 0x100
	v_add_u32_e32 v128, s44, v249
	v_add_u32_e32 v156, s45, v249
	ds_read_b128 v[112:115], v128
	ds_read_b128 v[120:123], v128 offset:1024
	ds_read_b128 v[124:127], v128 offset:2048
	ds_read_b128 v[128:131], v128 offset:3072
	ds_read_b128 v[136:139], v156
	ds_read_b128 v[140:143], v156 offset:1024
	ds_read_b128 v[144:147], v156 offset:2048
	ds_read_b128 v[156:159], v156 offset:3072
	s_add_u32 s26, s26, 0x40000
	s_addc_u32 s27, s27, 0
	s_mov_b32 m0, s47
	v_lshl_add_u64 v[212:213], s[26:27], 0, v[202:203]
	ds_read_b128 v[160:163], v251 offset:32768
	ds_read_b128 v[164:167], v251 offset:33792
	ds_read_b128 v[168:171], v251 offset:34816
	ds_read_b128 v[172:175], v251 offset:35840
	ds_read_b128 v[176:179], v251 offset:36864
	ds_read_b128 v[180:183], v251 offset:37888
	ds_read_b128 v[184:187], v251 offset:38912
	ds_read_b128 v[188:191], v251 offset:39936
	global_load_lds_dwordx4 v[212:213], off
	v_lshl_add_u64 v[212:213], s[26:27], 0, v[200:201]
	s_mov_b32 m0, s60
	s_nop 0
	global_load_lds_dwordx4 v[212:213], off
	s_waitcnt vmcnt(8)
	s_waitcnt lgkmcnt(0)
	s_barrier
	s_setprio 1
	s_waitcnt lgkmcnt(0)
	v_mfma_f32_16x16x32_bf16 v[152:155], v[112:115], v[160:163], v[152:155]
	v_mfma_f32_16x16x32_bf16 v[148:151], v[124:127], v[160:163], v[148:151]
	v_mfma_f32_16x16x32_bf16 v[108:111], v[112:115], v[168:171], v[108:111]
	v_mfma_f32_16x16x32_bf16 v[104:107], v[124:127], v[168:171], v[104:107]
	v_mfma_f32_16x16x32_bf16 v[92:95], v[112:115], v[176:179], v[92:95]
	v_mfma_f32_16x16x32_bf16 v[88:91], v[124:127], v[176:179], v[88:91]
	v_mfma_f32_16x16x32_bf16 v[76:79], v[112:115], v[184:187], v[76:79]
	v_mfma_f32_16x16x32_bf16 v[72:75], v[124:127], v[184:187], v[72:75]
	v_mfma_f32_16x16x32_bf16 v[152:155], v[120:123], v[164:167], v[152:155]
	v_mfma_f32_16x16x32_bf16 v[148:151], v[128:131], v[164:167], v[148:151]
	v_mfma_f32_16x16x32_bf16 v[108:111], v[120:123], v[172:175], v[108:111]
	v_mfma_f32_16x16x32_bf16 v[104:107], v[128:131], v[172:175], v[104:107]
	v_mfma_f32_16x16x32_bf16 v[92:95], v[120:123], v[180:183], v[92:95]
	v_mfma_f32_16x16x32_bf16 v[88:91], v[128:131], v[180:183], v[88:91]
	v_mfma_f32_16x16x32_bf16 v[76:79], v[120:123], v[188:191], v[76:79]
	v_mfma_f32_16x16x32_bf16 v[72:75], v[128:131], v[188:191], v[72:75]
	s_setprio 0
	s_setprio 1
	v_mfma_f32_16x16x32_bf16 v[132:135], v[136:139], v[160:163], v[132:135]
	v_mfma_f32_16x16x32_bf16 v[116:119], v[144:147], v[160:163], v[116:119]
	v_mfma_f32_16x16x32_bf16 v[100:103], v[136:139], v[168:171], v[100:103]
	v_mfma_f32_16x16x32_bf16 v[96:99], v[144:147], v[168:171], v[96:99]
	v_mfma_f32_16x16x32_bf16 v[84:87], v[136:139], v[176:179], v[84:87]
	v_mfma_f32_16x16x32_bf16 v[80:83], v[144:147], v[176:179], v[80:83]
	v_mfma_f32_16x16x32_bf16 v[68:71], v[136:139], v[184:187], v[68:71]
	v_mfma_f32_16x16x32_bf16 v[64:67], v[144:147], v[184:187], v[64:67]
	v_mfma_f32_16x16x32_bf16 v[132:135], v[140:143], v[164:167], v[132:135]
	v_mfma_f32_16x16x32_bf16 v[116:119], v[156:159], v[164:167], v[116:119]
	v_mfma_f32_16x16x32_bf16 v[100:103], v[140:143], v[172:175], v[100:103]
	v_mfma_f32_16x16x32_bf16 v[96:99], v[156:159], v[172:175], v[96:99]
	v_mfma_f32_16x16x32_bf16 v[84:87], v[140:143], v[180:183], v[84:87]
	v_mfma_f32_16x16x32_bf16 v[80:83], v[156:159], v[180:183], v[80:83]
	v_mfma_f32_16x16x32_bf16 v[68:71], v[140:143], v[188:191], v[68:71]
	v_mfma_f32_16x16x32_bf16 v[64:67], v[156:159], v[188:191], v[64:67]
	s_setprio 0
	s_barrier
; #define PG8_STAGE(bufoff, gbase, voff) do { _Pragma("unroll") for (int _i = 0; _i < 2; ++_i) \
;         __builtin_amdgcn_global_load_lds((const unsigned*)((const char*)(gbase) + (voff)[_i]), (PG8_LAS unsigned*)(lds + (bufoff) + ldsw + _i * 8192), 16, 0, 0); } while (0)
; #define PG8_LDA(dst, b, h) do { _Pragma("unroll") for (int m = 0; m < 4; ++m) _Pragma("unroll") for (int k = 0; k < 2; ++k) dst[m][k] = *(const PG8_LAS bf16x8*)(lds + PG8_SA(b, h) + aoff + m * 2048 + k * 1024); } while (0)
; #define PG8_WAIT_V(n) asm volatile("s_waitcnt vmcnt(" #n ")" ::: "memory")
; #define PG8_WAIT_L(n) asm volatile("s_waitcnt lgkmcnt(" #n ")" ::: "memory")
; #define PG8_BAR __builtin_amdgcn_s_barrier()
; template <class Epi, class Sched, bool ALIGN_EPI = false, bool SP2 = false>
; __device__ __forceinline__ void gemm_phase(PG8_LAS unsigned char* lds, const Gemm g, const Sched& S, const Epi& E, int wave_in) {
;     ...
;         for (int t = 0; t < nt; t += 2) {
;             const bool last = (t == nt - 2);
;             const char* a1 = cA + (size_t)(t + 1) * kstep;
;             const char* a2 = last ? nA : cA + (size_t)(t + 2) * kstep; const char* b2 = last ? nB : cB + (size_t)(t + 2) * kstep;
;             const char* a3 = a2 + kstep; const char* b3 = b2 + kstep;
;             if (last && has_next) S.a_ready(nxt);
;             if constexpr (SP2) {
;             PG8_LDB(B0, 0, 0); PG8_LDB(B1, 0, 1); PG8_SCHED; PG8_LDA(At, 0, 0); PG8_STAGE(PG8_SA(1, 1), a1 + hstep, voffA);
;             PG8_WAIT_V(8); PG8_WAIT_L(0); PG8_BAR; PG8_MMA(0, 0, At, B0); PG8_MMA(0, 1, At, B1); PG8_BAR; PG8_SCHED;
;             PG8_LDA(At, 0, 1); PG8_STAGE(PG8_SB(0, 0), b2, voffB); PG8_STAGE(PG8_SB(0, 1), b2 + hstep, voffB); PG8_STAGE(PG8_SA(0, 0), a2, voffA);
;             PG8_WAIT_V(8); PG8_WAIT_L(0); PG8_BAR; PG8_MMA(1, 0, At, B0); PG8_MMA(1, 1, At, B1); PG8_BAR; PG8_SCHED;
;             PG8_LDB(B0, 1, 0); PG8_LDB(B1, 1, 1); PG8_SCHED; PG8_LDA(At, 1, 0); PG8_STAGE(PG8_SA(0, 1), a2 + hstep, voffA);
;             PG8_WAIT_V(8); PG8_WAIT_L(0); PG8_BAR; PG8_MMA(0, 0, At, B0); PG8_MMA(0, 1, At, B1); PG8_BAR; PG8_SCHED;
;             PG8_LDA(At, 1, 1); PG8_STAGE(PG8_SB(1, 0), b3, voffB); PG8_STAGE(PG8_SB(1, 1), b3 + hstep, voffB); PG8_STAGE(PG8_SA(1, 0), a3, voffA);
;             PG8_WAIT_V(8); PG8_WAIT_L(0); PG8_BAR; PG8_MMA(1, 0, At, B0); PG8_MMA(1, 1, At, B1); PG8_BAR; PG8_SCHED;
	s_add_i32 s26, s44, s38
	v_lshl_add_u64 v[194:195], v[194:195], 0, s[88:89]
	s_mov_b32 m0, s26
	ds_read_b128 v[160:163], v251 offset:49152
	ds_read_b128 v[164:167], v251 offset:50176
	ds_read_b128 v[168:171], v251 offset:51200
	ds_read_b128 v[172:175], v251 offset:52224
	ds_read_b128 v[176:179], v251 offset:53248
	ds_read_b128 v[180:183], v251 offset:54272
	ds_read_b128 v[184:187], v251 offset:55296
	ds_read_b128 v[188:191], v251 offset:56320
	global_load_lds_dwordx4 v[194:195], off
	s_add_i32 m0, s26, 0x2000
	s_add_u32 s24, s24, 0x40080
	v_lshl_add_u64 v[194:195], v[196:197], 0, s[88:89]
	s_addc_u32 s25, s25, 0
	s_add_i32 s26, s45, s38
	global_load_lds_dwordx4 v[194:195], off
	v_lshl_add_u64 v[194:195], s[24:25], 0, v[192:193]
	s_mov_b32 m0, s26
	s_nop 0
	global_load_lds_dwordx4 v[194:195], off
	v_lshl_add_u64 v[194:195], s[24:25], 0, v[198:199]
	s_add_i32 m0, s26, 0x2000
	s_nop 0
	global_load_lds_dwordx4 v[194:195], off
	v_lshl_add_u64 v[194:195], v[208:209], 0, s[88:89]
	s_mov_b32 m0, s62
	s_nop 0
	global_load_lds_dwordx4 v[194:195], off
	v_lshl_add_u64 v[194:195], v[210:211], 0, s[88:89]
	s_mov_b32 m0, s63
	s_nop 0
	global_load_lds_dwordx4 v[194:195], off
	s_waitcnt vmcnt(8)
	s_waitcnt lgkmcnt(0)
	s_barrier
	s_setprio 1
	s_waitcnt lgkmcnt(0)
	v_mfma_f32_16x16x32_bf16 v[60:63], v[112:115], v[160:163], v[60:63]
	v_mfma_f32_16x16x32_bf16 v[56:59], v[124:127], v[160:163], v[56:59]
	v_mfma_f32_16x16x32_bf16 v[44:47], v[112:115], v[168:171], v[44:47]
	v_mfma_f32_16x16x32_bf16 v[40:43], v[124:127], v[168:171], v[40:43]
	v_mfma_f32_16x16x32_bf16 v[28:31], v[112:115], v[176:179], v[28:31]
	v_mfma_f32_16x16x32_bf16 v[24:27], v[124:127], v[176:179], v[24:27]
	v_mfma_f32_16x16x32_bf16 v[12:15], v[112:115], v[184:187], v[12:15]
	v_mfma_f32_16x16x32_bf16 v[8:11], v[124:127], v[184:187], v[8:11]
	v_mfma_f32_16x16x32_bf16 v[60:63], v[120:123], v[164:167], v[60:63]
	v_mfma_f32_16x16x32_bf16 v[56:59], v[128:131], v[164:167], v[56:59]
	v_mfma_f32_16x16x32_bf16 v[44:47], v[120:123], v[172:175], v[44:47]
	v_mfma_f32_16x16x32_bf16 v[40:43], v[128:131], v[172:175], v[40:43]
	v_mfma_f32_16x16x32_bf16 v[28:31], v[120:123], v[180:183], v[28:31]
	v_mfma_f32_16x16x32_bf16 v[24:27], v[128:131], v[180:183], v[24:27]
	v_mfma_f32_16x16x32_bf16 v[12:15], v[120:123], v[188:191], v[12:15]
	v_mfma_f32_16x16x32_bf16 v[8:11], v[128:131], v[188:191], v[8:11]
	s_setprio 0
	s_setprio 1
	v_mfma_f32_16x16x32_bf16 v[52:55], v[136:139], v[160:163], v[52:55]
	v_mfma_f32_16x16x32_bf16 v[48:51], v[144:147], v[160:163], v[48:51]
	v_mfma_f32_16x16x32_bf16 v[36:39], v[136:139], v[168:171], v[36:39]
	v_mfma_f32_16x16x32_bf16 v[32:35], v[144:147], v[168:171], v[32:35]
	v_mfma_f32_16x16x32_bf16 v[20:23], v[136:139], v[176:179], v[20:23]
	v_mfma_f32_16x16x32_bf16 v[16:19], v[144:147], v[176:179], v[16:19]
	v_mfma_f32_16x16x32_bf16 v[4:7], v[136:139], v[184:187], v[4:7]
	v_mfma_f32_16x16x32_bf16 v[0:3], v[144:147], v[184:187], v[0:3]
	v_mfma_f32_16x16x32_bf16 v[52:55], v[140:143], v[164:167], v[52:55]
	v_mfma_f32_16x16x32_bf16 v[48:51], v[156:159], v[164:167], v[48:51]
	v_mfma_f32_16x16x32_bf16 v[36:39], v[140:143], v[172:175], v[36:39]
	v_mfma_f32_16x16x32_bf16 v[32:35], v[156:159], v[172:175], v[32:35]
	v_mfma_f32_16x16x32_bf16 v[20:23], v[140:143], v[180:183], v[20:23]
	v_mfma_f32_16x16x32_bf16 v[16:19], v[156:159], v[180:183], v[16:19]
	v_mfma_f32_16x16x32_bf16 v[4:7], v[140:143], v[188:191], v[4:7]
	v_mfma_f32_16x16x32_bf16 v[0:3], v[156:159], v[188:191], v[0:3]
	s_setprio 0
	s_add_i32 s34, s34, 2
	s_add_u32 s15, s15, 0x100
	s_addc_u32 s17, s17, 0
	s_add_u32 s22, s22, 0x100
	s_addc_u32 s23, s23, 0
	s_cmp_gt_u32 s34, 13
	s_cbranch_scc1 .Lxbar_5
	s_add_u32 s24, s22, 0xfffc0080
	s_addc_u32 s25, s23, -1
	s_add_i32 s44, s35, 0x100
	s_cmp_eq_u32 s34, 12
	s_cselect_b32 s27, s19, s25
	s_cselect_b32 s26, s18, s24
	s_cselect_b32 s25, s21, s17
	s_cselect_b32 s24, s20, s15
	s_add_i32 s53, s90, 0x100

; #define PG8_STAGE(bufoff, gbase, voff) do { _Pragma("unroll") for (int _i = 0; _i < 2; ++_i) \
;         __builtin_amdgcn_global_load_lds((const unsigned*)((const char*)(gbase) + (voff)[_i]), (PG8_LAS unsigned*)(lds + (bufoff) + ldsw + _i * 8192), 16, 0, 0); } while (0)
; #define PG8_LDA(dst, b, h) do { _Pragma("unroll") for (int m = 0; m < 4; ++m) _Pragma("unroll") for (int k = 0; k < 2; ++k) dst[m][k] = *(const PG8_LAS bf16x8*)(lds + PG8_SA(b, h) + aoff + m * 2048 + k * 1024); } while (0)
; #define PG8_LDB(dst, b, h) do { _Pragma("unroll") for (int n = 0; n < 2; ++n) _Pragma("unroll") for (int k = 0; k < 2; ++k) dst[n][k] = *(const PG8_LAS bf16x8*)(lds + PG8_SB(b, h) + boff + n * 2048 + k * 1024); } while (0)
; #define PG8_MMA(ai, bj, At, Bt) do { __builtin_amdgcn_s_setprio(1); _Pragma("unroll") for (int m = 0; m < 4; ++m) _Pragma("unroll") for (int n = 0; n < 2; ++n) _Pragma("unroll") for (int k = 0; k < 2; ++k) \
;         acc[ai][bj][m][n] = __builtin_amdgcn_mfma_f32_16x16x32_bf16(Bt[n][k], At[m][k], acc[ai][bj][m][n], 0, 0, 0); __builtin_amdgcn_s_setprio(0); } while (0)
; #define PG8_WAIT_V(n) asm volatile("s_waitcnt vmcnt(" #n ")" ::: "memory")
; #define PG8_WAIT_L(n) asm volatile("s_waitcnt lgkmcnt(" #n ")" ::: "memory")
; #define PG8_BAR __builtin_amdgcn_s_barrier()
; #define PG8_SCHED __builtin_amdgcn_sched_barrier(0)
; template <class Epi, class Sched, bool ALIGN_EPI = false, bool SP2 = false>
; __device__ __forceinline__ void gemm_phase(PG8_LAS unsigned char* lds, const Gemm g, const Sched& S, const Epi& E, int wave_in) {
;     ...
;             PG8_LDB(B0, 0, 0); PG8_LDB(B1, 0, 1); PG8_SCHED; PG8_LDA(At, 0, 0); PG8_STAGE(PG8_SA(1, 1), a1 + hstep, voffA);
;             PG8_WAIT_V(8); PG8_WAIT_L(0); PG8_BAR; PG8_MMA(0, 0, At, B0); PG8_MMA(0, 1, At, B1); PG8_BAR; PG8_SCHED;
;             PG8_LDA(At, 0, 1); PG8_STAGE(PG8_SB(0, 0), b2, voffB); PG8_STAGE(PG8_SB(0, 1), b2 + hstep, voffB); PG8_STAGE(PG8_SA(0, 0), a2, voffA);
;             PG8_WAIT_V(8); PG8_WAIT_L(0); PG8_BAR; PG8_MMA(1, 0, At, B0); PG8_MMA(1, 1, At, B1); PG8_BAR; PG8_SCHED;
.LBB0_804:
	v_add_u32_e32 v128, s44, v249
	v_add_u32_e32 v156, s53, v249
	ds_read_b128 v[112:115], v128
	ds_read_b128 v[120:123], v128 offset:1024
	ds_read_b128 v[124:127], v128 offset:2048
	ds_read_b128 v[128:131], v128 offset:3072
	ds_read_b128 v[136:139], v156
	ds_read_b128 v[140:143], v156 offset:1024
	ds_read_b128 v[144:147], v156 offset:2048
	ds_read_b128 v[156:159], v156 offset:3072
	v_lshl_add_u64 v[194:195], s[22:23], 0, v[206:207]
	s_add_i32 m0, s39, 0xc000
	ds_read_b128 v[160:163], v251
	ds_read_b128 v[164:167], v251 offset:1024
	ds_read_b128 v[168:171], v251 offset:2048
	ds_read_b128 v[172:175], v251 offset:3072
	ds_read_b128 v[176:179], v251 offset:4096
	ds_read_b128 v[180:183], v251 offset:5120
	ds_read_b128 v[184:187], v251 offset:6144
	ds_read_b128 v[188:191], v251 offset:7168
	global_load_lds_dwordx4 v[194:195], off
	v_lshl_add_u64 v[194:195], s[22:23], 0, v[204:205]
	s_add_i32 m0, s39, 0xe000
	s_nop 0
	global_load_lds_dwordx4 v[194:195], off
	s_waitcnt vmcnt(8)
	s_waitcnt lgkmcnt(0)
	s_barrier
	s_setprio 1
	s_waitcnt lgkmcnt(0)
	v_mfma_f32_16x16x32_bf16 v[152:155], v[112:115], v[160:163], v[152:155]
	v_mfma_f32_16x16x32_bf16 v[148:151], v[124:127], v[160:163], v[148:151]
	v_mfma_f32_16x16x32_bf16 v[108:111], v[112:115], v[168:171], v[108:111]
	v_mfma_f32_16x16x32_bf16 v[104:107], v[124:127], v[168:171], v[104:107]
	v_mfma_f32_16x16x32_bf16 v[92:95], v[112:115], v[176:179], v[92:95]
	v_mfma_f32_16x16x32_bf16 v[88:91], v[124:127], v[176:179], v[88:91]
	v_mfma_f32_16x16x32_bf16 v[76:79], v[112:115], v[184:187], v[76:79]
	v_mfma_f32_16x16x32_bf16 v[72:75], v[124:127], v[184:187], v[72:75]
	v_mfma_f32_16x16x32_bf16 v[152:155], v[120:123], v[164:167], v[152:155]
	v_mfma_f32_16x16x32_bf16 v[148:151], v[128:131], v[164:167], v[148:151]
	v_mfma_f32_16x16x32_bf16 v[108:111], v[120:123], v[172:175], v[108:111]
	v_mfma_f32_16x16x32_bf16 v[104:107], v[128:131], v[172:175], v[104:107]
	v_mfma_f32_16x16x32_bf16 v[92:95], v[120:123], v[180:183], v[92:95]
	v_mfma_f32_16x16x32_bf16 v[88:91], v[128:131], v[180:183], v[88:91]
	v_mfma_f32_16x16x32_bf16 v[76:79], v[120:123], v[188:191], v[76:79]
	v_mfma_f32_16x16x32_bf16 v[72:75], v[128:131], v[188:191], v[72:75]
	s_setprio 0
	s_setprio 1
	v_mfma_f32_16x16x32_bf16 v[132:135], v[136:139], v[160:163], v[132:135]
	v_mfma_f32_16x16x32_bf16 v[116:119], v[144:147], v[160:163], v[116:119]
	v_mfma_f32_16x16x32_bf16 v[100:103], v[136:139], v[168:171], v[100:103]
	v_mfma_f32_16x16x32_bf16 v[96:99], v[144:147], v[168:171], v[96:99]
	v_mfma_f32_16x16x32_bf16 v[84:87], v[136:139], v[176:179], v[84:87]
	v_mfma_f32_16x16x32_bf16 v[80:83], v[144:147], v[176:179], v[80:83]
	v_mfma_f32_16x16x32_bf16 v[68:71], v[136:139], v[184:187], v[68:71]
	v_mfma_f32_16x16x32_bf16 v[64:67], v[144:147], v[184:187], v[64:67]
	v_mfma_f32_16x16x32_bf16 v[132:135], v[140:143], v[164:167], v[132:135]
	v_mfma_f32_16x16x32_bf16 v[116:119], v[156:159], v[164:167], v[116:119]
	v_mfma_f32_16x16x32_bf16 v[100:103], v[140:143], v[172:175], v[100:103]
	v_mfma_f32_16x16x32_bf16 v[96:99], v[156:159], v[172:175], v[96:99]
	v_mfma_f32_16x16x32_bf16 v[84:87], v[140:143], v[180:183], v[84:87]
	v_mfma_f32_16x16x32_bf16 v[80:83], v[156:159], v[180:183], v[80:83]
	v_mfma_f32_16x16x32_bf16 v[68:71], v[140:143], v[188:191], v[68:71]
	v_mfma_f32_16x16x32_bf16 v[64:67], v[156:159], v[188:191], v[64:67]
	s_setprio 0
	s_barrier
	s_add_i32 s44, s44, s38
	v_lshl_add_u64 v[194:195], s[24:25], 0, v[192:193]
	s_mov_b32 m0, s44
	ds_read_b128 v[160:163], v251 offset:16384
	ds_read_b128 v[164:167], v251 offset:17408
	ds_read_b128 v[168:171], v251 offset:18432
	ds_read_b128 v[172:175], v251 offset:19456
	ds_read_b128 v[176:179], v251 offset:20480
	ds_read_b128 v[180:183], v251 offset:21504
	ds_read_b128 v[184:187], v251 offset:22528
	ds_read_b128 v[188:191], v251 offset:23552
	global_load_lds_dwordx4 v[194:195], off
	s_add_i32 m0, s44, 0x2000
	s_add_u32 s44, s24, 0x40000
	v_lshl_add_u64 v[196:197], s[24:25], 0, v[198:199]
	s_addc_u32 s45, s25, 0
	s_add_i32 s53, s53, s38
	global_load_lds_dwordx4 v[196:197], off
	v_lshl_add_u64 v[208:209], s[44:45], 0, v[192:193]
	s_mov_b32 m0, s53
	v_lshl_add_u64 v[210:211], s[26:27], 0, v[200:201]
	global_load_lds_dwordx4 v[208:209], off
	v_lshl_add_u64 v[208:209], s[44:45], 0, v[198:199]
	s_add_i32 m0, s53, 0x2000
	s_nop 0
	global_load_lds_dwordx4 v[208:209], off
	v_lshl_add_u64 v[208:209], s[26:27], 0, v[202:203]
	s_mov_b32 m0, s39
	s_nop 0
	global_load_lds_dwordx4 v[208:209], off
	s_mov_b32 m0, s46
	s_nop 0
	global_load_lds_dwordx4 v[210:211], off
	s_waitcnt vmcnt(8)
	s_waitcnt lgkmcnt(0)
	s_barrier
; #define PG8_STAGE(bufoff, gbase, voff) do { _Pragma("unroll") for (int _i = 0; _i < 2; ++_i) \
;         __builtin_amdgcn_global_load_lds((const unsigned*)((const char*)(gbase) + (voff)[_i]), (PG8_LAS unsigned*)(lds + (bufoff) + ldsw + _i * 8192), 16, 0, 0); } while (0)
; #define PG8_LDA(dst, b, h) do { _Pragma("unroll") for (int m = 0; m < 4; ++m) _Pragma("unroll") for (int k = 0; k < 2; ++k) dst[m][k] = *(const PG8_LAS bf16x8*)(lds + PG8_SA(b, h) + aoff + m * 2048 + k * 1024); } while (0)
; #define PG8_LDB(dst, b, h) do { _Pragma("unroll") for (int n = 0; n < 2; ++n) _Pragma("unroll") for (int k = 0; k < 2; ++k) dst[n][k] = *(const PG8_LAS bf16x8*)(lds + PG8_SB(b, h) + boff + n * 2048 + k * 1024); } while (0)
; #define PG8_MMA(ai, bj, At, Bt) do { __builtin_amdgcn_s_setprio(1); _Pragma("unroll") for (int m = 0; m < 4; ++m) _Pragma("unroll") for (int n = 0; n < 2; ++n) _Pragma("unroll") for (int k = 0; k < 2; ++k) \
;         acc[ai][bj][m][n] = __builtin_amdgcn_mfma_f32_16x16x32_bf16(Bt[n][k], At[m][k], acc[ai][bj][m][n], 0, 0, 0); __builtin_amdgcn_s_setprio(0); } while (0)
; #define PG8_WAIT_V(n) asm volatile("s_waitcnt vmcnt(" #n ")" ::: "memory")
; #define PG8_WAIT_L(n) asm volatile("s_waitcnt lgkmcnt(" #n ")" ::: "memory")
; #define PG8_BAR __builtin_amdgcn_s_barrier()
; #define PG8_SCHED __builtin_amdgcn_sched_barrier(0)
; template <class Epi, class Sched, bool ALIGN_EPI = false, bool SP2 = false>
; __device__ __forceinline__ void gemm_phase(PG8_LAS unsigned char* lds, const Gemm g, const Sched& S, const Epi& E, int wave_in) {
;     ...
;             PG8_WAIT_V(8); PG8_WAIT_L(0); PG8_BAR; PG8_MMA(1, 0, At, B0); PG8_MMA(1, 1, At, B1); PG8_BAR; PG8_SCHED;
;             PG8_LDB(B0, 1, 0); PG8_LDB(B1, 1, 1); PG8_SCHED; PG8_LDA(At, 1, 0); PG8_STAGE(PG8_SA(0, 1), a2 + hstep, voffA);
;             PG8_WAIT_V(8); PG8_WAIT_L(0); PG8_BAR; PG8_MMA(0, 0, At, B0); PG8_MMA(0, 1, At, B1); PG8_BAR; PG8_SCHED;
	s_setprio 1
	s_waitcnt lgkmcnt(0)
	v_mfma_f32_16x16x32_bf16 v[60:63], v[112:115], v[160:163], v[60:63]
	v_mfma_f32_16x16x32_bf16 v[56:59], v[124:127], v[160:163], v[56:59]
	v_mfma_f32_16x16x32_bf16 v[44:47], v[112:115], v[168:171], v[44:47]
	v_mfma_f32_16x16x32_bf16 v[40:43], v[124:127], v[168:171], v[40:43]
	v_mfma_f32_16x16x32_bf16 v[28:31], v[112:115], v[176:179], v[28:31]
	v_mfma_f32_16x16x32_bf16 v[24:27], v[124:127], v[176:179], v[24:27]
	v_mfma_f32_16x16x32_bf16 v[12:15], v[112:115], v[184:187], v[12:15]
	v_mfma_f32_16x16x32_bf16 v[8:11], v[124:127], v[184:187], v[8:11]
	v_mfma_f32_16x16x32_bf16 v[60:63], v[120:123], v[164:167], v[60:63]
	v_mfma_f32_16x16x32_bf16 v[56:59], v[128:131], v[164:167], v[56:59]
	v_mfma_f32_16x16x32_bf16 v[44:47], v[120:123], v[172:175], v[44:47]
	v_mfma_f32_16x16x32_bf16 v[40:43], v[128:131], v[172:175], v[40:43]
	v_mfma_f32_16x16x32_bf16 v[28:31], v[120:123], v[180:183], v[28:31]
	v_mfma_f32_16x16x32_bf16 v[24:27], v[128:131], v[180:183], v[24:27]
	v_mfma_f32_16x16x32_bf16 v[12:15], v[120:123], v[188:191], v[12:15]
	v_mfma_f32_16x16x32_bf16 v[8:11], v[128:131], v[188:191], v[8:11]
	s_setprio 0
	s_setprio 1
	v_mfma_f32_16x16x32_bf16 v[52:55], v[136:139], v[160:163], v[52:55]
	v_mfma_f32_16x16x32_bf16 v[48:51], v[144:147], v[160:163], v[48:51]
	v_mfma_f32_16x16x32_bf16 v[36:39], v[136:139], v[168:171], v[36:39]
	v_mfma_f32_16x16x32_bf16 v[32:35], v[144:147], v[168:171], v[32:35]
	v_mfma_f32_16x16x32_bf16 v[20:23], v[136:139], v[176:179], v[20:23]
	v_mfma_f32_16x16x32_bf16 v[16:19], v[144:147], v[176:179], v[16:19]
	v_mfma_f32_16x16x32_bf16 v[4:7], v[136:139], v[184:187], v[4:7]
	v_mfma_f32_16x16x32_bf16 v[0:3], v[144:147], v[184:187], v[0:3]
	v_mfma_f32_16x16x32_bf16 v[52:55], v[140:143], v[164:167], v[52:55]
	v_mfma_f32_16x16x32_bf16 v[48:51], v[156:159], v[164:167], v[48:51]
	v_mfma_f32_16x16x32_bf16 v[36:39], v[140:143], v[172:175], v[36:39]
	v_mfma_f32_16x16x32_bf16 v[32:35], v[156:159], v[172:175], v[32:35]
	v_mfma_f32_16x16x32_bf16 v[20:23], v[140:143], v[180:183], v[20:23]
	v_mfma_f32_16x16x32_bf16 v[16:19], v[156:159], v[180:183], v[16:19]
	v_mfma_f32_16x16x32_bf16 v[4:7], v[140:143], v[188:191], v[4:7]
	v_mfma_f32_16x16x32_bf16 v[0:3], v[156:159], v[188:191], v[0:3]
	s_setprio 0
	s_barrier
	s_add_i32 s44, s65, 0x100
	s_add_i32 s45, s52, 0x100
	v_add_u32_e32 v128, s44, v249
	v_add_u32_e32 v156, s45, v249
	ds_read_b128 v[112:115], v128
	ds_read_b128 v[120:123], v128 offset:1024
	ds_read_b128 v[124:127], v128 offset:2048
	ds_read_b128 v[128:131], v128 offset:3072
	ds_read_b128 v[136:139], v156
	ds_read_b128 v[140:143], v156 offset:1024
	ds_read_b128 v[144:147], v156 offset:2048
	ds_read_b128 v[156:159], v156 offset:3072
	s_add_u32 s26, s26, 0x40000
	s_addc_u32 s27, s27, 0
	s_mov_b32 m0, s47
	v_lshl_add_u64 v[212:213], s[26:27], 0, v[202:203]
	ds_read_b128 v[160:163], v251 offset:32768
	ds_read_b128 v[164:167], v251 offset:33792
	ds_read_b128 v[168:171], v251 offset:34816
	ds_read_b128 v[172:175], v251 offset:35840
	ds_read_b128 v[176:179], v251 offset:36864
	ds_read_b128 v[180:183], v251 offset:37888
	ds_read_b128 v[184:187], v251 offset:38912
	ds_read_b128 v[188:191], v251 offset:39936
	global_load_lds_dwordx4 v[212:213], off
	v_lshl_add_u64 v[212:213], s[26:27], 0, v[200:201]
	s_mov_b32 m0, s60
	s_nop 0
	global_load_lds_dwordx4 v[212:213], off
	s_waitcnt vmcnt(8)
	s_waitcnt lgkmcnt(0)
	s_barrier
	s_setprio 1
	s_waitcnt lgkmcnt(0)
	v_mfma_f32_16x16x32_bf16 v[152:155], v[112:115], v[160:163], v[152:155]
	v_mfma_f32_16x16x32_bf16 v[148:151], v[124:127], v[160:163], v[148:151]
	v_mfma_f32_16x16x32_bf16 v[108:111], v[112:115], v[168:171], v[108:111]
	v_mfma_f32_16x16x32_bf16 v[104:107], v[124:127], v[168:171], v[104:107]
	v_mfma_f32_16x16x32_bf16 v[92:95], v[112:115], v[176:179], v[92:95]
	v_mfma_f32_16x16x32_bf16 v[88:91], v[124:127], v[176:179], v[88:91]
	v_mfma_f32_16x16x32_bf16 v[76:79], v[112:115], v[184:187], v[76:79]
	v_mfma_f32_16x16x32_bf16 v[72:75], v[124:127], v[184:187], v[72:75]
	v_mfma_f32_16x16x32_bf16 v[152:155], v[120:123], v[164:167], v[152:155]
	v_mfma_f32_16x16x32_bf16 v[148:151], v[128:131], v[164:167], v[148:151]
	v_mfma_f32_16x16x32_bf16 v[108:111], v[120:123], v[172:175], v[108:111]
	v_mfma_f32_16x16x32_bf16 v[104:107], v[128:131], v[172:175], v[104:107]
	v_mfma_f32_16x16x32_bf16 v[92:95], v[120:123], v[180:183], v[92:95]
	v_mfma_f32_16x16x32_bf16 v[88:91], v[128:131], v[180:183], v[88:91]
	v_mfma_f32_16x16x32_bf16 v[76:79], v[120:123], v[188:191], v[76:79]
	v_mfma_f32_16x16x32_bf16 v[72:75], v[128:131], v[188:191], v[72:75]
	s_setprio 0
	s_setprio 1
	v_mfma_f32_16x16x32_bf16 v[132:135], v[136:139], v[160:163], v[132:135]
	v_mfma_f32_16x16x32_bf16 v[116:119], v[144:147], v[160:163], v[116:119]
	v_mfma_f32_16x16x32_bf16 v[100:103], v[136:139], v[168:171], v[100:103]
	v_mfma_f32_16x16x32_bf16 v[96:99], v[144:147], v[168:171], v[96:99]
	v_mfma_f32_16x16x32_bf16 v[84:87], v[136:139], v[176:179], v[84:87]
	v_mfma_f32_16x16x32_bf16 v[80:83], v[144:147], v[176:179], v[80:83]
	v_mfma_f32_16x16x32_bf16 v[68:71], v[136:139], v[184:187], v[68:71]
	v_mfma_f32_16x16x32_bf16 v[64:67], v[144:147], v[184:187], v[64:67]
	v_mfma_f32_16x16x32_bf16 v[132:135], v[140:143], v[164:167], v[132:135]
	v_mfma_f32_16x16x32_bf16 v[116:119], v[156:159], v[164:167], v[116:119]
	v_mfma_f32_16x16x32_bf16 v[100:103], v[140:143], v[172:175], v[100:103]
	v_mfma_f32_16x16x32_bf16 v[96:99], v[156:159], v[172:175], v[96:99]
	v_mfma_f32_16x16x32_bf16 v[84:87], v[140:143], v[180:183], v[84:87]
	v_mfma_f32_16x16x32_bf16 v[80:83], v[156:159], v[180:183], v[80:83]
	v_mfma_f32_16x16x32_bf16 v[68:71], v[140:143], v[188:191], v[68:71]
	v_mfma_f32_16x16x32_bf16 v[64:67], v[156:159], v[188:191], v[64:67]
	s_setprio 0
	s_barrier
; #define PG8_STAGE(bufoff, gbase, voff) do { _Pragma("unroll") for (int _i = 0; _i < 2; ++_i) \
;         __builtin_amdgcn_global_load_lds((const unsigned*)((const char*)(gbase) + (voff)[_i]), (PG8_LAS unsigned*)(lds + (bufoff) + ldsw + _i * 8192), 16, 0, 0); } while (0)
; #define PG8_LDA(dst, b, h) do { _Pragma("unroll") for (int m = 0; m < 4; ++m) _Pragma("unroll") for (int k = 0; k < 2; ++k) dst[m][k] = *(const PG8_LAS bf16x8*)(lds + PG8_SA(b, h) + aoff + m * 2048 + k * 1024); } while (0)
; #define PG8_WAIT_V(n) asm volatile("s_waitcnt vmcnt(" #n ")" ::: "memory")
; #define PG8_WAIT_L(n) asm volatile("s_waitcnt lgkmcnt(" #n ")" ::: "memory")
; #define PG8_BAR __builtin_amdgcn_s_barrier()
; template <class Epi, class Sched, bool ALIGN_EPI = false, bool SP2 = false>
; __device__ __forceinline__ void gemm_phase(PG8_LAS unsigned char* lds, const Gemm g, const Sched& S, const Epi& E, int wave_in) {
;     ...
;         for (int t = 0; t < nt; t += 2) {
;             const bool last = (t == nt - 2);
;             const char* a1 = cA + (size_t)(t + 1) * kstep;
;             const char* a2 = last ? nA : cA + (size_t)(t + 2) * kstep; const char* b2 = last ? nB : cB + (size_t)(t + 2) * kstep;
;             const char* a3 = a2 + kstep; const char* b3 = b2 + kstep;
;             if (last && has_next) S.a_ready(nxt);
;             if constexpr (SP2) {
;             PG8_LDB(B0, 0, 0); PG8_LDB(B1, 0, 1); PG8_SCHED; PG8_LDA(At, 0, 0); PG8_STAGE(PG8_SA(1, 1), a1 + hstep, voffA);
;             PG8_WAIT_V(8); PG8_WAIT_L(0); PG8_BAR; PG8_MMA(0, 0, At, B0); PG8_MMA(0, 1, At, B1); PG8_BAR; PG8_SCHED;
;             PG8_LDA(At, 0, 1); PG8_STAGE(PG8_SB(0, 0), b2, voffB); PG8_STAGE(PG8_SB(0, 1), b2 + hstep, voffB); PG8_STAGE(PG8_SA(0, 0), a2, voffA);
;             PG8_WAIT_V(8); PG8_WAIT_L(0); PG8_BAR; PG8_MMA(1, 0, At, B0); PG8_MMA(1, 1, At, B1); PG8_BAR; PG8_SCHED;
;             PG8_LDB(B0, 1, 0); PG8_LDB(B1, 1, 1); PG8_SCHED; PG8_LDA(At, 1, 0); PG8_STAGE(PG8_SA(0, 1), a2 + hstep, voffA);
;             PG8_WAIT_V(8); PG8_WAIT_L(0); PG8_BAR; PG8_MMA(0, 0, At, B0); PG8_MMA(0, 1, At, B1); PG8_BAR; PG8_SCHED;
;             PG8_LDA(At, 1, 1); PG8_STAGE(PG8_SB(1, 0), b3, voffB); PG8_STAGE(PG8_SB(1, 1), b3 + hstep, voffB); PG8_STAGE(PG8_SA(1, 0), a3, voffA);
;             PG8_WAIT_V(8); PG8_WAIT_L(0); PG8_BAR; PG8_MMA(1, 0, At, B0); PG8_MMA(1, 1, At, B1); PG8_BAR; PG8_SCHED;
	s_add_i32 s26, s44, s38
	v_lshl_add_u64 v[194:195], v[194:195], 0, s[88:89]
	s_mov_b32 m0, s26
	ds_read_b128 v[160:163], v251 offset:49152
	ds_read_b128 v[164:167], v251 offset:50176
	ds_read_b128 v[168:171], v251 offset:51200
	ds_read_b128 v[172:175], v251 offset:52224
	ds_read_b128 v[176:179], v251 offset:53248
	ds_read_b128 v[180:183], v251 offset:54272
	ds_read_b128 v[184:187], v251 offset:55296
	ds_read_b128 v[188:191], v251 offset:56320
	global_load_lds_dwordx4 v[194:195], off
	s_add_i32 m0, s26, 0x2000
	s_add_u32 s24, s24, 0x40080
	v_lshl_add_u64 v[194:195], v[196:197], 0, s[88:89]
	s_addc_u32 s25, s25, 0
	s_add_i32 s26, s45, s38
	global_load_lds_dwordx4 v[194:195], off
	v_lshl_add_u64 v[194:195], s[24:25], 0, v[192:193]
	s_mov_b32 m0, s26
	s_nop 0
	global_load_lds_dwordx4 v[194:195], off
	v_lshl_add_u64 v[194:195], s[24:25], 0, v[198:199]
	s_add_i32 m0, s26, 0x2000
	s_nop 0
	global_load_lds_dwordx4 v[194:195], off
	v_lshl_add_u64 v[194:195], v[208:209], 0, s[88:89]
	s_mov_b32 m0, s62
	s_nop 0
	global_load_lds_dwordx4 v[194:195], off
	v_lshl_add_u64 v[194:195], v[210:211], 0, s[88:89]
	s_mov_b32 m0, s63
	s_nop 0
	global_load_lds_dwordx4 v[194:195], off
	s_waitcnt vmcnt(8)
	s_waitcnt lgkmcnt(0)
	s_barrier
	s_setprio 1
	s_waitcnt lgkmcnt(0)
	v_mfma_f32_16x16x32_bf16 v[60:63], v[112:115], v[160:163], v[60:63]
	v_mfma_f32_16x16x32_bf16 v[56:59], v[124:127], v[160:163], v[56:59]
	v_mfma_f32_16x16x32_bf16 v[44:47], v[112:115], v[168:171], v[44:47]
	v_mfma_f32_16x16x32_bf16 v[40:43], v[124:127], v[168:171], v[40:43]
	v_mfma_f32_16x16x32_bf16 v[28:31], v[112:115], v[176:179], v[28:31]
	v_mfma_f32_16x16x32_bf16 v[24:27], v[124:127], v[176:179], v[24:27]
	v_mfma_f32_16x16x32_bf16 v[12:15], v[112:115], v[184:187], v[12:15]
	v_mfma_f32_16x16x32_bf16 v[8:11], v[124:127], v[184:187], v[8:11]
	v_mfma_f32_16x16x32_bf16 v[60:63], v[120:123], v[164:167], v[60:63]
	v_mfma_f32_16x16x32_bf16 v[56:59], v[128:131], v[164:167], v[56:59]
	v_mfma_f32_16x16x32_bf16 v[44:47], v[120:123], v[172:175], v[44:47]
	v_mfma_f32_16x16x32_bf16 v[40:43], v[128:131], v[172:175], v[40:43]
	v_mfma_f32_16x16x32_bf16 v[28:31], v[120:123], v[180:183], v[28:31]
	v_mfma_f32_16x16x32_bf16 v[24:27], v[128:131], v[180:183], v[24:27]
	v_mfma_f32_16x16x32_bf16 v[12:15], v[120:123], v[188:191], v[12:15]
	v_mfma_f32_16x16x32_bf16 v[8:11], v[128:131], v[188:191], v[8:11]
	s_setprio 0
	s_setprio 1
	v_mfma_f32_16x16x32_bf16 v[52:55], v[136:139], v[160:163], v[52:55]
	v_mfma_f32_16x16x32_bf16 v[48:51], v[144:147], v[160:163], v[48:51]
	v_mfma_f32_16x16x32_bf16 v[36:39], v[136:139], v[168:171], v[36:39]
	v_mfma_f32_16x16x32_bf16 v[32:35], v[144:147], v[168:171], v[32:35]
	v_mfma_f32_16x16x32_bf16 v[20:23], v[136:139], v[176:179], v[20:23]
	v_mfma_f32_16x16x32_bf16 v[16:19], v[144:147], v[176:179], v[16:19]
	v_mfma_f32_16x16x32_bf16 v[4:7], v[136:139], v[184:187], v[4:7]
	v_mfma_f32_16x16x32_bf16 v[0:3], v[144:147], v[184:187], v[0:3]
	v_mfma_f32_16x16x32_bf16 v[52:55], v[140:143], v[164:167], v[52:55]
	v_mfma_f32_16x16x32_bf16 v[48:51], v[156:159], v[164:167], v[48:51]
	v_mfma_f32_16x16x32_bf16 v[36:39], v[140:143], v[172:175], v[36:39]
	v_mfma_f32_16x16x32_bf16 v[32:35], v[156:159], v[172:175], v[32:35]
	v_mfma_f32_16x16x32_bf16 v[20:23], v[140:143], v[180:183], v[20:23]
	v_mfma_f32_16x16x32_bf16 v[16:19], v[156:159], v[180:183], v[16:19]
	v_mfma_f32_16x16x32_bf16 v[4:7], v[140:143], v[188:191], v[4:7]
	v_mfma_f32_16x16x32_bf16 v[0:3], v[156:159], v[188:191], v[0:3]
	s_setprio 0
	s_add_i32 s34, s34, 2
	s_add_u32 s15, s15, 0x100
	s_addc_u32 s17, s17, 0
	s_add_u32 s22, s22, 0x100
	s_addc_u32 s23, s23, 0
	s_cmp_gt_u32 s34, 13
	s_cbranch_scc1 .Lxbar_5
	s_add_u32 s24, s22, 0xfffc0080
	s_addc_u32 s25, s23, -1
	s_add_i32 s44, s35, 0x100
	s_cmp_eq_u32 s34, 12
	s_cselect_b32 s27, s19, s25
	s_cselect_b32 s26, s18, s24
	s_cselect_b32 s25, s21, s17
	s_cselect_b32 s24, s20, s15
	s_add_i32 s53, s90, 0x100
	s_branch .Lhbar_5

; #define PG8_STAGE(bufoff, gbase, voff) do { _Pragma("unroll") for (int _i = 0; _i < 2; ++_i) \
;         __builtin_amdgcn_global_load_lds((const unsigned*)((const char*)(gbase) + (voff)[_i]), (PG8_LAS unsigned*)(lds + (bufoff) + ldsw + _i * 8192), 16, 0, 0); } while (0)
; #define PG8_LDA(dst, b, h) do { _Pragma("unroll") for (int m = 0; m < 4; ++m) _Pragma("unroll") for (int k = 0; k < 2; ++k) dst[m][k] = *(const PG8_LAS bf16x8*)(lds + PG8_SA(b, h) + aoff + m * 2048 + k * 1024); } while (0)
; #define PG8_LDB(dst, b, h) do { _Pragma("unroll") for (int n = 0; n < 2; ++n) _Pragma("unroll") for (int k = 0; k < 2; ++k) dst[n][k] = *(const PG8_LAS bf16x8*)(lds + PG8_SB(b, h) + boff + n * 2048 + k * 1024); } while (0)
; #define PG8_WAIT_V(n) asm volatile("s_waitcnt vmcnt(" #n ")" ::: "memory")
; #define PG8_WAIT_L(n) asm volatile("s_waitcnt lgkmcnt(" #n ")" ::: "memory")
; #define PG8_BAR __builtin_amdgcn_s_barrier()
; #define PG8_SCHED __builtin_amdgcn_sched_barrier(0)
; template <class Epi, class Sched, bool ALIGN_EPI = false, bool SP2 = false>
; __device__ __forceinline__ void gemm_phase(PG8_LAS unsigned char* lds, const Gemm g, const Sched& S, const Epi& E, int wave_in) {
;     ...
;         const bool has_next = S.next(ui + 1, nxt);
;         const char* nA = has_next ? (const char*)g.A + (size_t)(nxt.pm >> g.ash) * g.astride + (size_t)nxt.pm * tstep : cA; const char* nB = has_next ? (const char*)g.Bt + (size_t)(nxt.pm >> g.bsh) * g.bstride + (size_t)nxt.pn * tstep : cB;
;         for (int t = 0; t < nt; t += 2) {
;             const bool last = (t == nt - 2);
;             const char* a1 = cA + (size_t)(t + 1) * kstep;
;             const char* a2 = last ? nA : cA + (size_t)(t + 2) * kstep; const char* b2 = last ? nB : cB + (size_t)(t + 2) * kstep;
;             const char* a3 = a2 + kstep; const char* b3 = b2 + kstep;
;             if (last && has_next) S.a_ready(nxt);
;             if constexpr (SP2) {
;             PG8_LDB(B0, 0, 0); PG8_LDB(B1, 0, 1); PG8_SCHED; PG8_LDA(At, 0, 0); PG8_STAGE(PG8_SA(1, 1), a1 + hstep, voffA);
;             PG8_WAIT_V(8); PG8_WAIT_L(0); PG8_BAR; PG8_MMA(0, 0, At, B0); PG8_MMA(0, 1, At, B1); PG8_BAR; PG8_SCHED;
;             PG8_LDA(At, 0, 1); PG8_STAGE(PG8_SB(0, 0), b2, voffB); PG8_STAGE(PG8_SB(0, 1), b2 + hstep, voffB); PG8_STAGE(PG8_SA(0, 0), a2, voffA);
.LBB0_896:
	s_ashr_i32 s11, s10, 31
	s_lshl_b64 s[18:19], s[10:11], 19
	s_add_u32 s66, s6, s18
	s_addc_u32 s67, s72, s19
	s_and_b64 s[18:19], s[46:47], exec
	s_cselect_b32 s11, s67, s1
	s_cselect_b32 s34, s66, s0
	s_ashr_i32 s5, s4, 31
	s_lshl_b64 s[18:19], s[4:5], 19
	s_add_u32 s38, s73, s18
	s_addc_u32 s39, s74, s19
	s_and_b64 s[18:19], s[46:47], exec
	s_cselect_b32 s5, s39, s79
	s_cselect_b32 s53, s38, s78
	s_add_u32 s81, s78, 0x100
	s_addc_u32 s18, s79, 0
	s_add_u32 vcc_lo, s0, 0x40080
	s_addc_u32 vcc_hi, s1, 0
	s_mov_b32 s19, -2
	s_add_u32 s0, vcc_lo, 0xfffc0080
	s_addc_u32 s1, vcc_hi, -1
	s_add_i32 s76, s35, 0x100
	s_cmp_eq_u32 s19, 12
	s_cselect_b32 s79, s11, s1
	s_cselect_b32 s78, s34, s0
	s_cselect_b32 s1, s5, s18
	s_cselect_b32 s0, s53, s81
	s_add_i32 s29, s90, 0x100
	v_add_u32_e32 v140, s76, v207
	v_add_u32_e32 v156, s29, v207
	ds_read_b128 v[128:131], v140
	ds_read_b128 v[132:135], v140 offset:1024
	ds_read_b128 v[136:139], v140 offset:2048
	ds_read_b128 v[140:143], v140 offset:3072
	ds_read_b128 v[144:147], v156
	ds_read_b128 v[148:151], v156 offset:1024
	ds_read_b128 v[152:155], v156 offset:2048
	ds_read_b128 v[156:159], v156 offset:3072
	v_lshl_add_u64 v[190:191], vcc, 0, v[176:177]
	s_add_i32 m0, s33, 0xc000
	ds_read_b128 v[160:163], v219
	ds_read_b128 v[164:167], v219 offset:1024
	ds_read_b128 v[178:181], v219 offset:2048
	ds_read_b128 v[182:185], v219 offset:3072
	ds_read_b128 v[186:189], v219 offset:4096
	ds_read_b128 v[198:201], v219 offset:5120
	ds_read_b128 v[202:205], v219 offset:6144
	ds_read_b128 v[220:223], v219 offset:7168
	global_load_lds_dwordx4 v[190:191], off
	v_lshl_add_u64 v[190:191], vcc, 0, v[174:175]
	s_add_i32 m0, s33, 0xe000
	s_nop 0
	global_load_lds_dwordx4 v[190:191], off
	s_waitcnt vmcnt(8)
	s_waitcnt lgkmcnt(0)
	s_barrier
	s_setprio 1
	s_waitcnt lgkmcnt(0)
	v_mfma_f32_16x16x32_bf16 v[124:127], v[128:131], v[160:163], 0
	v_mfma_f32_16x16x32_bf16 v[60:63], v[136:139], v[160:163], 0
	v_mfma_f32_16x16x32_bf16 v[116:119], v[128:131], v[178:181], 0
	v_mfma_f32_16x16x32_bf16 v[52:55], v[136:139], v[178:181], 0
	v_mfma_f32_16x16x32_bf16 v[108:111], v[128:131], v[186:189], 0
	v_mfma_f32_16x16x32_bf16 v[44:47], v[136:139], v[186:189], 0
	v_mfma_f32_16x16x32_bf16 v[100:103], v[128:131], v[202:205], 0
	v_mfma_f32_16x16x32_bf16 v[36:39], v[136:139], v[202:205], 0
	v_mfma_f32_16x16x32_bf16 v[124:127], v[132:135], v[164:167], v[124:127]
	v_mfma_f32_16x16x32_bf16 v[60:63], v[140:143], v[164:167], v[60:63]
	v_mfma_f32_16x16x32_bf16 v[116:119], v[132:135], v[182:185], v[116:119]
	v_mfma_f32_16x16x32_bf16 v[52:55], v[140:143], v[182:185], v[52:55]
	v_mfma_f32_16x16x32_bf16 v[108:111], v[132:135], v[198:201], v[108:111]
	v_mfma_f32_16x16x32_bf16 v[44:47], v[140:143], v[198:201], v[44:47]
	v_mfma_f32_16x16x32_bf16 v[100:103], v[132:135], v[220:223], v[100:103]
	v_mfma_f32_16x16x32_bf16 v[36:39], v[140:143], v[220:223], v[36:39]
	s_setprio 0
	s_setprio 1
	v_mfma_f32_16x16x32_bf16 v[120:123], v[144:147], v[160:163], 0
	v_mfma_f32_16x16x32_bf16 v[56:59], v[152:155], v[160:163], 0
	v_mfma_f32_16x16x32_bf16 v[112:115], v[144:147], v[178:181], 0
	v_mfma_f32_16x16x32_bf16 v[48:51], v[152:155], v[178:181], 0
	v_mfma_f32_16x16x32_bf16 v[104:107], v[144:147], v[186:189], 0
	v_mfma_f32_16x16x32_bf16 v[40:43], v[152:155], v[186:189], 0
	v_mfma_f32_16x16x32_bf16 v[96:99], v[144:147], v[202:205], 0
	v_mfma_f32_16x16x32_bf16 v[32:35], v[152:155], v[202:205], 0
	v_mfma_f32_16x16x32_bf16 v[120:123], v[148:151], v[164:167], v[120:123]
	v_mfma_f32_16x16x32_bf16 v[56:59], v[156:159], v[164:167], v[56:59]
	v_mfma_f32_16x16x32_bf16 v[112:115], v[148:151], v[182:185], v[112:115]
	v_mfma_f32_16x16x32_bf16 v[48:51], v[156:159], v[182:185], v[48:51]
	v_mfma_f32_16x16x32_bf16 v[104:107], v[148:151], v[198:201], v[104:107]
	v_mfma_f32_16x16x32_bf16 v[40:43], v[156:159], v[198:201], v[40:43]
	v_mfma_f32_16x16x32_bf16 v[96:99], v[148:151], v[220:223], v[96:99]
	v_mfma_f32_16x16x32_bf16 v[32:35], v[156:159], v[220:223], v[32:35]
	s_setprio 0
	s_barrier
	s_add_i32 s76, s76, s75
	v_lshl_add_u64 v[190:191], s[0:1], 0, v[192:193]
	s_mov_b32 m0, s76
	ds_read_b128 v[160:163], v219 offset:16384
	ds_read_b128 v[164:167], v219 offset:17408
	ds_read_b128 v[178:181], v219 offset:18432
	ds_read_b128 v[182:185], v219 offset:19456
	ds_read_b128 v[186:189], v219 offset:20480
	ds_read_b128 v[198:201], v219 offset:21504
	ds_read_b128 v[202:205], v219 offset:22528
	ds_read_b128 v[220:223], v219 offset:23552
	global_load_lds_dwordx4 v[190:191], off
	s_add_i32 m0, s76, 0x2000
	s_add_u32 s76, s0, 0x40000
	v_lshl_add_u64 v[194:195], s[0:1], 0, v[168:169]
	s_addc_u32 s77, s1, 0
	s_add_i32 s29, s29, s75
	global_load_lds_dwordx4 v[194:195], off
	v_lshl_add_u64 v[196:197], s[76:77], 0, v[192:193]
	s_mov_b32 m0, s29
	v_lshl_add_u64 v[224:225], s[78:79], 0, v[170:171]
	global_load_lds_dwordx4 v[196:197], off
	v_lshl_add_u64 v[196:197], s[76:77], 0, v[168:169]
	s_add_i32 m0, s29, 0x2000
	s_nop 0
	global_load_lds_dwordx4 v[196:197], off
	v_lshl_add_u64 v[196:197], s[78:79], 0, v[172:173]
	s_mov_b32 m0, s33
	s_nop 0
	global_load_lds_dwordx4 v[196:197], off
	s_mov_b32 m0, s62
	s_nop 0
	global_load_lds_dwordx4 v[224:225], off
	s_waitcnt vmcnt(8)
	s_waitcnt lgkmcnt(0)
	s_barrier
; #define PG8_STAGE(bufoff, gbase, voff) do { _Pragma("unroll") for (int _i = 0; _i < 2; ++_i) \
;         __builtin_amdgcn_global_load_lds((const unsigned*)((const char*)(gbase) + (voff)[_i]), (PG8_LAS unsigned*)(lds + (bufoff) + ldsw + _i * 8192), 16, 0, 0); } while (0)
; #define PG8_LDA(dst, b, h) do { _Pragma("unroll") for (int m = 0; m < 4; ++m) _Pragma("unroll") for (int k = 0; k < 2; ++k) dst[m][k] = *(const PG8_LAS bf16x8*)(lds + PG8_SA(b, h) + aoff + m * 2048 + k * 1024); } while (0)
; #define PG8_LDB(dst, b, h) do { _Pragma("unroll") for (int n = 0; n < 2; ++n) _Pragma("unroll") for (int k = 0; k < 2; ++k) dst[n][k] = *(const PG8_LAS bf16x8*)(lds + PG8_SB(b, h) + boff + n * 2048 + k * 1024); } while (0)
; #define PG8_MMA(ai, bj, At, Bt) do { __builtin_amdgcn_s_setprio(1); _Pragma("unroll") for (int m = 0; m < 4; ++m) _Pragma("unroll") for (int n = 0; n < 2; ++n) _Pragma("unroll") for (int k = 0; k < 2; ++k) \
;         acc[ai][bj][m][n] = __builtin_amdgcn_mfma_f32_16x16x32_bf16(Bt[n][k], At[m][k], acc[ai][bj][m][n], 0, 0, 0); __builtin_amdgcn_s_setprio(0); } while (0)
; #define PG8_WAIT_V(n) asm volatile("s_waitcnt vmcnt(" #n ")" ::: "memory")
; #define PG8_WAIT_L(n) asm volatile("s_waitcnt lgkmcnt(" #n ")" ::: "memory")
; #define PG8_BAR __builtin_amdgcn_s_barrier()
; #define PG8_SCHED __builtin_amdgcn_sched_barrier(0)
; template <class Epi, class Sched, bool ALIGN_EPI = false, bool SP2 = false>
; __device__ __forceinline__ void gemm_phase(PG8_LAS unsigned char* lds, const Gemm g, const Sched& S, const Epi& E, int wave_in) {
;     ...
;             PG8_WAIT_V(8); PG8_WAIT_L(0); PG8_BAR; PG8_MMA(1, 0, At, B0); PG8_MMA(1, 1, At, B1); PG8_BAR; PG8_SCHED;
;             PG8_LDB(B0, 1, 0); PG8_LDB(B1, 1, 1); PG8_SCHED; PG8_LDA(At, 1, 0); PG8_STAGE(PG8_SA(0, 1), a2 + hstep, voffA);
;             PG8_WAIT_V(8); PG8_WAIT_L(0); PG8_BAR; PG8_MMA(0, 0, At, B0); PG8_MMA(0, 1, At, B1); PG8_BAR; PG8_SCHED;
	s_setprio 1
	s_waitcnt lgkmcnt(0)
	v_mfma_f32_16x16x32_bf16 v[92:95], v[128:131], v[160:163], 0
	v_mfma_f32_16x16x32_bf16 v[28:31], v[136:139], v[160:163], 0
	v_mfma_f32_16x16x32_bf16 v[84:87], v[128:131], v[178:181], 0
	v_mfma_f32_16x16x32_bf16 v[20:23], v[136:139], v[178:181], 0
	v_mfma_f32_16x16x32_bf16 v[76:79], v[128:131], v[186:189], 0
	v_mfma_f32_16x16x32_bf16 v[12:15], v[136:139], v[186:189], 0
	v_mfma_f32_16x16x32_bf16 v[68:71], v[128:131], v[202:205], 0
	v_mfma_f32_16x16x32_bf16 v[4:7], v[136:139], v[202:205], 0
	v_mfma_f32_16x16x32_bf16 v[92:95], v[132:135], v[164:167], v[92:95]
	v_mfma_f32_16x16x32_bf16 v[28:31], v[140:143], v[164:167], v[28:31]
	v_mfma_f32_16x16x32_bf16 v[84:87], v[132:135], v[182:185], v[84:87]
	v_mfma_f32_16x16x32_bf16 v[20:23], v[140:143], v[182:185], v[20:23]
	v_mfma_f32_16x16x32_bf16 v[76:79], v[132:135], v[198:201], v[76:79]
	v_mfma_f32_16x16x32_bf16 v[12:15], v[140:143], v[198:201], v[12:15]
	v_mfma_f32_16x16x32_bf16 v[68:71], v[132:135], v[220:223], v[68:71]
	v_mfma_f32_16x16x32_bf16 v[4:7], v[140:143], v[220:223], v[4:7]
	s_setprio 0
	s_setprio 1
	v_mfma_f32_16x16x32_bf16 v[88:91], v[144:147], v[160:163], 0
	v_mfma_f32_16x16x32_bf16 v[24:27], v[152:155], v[160:163], 0
	v_mfma_f32_16x16x32_bf16 v[80:83], v[144:147], v[178:181], 0
	v_mfma_f32_16x16x32_bf16 v[16:19], v[152:155], v[178:181], 0
	v_mfma_f32_16x16x32_bf16 v[72:75], v[144:147], v[186:189], 0
	v_mfma_f32_16x16x32_bf16 v[8:11], v[152:155], v[186:189], 0
	v_mfma_f32_16x16x32_bf16 v[64:67], v[144:147], v[202:205], 0
	v_mfma_f32_16x16x32_bf16 v[0:3], v[152:155], v[202:205], 0
	v_mfma_f32_16x16x32_bf16 v[88:91], v[148:151], v[164:167], v[88:91]
	v_mfma_f32_16x16x32_bf16 v[24:27], v[156:159], v[164:167], v[24:27]
	v_mfma_f32_16x16x32_bf16 v[80:83], v[148:151], v[182:185], v[80:83]
	v_mfma_f32_16x16x32_bf16 v[16:19], v[156:159], v[182:185], v[16:19]
	v_mfma_f32_16x16x32_bf16 v[72:75], v[148:151], v[198:201], v[72:75]
	v_mfma_f32_16x16x32_bf16 v[8:11], v[156:159], v[198:201], v[8:11]
	v_mfma_f32_16x16x32_bf16 v[64:67], v[148:151], v[220:223], v[64:67]
	v_mfma_f32_16x16x32_bf16 v[0:3], v[156:159], v[220:223], v[0:3]
	s_setprio 0
	s_barrier
	s_add_i32 s29, s65, 0x100
	s_add_i32 s2, s52, 0x100
	v_add_u32_e32 v140, s29, v207
	v_add_u32_e32 v156, s2, v207
	ds_read_b128 v[128:131], v140
	ds_read_b128 v[132:135], v140 offset:1024
	ds_read_b128 v[136:139], v140 offset:2048
	ds_read_b128 v[140:143], v140 offset:3072
	ds_read_b128 v[144:147], v156
	ds_read_b128 v[148:151], v156 offset:1024
	ds_read_b128 v[152:155], v156 offset:2048
	ds_read_b128 v[156:159], v156 offset:3072
	s_add_u32 s76, s78, 0x40000
	s_addc_u32 s77, s79, 0
	s_mov_b32 m0, s63
	v_lshl_add_u64 v[226:227], s[76:77], 0, v[172:173]
	ds_read_b128 v[160:163], v219 offset:32768
	ds_read_b128 v[164:167], v219 offset:33792
	ds_read_b128 v[178:181], v219 offset:34816
	ds_read_b128 v[182:185], v219 offset:35840
	ds_read_b128 v[186:189], v219 offset:36864
	ds_read_b128 v[198:201], v219 offset:37888
	ds_read_b128 v[202:205], v219 offset:38912
	ds_read_b128 v[220:223], v219 offset:39936
	global_load_lds_dwordx4 v[226:227], off
	v_lshl_add_u64 v[226:227], s[76:77], 0, v[170:171]
	s_mov_b32 m0, s31
	s_nop 0
	global_load_lds_dwordx4 v[226:227], off
	s_waitcnt vmcnt(8)
	s_waitcnt lgkmcnt(0)
	s_barrier
	s_setprio 1
	s_waitcnt lgkmcnt(0)
	v_mfma_f32_16x16x32_bf16 v[124:127], v[128:131], v[160:163], v[124:127]
	v_mfma_f32_16x16x32_bf16 v[60:63], v[136:139], v[160:163], v[60:63]
	v_mfma_f32_16x16x32_bf16 v[116:119], v[128:131], v[178:181], v[116:119]
	v_mfma_f32_16x16x32_bf16 v[52:55], v[136:139], v[178:181], v[52:55]
	v_mfma_f32_16x16x32_bf16 v[108:111], v[128:131], v[186:189], v[108:111]
	v_mfma_f32_16x16x32_bf16 v[44:47], v[136:139], v[186:189], v[44:47]
	v_mfma_f32_16x16x32_bf16 v[100:103], v[128:131], v[202:205], v[100:103]
	v_mfma_f32_16x16x32_bf16 v[36:39], v[136:139], v[202:205], v[36:39]
	v_mfma_f32_16x16x32_bf16 v[124:127], v[132:135], v[164:167], v[124:127]
	v_mfma_f32_16x16x32_bf16 v[60:63], v[140:143], v[164:167], v[60:63]
	v_mfma_f32_16x16x32_bf16 v[116:119], v[132:135], v[182:185], v[116:119]
	v_mfma_f32_16x16x32_bf16 v[52:55], v[140:143], v[182:185], v[52:55]
	v_mfma_f32_16x16x32_bf16 v[108:111], v[132:135], v[198:201], v[108:111]
	v_mfma_f32_16x16x32_bf16 v[44:47], v[140:143], v[198:201], v[44:47]
	v_mfma_f32_16x16x32_bf16 v[100:103], v[132:135], v[220:223], v[100:103]
	v_mfma_f32_16x16x32_bf16 v[36:39], v[140:143], v[220:223], v[36:39]
	s_setprio 0
	s_setprio 1
	v_mfma_f32_16x16x32_bf16 v[120:123], v[144:147], v[160:163], v[120:123]
	v_mfma_f32_16x16x32_bf16 v[56:59], v[152:155], v[160:163], v[56:59]
	v_mfma_f32_16x16x32_bf16 v[112:115], v[144:147], v[178:181], v[112:115]
	v_mfma_f32_16x16x32_bf16 v[48:51], v[152:155], v[178:181], v[48:51]
	v_mfma_f32_16x16x32_bf16 v[104:107], v[144:147], v[186:189], v[104:107]
	v_mfma_f32_16x16x32_bf16 v[40:43], v[152:155], v[186:189], v[40:43]
	v_mfma_f32_16x16x32_bf16 v[96:99], v[144:147], v[202:205], v[96:99]
	v_mfma_f32_16x16x32_bf16 v[32:35], v[152:155], v[202:205], v[32:35]
	v_mfma_f32_16x16x32_bf16 v[120:123], v[148:151], v[164:167], v[120:123]
	v_mfma_f32_16x16x32_bf16 v[56:59], v[156:159], v[164:167], v[56:59]
	v_mfma_f32_16x16x32_bf16 v[112:115], v[148:151], v[182:185], v[112:115]
	v_mfma_f32_16x16x32_bf16 v[48:51], v[156:159], v[182:185], v[48:51]
	v_mfma_f32_16x16x32_bf16 v[104:107], v[148:151], v[198:201], v[104:107]
	v_mfma_f32_16x16x32_bf16 v[40:43], v[156:159], v[198:201], v[40:43]
	v_mfma_f32_16x16x32_bf16 v[96:99], v[148:151], v[220:223], v[96:99]
	v_mfma_f32_16x16x32_bf16 v[32:35], v[156:159], v[220:223], v[32:35]
	s_setprio 0
	s_barrier
; #define PG8_STAGE(bufoff, gbase, voff) do { _Pragma("unroll") for (int _i = 0; _i < 2; ++_i) \
;         __builtin_amdgcn_global_load_lds((const unsigned*)((const char*)(gbase) + (voff)[_i]), (PG8_LAS unsigned*)(lds + (bufoff) + ldsw + _i * 8192), 16, 0, 0); } while (0)
; #define PG8_LDA(dst, b, h) do { _Pragma("unroll") for (int m = 0; m < 4; ++m) _Pragma("unroll") for (int k = 0; k < 2; ++k) dst[m][k] = *(const PG8_LAS bf16x8*)(lds + PG8_SA(b, h) + aoff + m * 2048 + k * 1024); } while (0)
; #define PG8_WAIT_V(n) asm volatile("s_waitcnt vmcnt(" #n ")" ::: "memory")
; #define PG8_WAIT_L(n) asm volatile("s_waitcnt lgkmcnt(" #n ")" ::: "memory")
; #define PG8_BAR __builtin_amdgcn_s_barrier()
; template <class Epi, class Sched, bool ALIGN_EPI = false, bool SP2 = false>
; __device__ __forceinline__ void gemm_phase(PG8_LAS unsigned char* lds, const Gemm g, const Sched& S, const Epi& E, int wave_in) {
;     ...
;         for (int t = 0; t < nt; t += 2) {
;             const bool last = (t == nt - 2);
;             const char* a1 = cA + (size_t)(t + 1) * kstep;
;             const char* a2 = last ? nA : cA + (size_t)(t + 2) * kstep; const char* b2 = last ? nB : cB + (size_t)(t + 2) * kstep;
;             const char* a3 = a2 + kstep; const char* b3 = b2 + kstep;
;             if (last && has_next) S.a_ready(nxt);
;             if constexpr (SP2) {
;             PG8_LDB(B0, 0, 0); PG8_LDB(B1, 0, 1); PG8_SCHED; PG8_LDA(At, 0, 0); PG8_STAGE(PG8_SA(1, 1), a1 + hstep, voffA);
;             PG8_WAIT_V(8); PG8_WAIT_L(0); PG8_BAR; PG8_MMA(0, 0, At, B0); PG8_MMA(0, 1, At, B1); PG8_BAR; PG8_SCHED;
;             PG8_LDA(At, 0, 1); PG8_STAGE(PG8_SB(0, 0), b2, voffB); PG8_STAGE(PG8_SB(0, 1), b2 + hstep, voffB); PG8_STAGE(PG8_SA(0, 0), a2, voffA);
;             PG8_WAIT_V(8); PG8_WAIT_L(0); PG8_BAR; PG8_MMA(1, 0, At, B0); PG8_MMA(1, 1, At, B1); PG8_BAR; PG8_SCHED;
;             PG8_LDB(B0, 1, 0); PG8_LDB(B1, 1, 1); PG8_SCHED; PG8_LDA(At, 1, 0); PG8_STAGE(PG8_SA(0, 1), a2 + hstep, voffA);
;             PG8_WAIT_V(8); PG8_WAIT_L(0); PG8_BAR; PG8_MMA(0, 0, At, B0); PG8_MMA(0, 1, At, B1); PG8_BAR; PG8_SCHED;
;             PG8_LDA(At, 1, 1); PG8_STAGE(PG8_SB(1, 0), b3, voffB); PG8_STAGE(PG8_SB(1, 1), b3 + hstep, voffB); PG8_STAGE(PG8_SA(1, 0), a3, voffA);
;             PG8_WAIT_V(8); PG8_WAIT_L(0); PG8_BAR; PG8_MMA(1, 0, At, B0); PG8_MMA(1, 1, At, B1); PG8_BAR; PG8_SCHED;
	s_add_i32 s29, s29, s75
	v_lshl_add_u64 v[190:191], v[190:191], 0, s[88:89]
	s_mov_b32 m0, s29
	ds_read_b128 v[160:163], v219 offset:49152
	ds_read_b128 v[164:167], v219 offset:50176
	ds_read_b128 v[178:181], v219 offset:51200
	ds_read_b128 v[182:185], v219 offset:52224
	ds_read_b128 v[186:189], v219 offset:53248
	ds_read_b128 v[198:201], v219 offset:54272
	ds_read_b128 v[202:205], v219 offset:55296
	ds_read_b128 v[220:223], v219 offset:56320
	global_load_lds_dwordx4 v[190:191], off
	s_add_i32 m0, s29, 0x2000
	s_add_u32 s0, s0, 0x40080
	v_lshl_add_u64 v[190:191], v[194:195], 0, s[88:89]
	s_addc_u32 s1, s1, 0
	s_add_i32 s2, s2, s75
	global_load_lds_dwordx4 v[190:191], off
	v_lshl_add_u64 v[190:191], s[0:1], 0, v[192:193]
	s_mov_b32 m0, s2
	s_nop 0
	global_load_lds_dwordx4 v[190:191], off
	v_lshl_add_u64 v[190:191], s[0:1], 0, v[168:169]
	s_add_i32 m0, s2, 0x2000
	s_nop 0
	global_load_lds_dwordx4 v[190:191], off
	v_lshl_add_u64 v[190:191], v[196:197], 0, s[88:89]
	s_mov_b32 m0, s9
	s_nop 0
	global_load_lds_dwordx4 v[190:191], off
	v_lshl_add_u64 v[190:191], v[224:225], 0, s[88:89]
	s_mov_b32 m0, s96
	s_nop 0
	global_load_lds_dwordx4 v[190:191], off
	s_waitcnt vmcnt(8)
	s_waitcnt lgkmcnt(0)
	s_barrier
	s_setprio 1
	s_waitcnt lgkmcnt(0)
	v_mfma_f32_16x16x32_bf16 v[92:95], v[128:131], v[160:163], v[92:95]
	v_mfma_f32_16x16x32_bf16 v[28:31], v[136:139], v[160:163], v[28:31]
	v_mfma_f32_16x16x32_bf16 v[84:87], v[128:131], v[178:181], v[84:87]
	v_mfma_f32_16x16x32_bf16 v[20:23], v[136:139], v[178:181], v[20:23]
	v_mfma_f32_16x16x32_bf16 v[76:79], v[128:131], v[186:189], v[76:79]
	v_mfma_f32_16x16x32_bf16 v[12:15], v[136:139], v[186:189], v[12:15]
	v_mfma_f32_16x16x32_bf16 v[68:71], v[128:131], v[202:205], v[68:71]
	v_mfma_f32_16x16x32_bf16 v[4:7], v[136:139], v[202:205], v[4:7]
	v_mfma_f32_16x16x32_bf16 v[92:95], v[132:135], v[164:167], v[92:95]
	v_mfma_f32_16x16x32_bf16 v[28:31], v[140:143], v[164:167], v[28:31]
	v_mfma_f32_16x16x32_bf16 v[84:87], v[132:135], v[182:185], v[84:87]
	v_mfma_f32_16x16x32_bf16 v[20:23], v[140:143], v[182:185], v[20:23]
	v_mfma_f32_16x16x32_bf16 v[76:79], v[132:135], v[198:201], v[76:79]
	v_mfma_f32_16x16x32_bf16 v[12:15], v[140:143], v[198:201], v[12:15]
	v_mfma_f32_16x16x32_bf16 v[68:71], v[132:135], v[220:223], v[68:71]
	v_mfma_f32_16x16x32_bf16 v[4:7], v[140:143], v[220:223], v[4:7]
	s_setprio 0
	s_setprio 1
	v_mfma_f32_16x16x32_bf16 v[88:91], v[144:147], v[160:163], v[88:91]
	v_mfma_f32_16x16x32_bf16 v[24:27], v[152:155], v[160:163], v[24:27]
	v_mfma_f32_16x16x32_bf16 v[80:83], v[144:147], v[178:181], v[80:83]
	v_mfma_f32_16x16x32_bf16 v[16:19], v[152:155], v[178:181], v[16:19]
	v_mfma_f32_16x16x32_bf16 v[72:75], v[144:147], v[186:189], v[72:75]
	v_mfma_f32_16x16x32_bf16 v[8:11], v[152:155], v[186:189], v[8:11]
	v_mfma_f32_16x16x32_bf16 v[64:67], v[144:147], v[202:205], v[64:67]
	v_mfma_f32_16x16x32_bf16 v[0:3], v[152:155], v[202:205], v[0:3]
	v_mfma_f32_16x16x32_bf16 v[88:91], v[148:151], v[164:167], v[88:91]
	v_mfma_f32_16x16x32_bf16 v[24:27], v[156:159], v[164:167], v[24:27]
	v_mfma_f32_16x16x32_bf16 v[80:83], v[148:151], v[182:185], v[80:83]
	v_mfma_f32_16x16x32_bf16 v[16:19], v[156:159], v[182:185], v[16:19]
	v_mfma_f32_16x16x32_bf16 v[72:75], v[148:151], v[198:201], v[72:75]
	v_mfma_f32_16x16x32_bf16 v[8:11], v[156:159], v[198:201], v[8:11]
	v_mfma_f32_16x16x32_bf16 v[64:67], v[148:151], v[220:223], v[64:67]
	v_mfma_f32_16x16x32_bf16 v[0:3], v[156:159], v[220:223], v[0:3]
	s_setprio 0
	s_add_i32 s19, s19, 2
	s_add_u32 s81, s81, 0x100
	s_addc_u32 s18, s18, 0
	s_add_u32 vcc_lo, vcc_lo, 0x100
	s_addc_u32 vcc_hi, vcc_hi, 0
	s_cmp_gt_u32 s19, 13
	s_cbranch_scc1 .Lxbar_6
	s_add_u32 s0, vcc_lo, 0xfffc0080
	s_addc_u32 s1, vcc_hi, -1
	s_add_i32 s76, s35, 0x100
	s_cmp_eq_u32 s19, 12
	s_cselect_b32 s79, s11, s1
	s_cselect_b32 s78, s34, s0
	s_cselect_b32 s1, s5, s18
	s_cselect_b32 s0, s53, s81
	s_add_i32 s29, s90, 0x100

; #define PG8_STAGE(bufoff, gbase, voff) do { _Pragma("unroll") for (int _i = 0; _i < 2; ++_i) \
;         __builtin_amdgcn_global_load_lds((const unsigned*)((const char*)(gbase) + (voff)[_i]), (PG8_LAS unsigned*)(lds + (bufoff) + ldsw + _i * 8192), 16, 0, 0); } while (0)
; #define PG8_LDA(dst, b, h) do { _Pragma("unroll") for (int m = 0; m < 4; ++m) _Pragma("unroll") for (int k = 0; k < 2; ++k) dst[m][k] = *(const PG8_LAS bf16x8*)(lds + PG8_SA(b, h) + aoff + m * 2048 + k * 1024); } while (0)
; #define PG8_LDB(dst, b, h) do { _Pragma("unroll") for (int n = 0; n < 2; ++n) _Pragma("unroll") for (int k = 0; k < 2; ++k) dst[n][k] = *(const PG8_LAS bf16x8*)(lds + PG8_SB(b, h) + boff + n * 2048 + k * 1024); } while (0)
; #define PG8_MMA(ai, bj, At, Bt) do { __builtin_amdgcn_s_setprio(1); _Pragma("unroll") for (int m = 0; m < 4; ++m) _Pragma("unroll") for (int n = 0; n < 2; ++n) _Pragma("unroll") for (int k = 0; k < 2; ++k) \
;         acc[ai][bj][m][n] = __builtin_amdgcn_mfma_f32_16x16x32_bf16(Bt[n][k], At[m][k], acc[ai][bj][m][n], 0, 0, 0); __builtin_amdgcn_s_setprio(0); } while (0)
; #define PG8_WAIT_V(n) asm volatile("s_waitcnt vmcnt(" #n ")" ::: "memory")
; #define PG8_WAIT_L(n) asm volatile("s_waitcnt lgkmcnt(" #n ")" ::: "memory")
; #define PG8_BAR __builtin_amdgcn_s_barrier()
; #define PG8_SCHED __builtin_amdgcn_sched_barrier(0)
; template <class Epi, class Sched, bool ALIGN_EPI = false, bool SP2 = false>
; __device__ __forceinline__ void gemm_phase(PG8_LAS unsigned char* lds, const Gemm g, const Sched& S, const Epi& E, int wave_in) {
;     ...
;             PG8_LDB(B0, 0, 0); PG8_LDB(B1, 0, 1); PG8_SCHED; PG8_LDA(At, 0, 0); PG8_STAGE(PG8_SA(1, 1), a1 + hstep, voffA);
;             PG8_WAIT_V(8); PG8_WAIT_L(0); PG8_BAR; PG8_MMA(0, 0, At, B0); PG8_MMA(0, 1, At, B1); PG8_BAR; PG8_SCHED;
;             PG8_LDA(At, 0, 1); PG8_STAGE(PG8_SB(0, 0), b2, voffB); PG8_STAGE(PG8_SB(0, 1), b2 + hstep, voffB); PG8_STAGE(PG8_SA(0, 0), a2, voffA);
;             PG8_WAIT_V(8); PG8_WAIT_L(0); PG8_BAR; PG8_MMA(1, 0, At, B0); PG8_MMA(1, 1, At, B1); PG8_BAR; PG8_SCHED;
.LBB0_897:
	v_add_u32_e32 v140, s76, v207
	v_add_u32_e32 v156, s29, v207
	ds_read_b128 v[128:131], v140
	ds_read_b128 v[132:135], v140 offset:1024
	ds_read_b128 v[136:139], v140 offset:2048
	ds_read_b128 v[140:143], v140 offset:3072
	ds_read_b128 v[144:147], v156
	ds_read_b128 v[148:151], v156 offset:1024
	ds_read_b128 v[152:155], v156 offset:2048
	ds_read_b128 v[156:159], v156 offset:3072
	v_lshl_add_u64 v[190:191], vcc, 0, v[176:177]
	s_add_i32 m0, s33, 0xc000
	ds_read_b128 v[160:163], v219
	ds_read_b128 v[164:167], v219 offset:1024
	ds_read_b128 v[178:181], v219 offset:2048
	ds_read_b128 v[182:185], v219 offset:3072
	ds_read_b128 v[186:189], v219 offset:4096
	ds_read_b128 v[198:201], v219 offset:5120
	ds_read_b128 v[202:205], v219 offset:6144
	ds_read_b128 v[220:223], v219 offset:7168
	global_load_lds_dwordx4 v[190:191], off
	v_lshl_add_u64 v[190:191], vcc, 0, v[174:175]
	s_add_i32 m0, s33, 0xe000
	s_nop 0
	global_load_lds_dwordx4 v[190:191], off
	s_waitcnt vmcnt(8)
	s_waitcnt lgkmcnt(0)
	s_barrier
	s_setprio 1
	s_waitcnt lgkmcnt(0)
	v_mfma_f32_16x16x32_bf16 v[124:127], v[128:131], v[160:163], v[124:127]
	v_mfma_f32_16x16x32_bf16 v[60:63], v[136:139], v[160:163], v[60:63]
	v_mfma_f32_16x16x32_bf16 v[116:119], v[128:131], v[178:181], v[116:119]
	v_mfma_f32_16x16x32_bf16 v[52:55], v[136:139], v[178:181], v[52:55]
	v_mfma_f32_16x16x32_bf16 v[108:111], v[128:131], v[186:189], v[108:111]
	v_mfma_f32_16x16x32_bf16 v[44:47], v[136:139], v[186:189], v[44:47]
	v_mfma_f32_16x16x32_bf16 v[100:103], v[128:131], v[202:205], v[100:103]
	v_mfma_f32_16x16x32_bf16 v[36:39], v[136:139], v[202:205], v[36:39]
	v_mfma_f32_16x16x32_bf16 v[124:127], v[132:135], v[164:167], v[124:127]
	v_mfma_f32_16x16x32_bf16 v[60:63], v[140:143], v[164:167], v[60:63]
	v_mfma_f32_16x16x32_bf16 v[116:119], v[132:135], v[182:185], v[116:119]
	v_mfma_f32_16x16x32_bf16 v[52:55], v[140:143], v[182:185], v[52:55]
	v_mfma_f32_16x16x32_bf16 v[108:111], v[132:135], v[198:201], v[108:111]
	v_mfma_f32_16x16x32_bf16 v[44:47], v[140:143], v[198:201], v[44:47]
	v_mfma_f32_16x16x32_bf16 v[100:103], v[132:135], v[220:223], v[100:103]
	v_mfma_f32_16x16x32_bf16 v[36:39], v[140:143], v[220:223], v[36:39]
	s_setprio 0
	s_setprio 1
	v_mfma_f32_16x16x32_bf16 v[120:123], v[144:147], v[160:163], v[120:123]
	v_mfma_f32_16x16x32_bf16 v[56:59], v[152:155], v[160:163], v[56:59]
	v_mfma_f32_16x16x32_bf16 v[112:115], v[144:147], v[178:181], v[112:115]
	v_mfma_f32_16x16x32_bf16 v[48:51], v[152:155], v[178:181], v[48:51]
	v_mfma_f32_16x16x32_bf16 v[104:107], v[144:147], v[186:189], v[104:107]
	v_mfma_f32_16x16x32_bf16 v[40:43], v[152:155], v[186:189], v[40:43]
	v_mfma_f32_16x16x32_bf16 v[96:99], v[144:147], v[202:205], v[96:99]
	v_mfma_f32_16x16x32_bf16 v[32:35], v[152:155], v[202:205], v[32:35]
	v_mfma_f32_16x16x32_bf16 v[120:123], v[148:151], v[164:167], v[120:123]
	v_mfma_f32_16x16x32_bf16 v[56:59], v[156:159], v[164:167], v[56:59]
	v_mfma_f32_16x16x32_bf16 v[112:115], v[148:151], v[182:185], v[112:115]
	v_mfma_f32_16x16x32_bf16 v[48:51], v[156:159], v[182:185], v[48:51]
	v_mfma_f32_16x16x32_bf16 v[104:107], v[148:151], v[198:201], v[104:107]
	v_mfma_f32_16x16x32_bf16 v[40:43], v[156:159], v[198:201], v[40:43]
	v_mfma_f32_16x16x32_bf16 v[96:99], v[148:151], v[220:223], v[96:99]
	v_mfma_f32_16x16x32_bf16 v[32:35], v[156:159], v[220:223], v[32:35]
	s_setprio 0
	s_barrier
	s_add_i32 s76, s76, s75
	v_lshl_add_u64 v[190:191], s[0:1], 0, v[192:193]
	s_mov_b32 m0, s76
	ds_read_b128 v[160:163], v219 offset:16384
	ds_read_b128 v[164:167], v219 offset:17408
	ds_read_b128 v[178:181], v219 offset:18432
	ds_read_b128 v[182:185], v219 offset:19456
	ds_read_b128 v[186:189], v219 offset:20480
	ds_read_b128 v[198:201], v219 offset:21504
	ds_read_b128 v[202:205], v219 offset:22528
	ds_read_b128 v[220:223], v219 offset:23552
	global_load_lds_dwordx4 v[190:191], off
	s_add_i32 m0, s76, 0x2000
	s_add_u32 s76, s0, 0x40000
	v_lshl_add_u64 v[194:195], s[0:1], 0, v[168:169]
	s_addc_u32 s77, s1, 0
	s_add_i32 s29, s29, s75
	global_load_lds_dwordx4 v[194:195], off
	v_lshl_add_u64 v[196:197], s[76:77], 0, v[192:193]
	s_mov_b32 m0, s29
	v_lshl_add_u64 v[224:225], s[78:79], 0, v[170:171]
	global_load_lds_dwordx4 v[196:197], off
	v_lshl_add_u64 v[196:197], s[76:77], 0, v[168:169]
	s_add_i32 m0, s29, 0x2000
	s_nop 0
	global_load_lds_dwordx4 v[196:197], off
	v_lshl_add_u64 v[196:197], s[78:79], 0, v[172:173]
	s_mov_b32 m0, s33
	s_nop 0
	global_load_lds_dwordx4 v[196:197], off
	s_mov_b32 m0, s62
	s_nop 0
	global_load_lds_dwordx4 v[224:225], off
	s_waitcnt vmcnt(8)
	s_waitcnt lgkmcnt(0)
	s_barrier
; #define PG8_STAGE(bufoff, gbase, voff) do { _Pragma("unroll") for (int _i = 0; _i < 2; ++_i) \
;         __builtin_amdgcn_global_load_lds((const unsigned*)((const char*)(gbase) + (voff)[_i]), (PG8_LAS unsigned*)(lds + (bufoff) + ldsw + _i * 8192), 16, 0, 0); } while (0)
; #define PG8_LDA(dst, b, h) do { _Pragma("unroll") for (int m = 0; m < 4; ++m) _Pragma("unroll") for (int k = 0; k < 2; ++k) dst[m][k] = *(const PG8_LAS bf16x8*)(lds + PG8_SA(b, h) + aoff + m * 2048 + k * 1024); } while (0)
; #define PG8_LDB(dst, b, h) do { _Pragma("unroll") for (int n = 0; n < 2; ++n) _Pragma("unroll") for (int k = 0; k < 2; ++k) dst[n][k] = *(const PG8_LAS bf16x8*)(lds + PG8_SB(b, h) + boff + n * 2048 + k * 1024); } while (0)
; #define PG8_MMA(ai, bj, At, Bt) do { __builtin_amdgcn_s_setprio(1); _Pragma("unroll") for (int m = 0; m < 4; ++m) _Pragma("unroll") for (int n = 0; n < 2; ++n) _Pragma("unroll") for (int k = 0; k < 2; ++k) \
;         acc[ai][bj][m][n] = __builtin_amdgcn_mfma_f32_16x16x32_bf16(Bt[n][k], At[m][k], acc[ai][bj][m][n], 0, 0, 0); __builtin_amdgcn_s_setprio(0); } while (0)
; #define PG8_WAIT_V(n) asm volatile("s_waitcnt vmcnt(" #n ")" ::: "memory")
; #define PG8_WAIT_L(n) asm volatile("s_waitcnt lgkmcnt(" #n ")" ::: "memory")
; #define PG8_BAR __builtin_amdgcn_s_barrier()
; #define PG8_SCHED __builtin_amdgcn_sched_barrier(0)
; template <class Epi, class Sched, bool ALIGN_EPI = false, bool SP2 = false>
; __device__ __forceinline__ void gemm_phase(PG8_LAS unsigned char* lds, const Gemm g, const Sched& S, const Epi& E, int wave_in) {
;     ...
;             PG8_WAIT_V(8); PG8_WAIT_L(0); PG8_BAR; PG8_MMA(1, 0, At, B0); PG8_MMA(1, 1, At, B1); PG8_BAR; PG8_SCHED;
;             PG8_LDB(B0, 1, 0); PG8_LDB(B1, 1, 1); PG8_SCHED; PG8_LDA(At, 1, 0); PG8_STAGE(PG8_SA(0, 1), a2 + hstep, voffA);
;             PG8_WAIT_V(8); PG8_WAIT_L(0); PG8_BAR; PG8_MMA(0, 0, At, B0); PG8_MMA(0, 1, At, B1); PG8_BAR; PG8_SCHED;
	s_setprio 1
	s_waitcnt lgkmcnt(0)
	v_mfma_f32_16x16x32_bf16 v[92:95], v[128:131], v[160:163], v[92:95]
	v_mfma_f32_16x16x32_bf16 v[28:31], v[136:139], v[160:163], v[28:31]
	v_mfma_f32_16x16x32_bf16 v[84:87], v[128:131], v[178:181], v[84:87]
	v_mfma_f32_16x16x32_bf16 v[20:23], v[136:139], v[178:181], v[20:23]
	v_mfma_f32_16x16x32_bf16 v[76:79], v[128:131], v[186:189], v[76:79]
	v_mfma_f32_16x16x32_bf16 v[12:15], v[136:139], v[186:189], v[12:15]
	v_mfma_f32_16x16x32_bf16 v[68:71], v[128:131], v[202:205], v[68:71]
	v_mfma_f32_16x16x32_bf16 v[4:7], v[136:139], v[202:205], v[4:7]
	v_mfma_f32_16x16x32_bf16 v[92:95], v[132:135], v[164:167], v[92:95]
	v_mfma_f32_16x16x32_bf16 v[28:31], v[140:143], v[164:167], v[28:31]
	v_mfma_f32_16x16x32_bf16 v[84:87], v[132:135], v[182:185], v[84:87]
	v_mfma_f32_16x16x32_bf16 v[20:23], v[140:143], v[182:185], v[20:23]
	v_mfma_f32_16x16x32_bf16 v[76:79], v[132:135], v[198:201], v[76:79]
	v_mfma_f32_16x16x32_bf16 v[12:15], v[140:143], v[198:201], v[12:15]
	v_mfma_f32_16x16x32_bf16 v[68:71], v[132:135], v[220:223], v[68:71]
	v_mfma_f32_16x16x32_bf16 v[4:7], v[140:143], v[220:223], v[4:7]
	s_setprio 0
	s_setprio 1
	v_mfma_f32_16x16x32_bf16 v[88:91], v[144:147], v[160:163], v[88:91]
	v_mfma_f32_16x16x32_bf16 v[24:27], v[152:155], v[160:163], v[24:27]
	v_mfma_f32_16x16x32_bf16 v[80:83], v[144:147], v[178:181], v[80:83]
	v_mfma_f32_16x16x32_bf16 v[16:19], v[152:155], v[178:181], v[16:19]
	v_mfma_f32_16x16x32_bf16 v[72:75], v[144:147], v[186:189], v[72:75]
	v_mfma_f32_16x16x32_bf16 v[8:11], v[152:155], v[186:189], v[8:11]
	v_mfma_f32_16x16x32_bf16 v[64:67], v[144:147], v[202:205], v[64:67]
	v_mfma_f32_16x16x32_bf16 v[0:3], v[152:155], v[202:205], v[0:3]
	v_mfma_f32_16x16x32_bf16 v[88:91], v[148:151], v[164:167], v[88:91]
	v_mfma_f32_16x16x32_bf16 v[24:27], v[156:159], v[164:167], v[24:27]
	v_mfma_f32_16x16x32_bf16 v[80:83], v[148:151], v[182:185], v[80:83]
	v_mfma_f32_16x16x32_bf16 v[16:19], v[156:159], v[182:185], v[16:19]
	v_mfma_f32_16x16x32_bf16 v[72:75], v[148:151], v[198:201], v[72:75]
	v_mfma_f32_16x16x32_bf16 v[8:11], v[156:159], v[198:201], v[8:11]
	v_mfma_f32_16x16x32_bf16 v[64:67], v[148:151], v[220:223], v[64:67]
	v_mfma_f32_16x16x32_bf16 v[0:3], v[156:159], v[220:223], v[0:3]
	s_setprio 0
	s_barrier
	s_add_i32 s29, s65, 0x100
	s_add_i32 s2, s52, 0x100
	v_add_u32_e32 v140, s29, v207
	v_add_u32_e32 v156, s2, v207
	ds_read_b128 v[128:131], v140
	ds_read_b128 v[132:135], v140 offset:1024
	ds_read_b128 v[136:139], v140 offset:2048
	ds_read_b128 v[140:143], v140 offset:3072
	ds_read_b128 v[144:147], v156
	ds_read_b128 v[148:151], v156 offset:1024
	ds_read_b128 v[152:155], v156 offset:2048
	ds_read_b128 v[156:159], v156 offset:3072
	s_add_u32 s76, s78, 0x40000
	s_addc_u32 s77, s79, 0
	s_mov_b32 m0, s63
	v_lshl_add_u64 v[226:227], s[76:77], 0, v[172:173]
	ds_read_b128 v[160:163], v219 offset:32768
	ds_read_b128 v[164:167], v219 offset:33792
	ds_read_b128 v[178:181], v219 offset:34816
	ds_read_b128 v[182:185], v219 offset:35840
	ds_read_b128 v[186:189], v219 offset:36864
	ds_read_b128 v[198:201], v219 offset:37888
	ds_read_b128 v[202:205], v219 offset:38912
	ds_read_b128 v[220:223], v219 offset:39936
	global_load_lds_dwordx4 v[226:227], off
	v_lshl_add_u64 v[226:227], s[76:77], 0, v[170:171]
	s_mov_b32 m0, s31
	s_nop 0
	global_load_lds_dwordx4 v[226:227], off
	s_waitcnt vmcnt(8)
	s_waitcnt lgkmcnt(0)
	s_barrier
	s_setprio 1
	s_waitcnt lgkmcnt(0)
	v_mfma_f32_16x16x32_bf16 v[124:127], v[128:131], v[160:163], v[124:127]
	v_mfma_f32_16x16x32_bf16 v[60:63], v[136:139], v[160:163], v[60:63]
	v_mfma_f32_16x16x32_bf16 v[116:119], v[128:131], v[178:181], v[116:119]
	v_mfma_f32_16x16x32_bf16 v[52:55], v[136:139], v[178:181], v[52:55]
	v_mfma_f32_16x16x32_bf16 v[108:111], v[128:131], v[186:189], v[108:111]
	v_mfma_f32_16x16x32_bf16 v[44:47], v[136:139], v[186:189], v[44:47]
	v_mfma_f32_16x16x32_bf16 v[100:103], v[128:131], v[202:205], v[100:103]
	v_mfma_f32_16x16x32_bf16 v[36:39], v[136:139], v[202:205], v[36:39]
	v_mfma_f32_16x16x32_bf16 v[124:127], v[132:135], v[164:167], v[124:127]
	v_mfma_f32_16x16x32_bf16 v[60:63], v[140:143], v[164:167], v[60:63]
	v_mfma_f32_16x16x32_bf16 v[116:119], v[132:135], v[182:185], v[116:119]
	v_mfma_f32_16x16x32_bf16 v[52:55], v[140:143], v[182:185], v[52:55]
	v_mfma_f32_16x16x32_bf16 v[108:111], v[132:135], v[198:201], v[108:111]
	v_mfma_f32_16x16x32_bf16 v[44:47], v[140:143], v[198:201], v[44:47]
	v_mfma_f32_16x16x32_bf16 v[100:103], v[132:135], v[220:223], v[100:103]
	v_mfma_f32_16x16x32_bf16 v[36:39], v[140:143], v[220:223], v[36:39]
	s_setprio 0
	s_setprio 1
	v_mfma_f32_16x16x32_bf16 v[120:123], v[144:147], v[160:163], v[120:123]
	v_mfma_f32_16x16x32_bf16 v[56:59], v[152:155], v[160:163], v[56:59]
	v_mfma_f32_16x16x32_bf16 v[112:115], v[144:147], v[178:181], v[112:115]
	v_mfma_f32_16x16x32_bf16 v[48:51], v[152:155], v[178:181], v[48:51]
	v_mfma_f32_16x16x32_bf16 v[104:107], v[144:147], v[186:189], v[104:107]
	v_mfma_f32_16x16x32_bf16 v[40:43], v[152:155], v[186:189], v[40:43]
	v_mfma_f32_16x16x32_bf16 v[96:99], v[144:147], v[202:205], v[96:99]
	v_mfma_f32_16x16x32_bf16 v[32:35], v[152:155], v[202:205], v[32:35]
	v_mfma_f32_16x16x32_bf16 v[120:123], v[148:151], v[164:167], v[120:123]
	v_mfma_f32_16x16x32_bf16 v[56:59], v[156:159], v[164:167], v[56:59]
	v_mfma_f32_16x16x32_bf16 v[112:115], v[148:151], v[182:185], v[112:115]
	v_mfma_f32_16x16x32_bf16 v[48:51], v[156:159], v[182:185], v[48:51]
	v_mfma_f32_16x16x32_bf16 v[104:107], v[148:151], v[198:201], v[104:107]
	v_mfma_f32_16x16x32_bf16 v[40:43], v[156:159], v[198:201], v[40:43]
	v_mfma_f32_16x16x32_bf16 v[96:99], v[148:151], v[220:223], v[96:99]
	v_mfma_f32_16x16x32_bf16 v[32:35], v[156:159], v[220:223], v[32:35]
	s_setprio 0
	s_barrier
; #define PG8_STAGE(bufoff, gbase, voff) do { _Pragma("unroll") for (int _i = 0; _i < 2; ++_i) \
;         __builtin_amdgcn_global_load_lds((const unsigned*)((const char*)(gbase) + (voff)[_i]), (PG8_LAS unsigned*)(lds + (bufoff) + ldsw + _i * 8192), 16, 0, 0); } while (0)
; #define PG8_LDA(dst, b, h) do { _Pragma("unroll") for (int m = 0; m < 4; ++m) _Pragma("unroll") for (int k = 0; k < 2; ++k) dst[m][k] = *(const PG8_LAS bf16x8*)(lds + PG8_SA(b, h) + aoff + m * 2048 + k * 1024); } while (0)
; #define PG8_WAIT_V(n) asm volatile("s_waitcnt vmcnt(" #n ")" ::: "memory")
; #define PG8_WAIT_L(n) asm volatile("s_waitcnt lgkmcnt(" #n ")" ::: "memory")
; #define PG8_BAR __builtin_amdgcn_s_barrier()
; template <class Epi, class Sched, bool ALIGN_EPI = false, bool SP2 = false>
; __device__ __forceinline__ void gemm_phase(PG8_LAS unsigned char* lds, const Gemm g, const Sched& S, const Epi& E, int wave_in) {
;     ...
;         for (int t = 0; t < nt; t += 2) {
;             const bool last = (t == nt - 2);
;             const char* a1 = cA + (size_t)(t + 1) * kstep;
;             const char* a2 = last ? nA : cA + (size_t)(t + 2) * kstep; const char* b2 = last ? nB : cB + (size_t)(t + 2) * kstep;
;             const char* a3 = a2 + kstep; const char* b3 = b2 + kstep;
;             if (last && has_next) S.a_ready(nxt);
;             if constexpr (SP2) {
;             PG8_LDB(B0, 0, 0); PG8_LDB(B1, 0, 1); PG8_SCHED; PG8_LDA(At, 0, 0); PG8_STAGE(PG8_SA(1, 1), a1 + hstep, voffA);
;             PG8_WAIT_V(8); PG8_WAIT_L(0); PG8_BAR; PG8_MMA(0, 0, At, B0); PG8_MMA(0, 1, At, B1); PG8_BAR; PG8_SCHED;
;             PG8_LDA(At, 0, 1); PG8_STAGE(PG8_SB(0, 0), b2, voffB); PG8_STAGE(PG8_SB(0, 1), b2 + hstep, voffB); PG8_STAGE(PG8_SA(0, 0), a2, voffA);
;             PG8_WAIT_V(8); PG8_WAIT_L(0); PG8_BAR; PG8_MMA(1, 0, At, B0); PG8_MMA(1, 1, At, B1); PG8_BAR; PG8_SCHED;
;             PG8_LDB(B0, 1, 0); PG8_LDB(B1, 1, 1); PG8_SCHED; PG8_LDA(At, 1, 0); PG8_STAGE(PG8_SA(0, 1), a2 + hstep, voffA);
;             PG8_WAIT_V(8); PG8_WAIT_L(0); PG8_BAR; PG8_MMA(0, 0, At, B0); PG8_MMA(0, 1, At, B1); PG8_BAR; PG8_SCHED;
;             PG8_LDA(At, 1, 1); PG8_STAGE(PG8_SB(1, 0), b3, voffB); PG8_STAGE(PG8_SB(1, 1), b3 + hstep, voffB); PG8_STAGE(PG8_SA(1, 0), a3, voffA);
;             PG8_WAIT_V(8); PG8_WAIT_L(0); PG8_BAR; PG8_MMA(1, 0, At, B0); PG8_MMA(1, 1, At, B1); PG8_BAR; PG8_SCHED;
	s_add_i32 s29, s29, s75
	v_lshl_add_u64 v[190:191], v[190:191], 0, s[88:89]
	s_mov_b32 m0, s29
	ds_read_b128 v[160:163], v219 offset:49152
	ds_read_b128 v[164:167], v219 offset:50176
	ds_read_b128 v[178:181], v219 offset:51200
	ds_read_b128 v[182:185], v219 offset:52224
	ds_read_b128 v[186:189], v219 offset:53248
	ds_read_b128 v[198:201], v219 offset:54272
	ds_read_b128 v[202:205], v219 offset:55296
	ds_read_b128 v[220:223], v219 offset:56320
	global_load_lds_dwordx4 v[190:191], off
	s_add_i32 m0, s29, 0x2000
	s_add_u32 s0, s0, 0x40080
	v_lshl_add_u64 v[190:191], v[194:195], 0, s[88:89]
	s_addc_u32 s1, s1, 0
	s_add_i32 s2, s2, s75
	global_load_lds_dwordx4 v[190:191], off
	v_lshl_add_u64 v[190:191], s[0:1], 0, v[192:193]
	s_mov_b32 m0, s2
	s_nop 0
	global_load_lds_dwordx4 v[190:191], off
	v_lshl_add_u64 v[190:191], s[0:1], 0, v[168:169]
	s_add_i32 m0, s2, 0x2000
	s_nop 0
	global_load_lds_dwordx4 v[190:191], off
	v_lshl_add_u64 v[190:191], v[196:197], 0, s[88:89]
	s_mov_b32 m0, s9
	s_nop 0
	global_load_lds_dwordx4 v[190:191], off
	v_lshl_add_u64 v[190:191], v[224:225], 0, s[88:89]
	s_mov_b32 m0, s96
	s_nop 0
	global_load_lds_dwordx4 v[190:191], off
	s_waitcnt vmcnt(8)
	s_waitcnt lgkmcnt(0)
	s_barrier
	s_setprio 1
	s_waitcnt lgkmcnt(0)
	v_mfma_f32_16x16x32_bf16 v[92:95], v[128:131], v[160:163], v[92:95]
	v_mfma_f32_16x16x32_bf16 v[28:31], v[136:139], v[160:163], v[28:31]
	v_mfma_f32_16x16x32_bf16 v[84:87], v[128:131], v[178:181], v[84:87]
	v_mfma_f32_16x16x32_bf16 v[20:23], v[136:139], v[178:181], v[20:23]
	v_mfma_f32_16x16x32_bf16 v[76:79], v[128:131], v[186:189], v[76:79]
	v_mfma_f32_16x16x32_bf16 v[12:15], v[136:139], v[186:189], v[12:15]
	v_mfma_f32_16x16x32_bf16 v[68:71], v[128:131], v[202:205], v[68:71]
	v_mfma_f32_16x16x32_bf16 v[4:7], v[136:139], v[202:205], v[4:7]
	v_mfma_f32_16x16x32_bf16 v[92:95], v[132:135], v[164:167], v[92:95]
	v_mfma_f32_16x16x32_bf16 v[28:31], v[140:143], v[164:167], v[28:31]
	v_mfma_f32_16x16x32_bf16 v[84:87], v[132:135], v[182:185], v[84:87]
	v_mfma_f32_16x16x32_bf16 v[20:23], v[140:143], v[182:185], v[20:23]
	v_mfma_f32_16x16x32_bf16 v[76:79], v[132:135], v[198:201], v[76:79]
	v_mfma_f32_16x16x32_bf16 v[12:15], v[140:143], v[198:201], v[12:15]
	v_mfma_f32_16x16x32_bf16 v[68:71], v[132:135], v[220:223], v[68:71]
	v_mfma_f32_16x16x32_bf16 v[4:7], v[140:143], v[220:223], v[4:7]
	s_setprio 0
	s_setprio 1
	v_mfma_f32_16x16x32_bf16 v[88:91], v[144:147], v[160:163], v[88:91]
	v_mfma_f32_16x16x32_bf16 v[24:27], v[152:155], v[160:163], v[24:27]
	v_mfma_f32_16x16x32_bf16 v[80:83], v[144:147], v[178:181], v[80:83]
	v_mfma_f32_16x16x32_bf16 v[16:19], v[152:155], v[178:181], v[16:19]
	v_mfma_f32_16x16x32_bf16 v[72:75], v[144:147], v[186:189], v[72:75]
	v_mfma_f32_16x16x32_bf16 v[8:11], v[152:155], v[186:189], v[8:11]
	v_mfma_f32_16x16x32_bf16 v[64:67], v[144:147], v[202:205], v[64:67]
	v_mfma_f32_16x16x32_bf16 v[0:3], v[152:155], v[202:205], v[0:3]
	v_mfma_f32_16x16x32_bf16 v[88:91], v[148:151], v[164:167], v[88:91]
	v_mfma_f32_16x16x32_bf16 v[24:27], v[156:159], v[164:167], v[24:27]
	v_mfma_f32_16x16x32_bf16 v[80:83], v[148:151], v[182:185], v[80:83]
	v_mfma_f32_16x16x32_bf16 v[16:19], v[156:159], v[182:185], v[16:19]
	v_mfma_f32_16x16x32_bf16 v[72:75], v[148:151], v[198:201], v[72:75]
	v_mfma_f32_16x16x32_bf16 v[8:11], v[156:159], v[198:201], v[8:11]
	v_mfma_f32_16x16x32_bf16 v[64:67], v[148:151], v[220:223], v[64:67]
	v_mfma_f32_16x16x32_bf16 v[0:3], v[156:159], v[220:223], v[0:3]
	s_setprio 0
	s_add_i32 s19, s19, 2
	s_add_u32 s81, s81, 0x100
	s_addc_u32 s18, s18, 0
	s_add_u32 vcc_lo, vcc_lo, 0x100
	s_addc_u32 vcc_hi, vcc_hi, 0
	s_cmp_gt_u32 s19, 13
	s_cbranch_scc1 .Lxbar_6
	s_add_u32 s0, vcc_lo, 0xfffc0080
	s_addc_u32 s1, vcc_hi, -1
	s_add_i32 s76, s35, 0x100
	s_cmp_eq_u32 s19, 12
	s_cselect_b32 s79, s11, s1
	s_cselect_b32 s78, s34, s0
	s_cselect_b32 s1, s5, s18
	s_cselect_b32 s0, s53, s81
	s_add_i32 s29, s90, 0x100
	s_branch .Lhbar_6

; #define PG8_STAGE(bufoff, gbase, voff) do { _Pragma("unroll") for (int _i = 0; _i < 2; ++_i) \
;         __builtin_amdgcn_global_load_lds((const unsigned*)((const char*)(gbase) + (voff)[_i]), (PG8_LAS unsigned*)(lds + (bufoff) + ldsw + _i * 8192), 16, 0, 0); } while (0)
; #define PG8_LDA(dst, b, h) do { _Pragma("unroll") for (int m = 0; m < 4; ++m) _Pragma("unroll") for (int k = 0; k < 2; ++k) dst[m][k] = *(const PG8_LAS bf16x8*)(lds + PG8_SA(b, h) + aoff + m * 2048 + k * 1024); } while (0)
; #define PG8_LDB(dst, b, h) do { _Pragma("unroll") for (int n = 0; n < 2; ++n) _Pragma("unroll") for (int k = 0; k < 2; ++k) dst[n][k] = *(const PG8_LAS bf16x8*)(lds + PG8_SB(b, h) + boff + n * 2048 + k * 1024); } while (0)
; #define PG8_MMA(ai, bj, At, Bt) do { __builtin_amdgcn_s_setprio(1); _Pragma("unroll") for (int m = 0; m < 4; ++m) _Pragma("unroll") for (int n = 0; n < 2; ++n) _Pragma("unroll") for (int k = 0; k < 2; ++k) \
;         acc[ai][bj][m][n] = __builtin_amdgcn_mfma_f32_16x16x32_bf16(Bt[n][k], At[m][k], acc[ai][bj][m][n], 0, 0, 0); __builtin_amdgcn_s_setprio(0); } while (0)
; #define PG8_WAIT_V(n) asm volatile("s_waitcnt vmcnt(" #n ")" ::: "memory")
; #define PG8_WAIT_L(n) asm volatile("s_waitcnt lgkmcnt(" #n ")" ::: "memory")
; #define PG8_BAR __builtin_amdgcn_s_barrier()
; #define PG8_SCHED __builtin_amdgcn_sched_barrier(0)
; template <class Epi, class Sched, bool ALIGN_EPI = false, bool SP2 = false>
; __device__ __forceinline__ void gemm_phase(PG8_LAS unsigned char* lds, const Gemm g, const Sched& S, const Epi& E, int wave_in) {
;     ...
;         for (int t = 0; t < nt; t += 2) {
;             const bool last = (t == nt - 2);
;             const char* a1 = cA + (size_t)(t + 1) * kstep;
;             const char* a2 = last ? nA : cA + (size_t)(t + 2) * kstep; const char* b2 = last ? nB : cB + (size_t)(t + 2) * kstep;
;             const char* a3 = a2 + kstep; const char* b3 = b2 + kstep;
;             if (last && has_next) S.a_ready(nxt);
;             if constexpr (SP2) {
;             PG8_LDB(B0, 0, 0); PG8_LDB(B1, 0, 1); PG8_SCHED; PG8_LDA(At, 0, 0); PG8_STAGE(PG8_SA(1, 1), a1 + hstep, voffA);
;             PG8_WAIT_V(8); PG8_WAIT_L(0); PG8_BAR; PG8_MMA(0, 0, At, B0); PG8_MMA(0, 1, At, B1); PG8_BAR; PG8_SCHED;
;             PG8_LDA(At, 0, 1); PG8_STAGE(PG8_SB(0, 0), b2, voffB); PG8_STAGE(PG8_SB(0, 1), b2 + hstep, voffB); PG8_STAGE(PG8_SA(0, 0), a2, voffA);
.LBB0_1030:
	s_add_u32 s34, s20, 0x100
	s_addc_u32 s42, s21, 0
	s_mov_b32 s43, -2
	s_add_u32 s20, s16, 0x100
	s_addc_u32 s21, s17, 0
	s_add_i32 s2, s35, 0x100
	s_cmp_eq_u32 s43, 40
	s_cselect_b32 s25, s13, s21
	s_cselect_b32 s24, s12, s20
	s_cselect_b32 s23, s15, s42
	s_cselect_b32 s22, s14, s34
	s_add_i32 s29, s90, 0x100
	v_add_u32_e32 v128, s2, v249
	v_add_u32_e32 v156, s29, v249
	ds_read_b128 v[112:115], v128
	ds_read_b128 v[120:123], v128 offset:1024
	ds_read_b128 v[124:127], v128 offset:2048
	ds_read_b128 v[128:131], v128 offset:3072
	ds_read_b128 v[136:139], v156
	ds_read_b128 v[140:143], v156 offset:1024
	ds_read_b128 v[144:147], v156 offset:2048
	ds_read_b128 v[156:159], v156 offset:3072
	v_lshl_add_u64 v[194:195], s[16:17], 0, v[206:207]
	s_add_i32 m0, s45, 0xc000
	ds_read_b128 v[160:163], v251
	ds_read_b128 v[164:167], v251 offset:1024
	ds_read_b128 v[168:171], v251 offset:2048
	ds_read_b128 v[172:175], v251 offset:3072
	ds_read_b128 v[176:179], v251 offset:4096
	ds_read_b128 v[180:183], v251 offset:5120
	ds_read_b128 v[184:187], v251 offset:6144
	ds_read_b128 v[188:191], v251 offset:7168
	global_load_lds_dwordx4 v[194:195], off
	v_lshl_add_u64 v[194:195], s[16:17], 0, v[204:205]
	s_add_i32 m0, s45, 0xe000
	s_nop 0
	global_load_lds_dwordx4 v[194:195], off
	s_waitcnt vmcnt(8)
	s_waitcnt lgkmcnt(0)
	s_barrier
	s_setprio 1
	s_waitcnt lgkmcnt(0)
	v_mfma_f32_16x16x32_bf16 v[152:155], v[112:115], v[160:163], 0
	v_mfma_f32_16x16x32_bf16 v[148:151], v[124:127], v[160:163], 0
	v_mfma_f32_16x16x32_bf16 v[108:111], v[112:115], v[168:171], 0
	v_mfma_f32_16x16x32_bf16 v[104:107], v[124:127], v[168:171], 0
	v_mfma_f32_16x16x32_bf16 v[92:95], v[112:115], v[176:179], 0
	v_mfma_f32_16x16x32_bf16 v[88:91], v[124:127], v[176:179], 0
	v_mfma_f32_16x16x32_bf16 v[76:79], v[112:115], v[184:187], 0
	v_mfma_f32_16x16x32_bf16 v[72:75], v[124:127], v[184:187], 0
	v_mfma_f32_16x16x32_bf16 v[152:155], v[120:123], v[164:167], v[152:155]
	v_mfma_f32_16x16x32_bf16 v[148:151], v[128:131], v[164:167], v[148:151]
	v_mfma_f32_16x16x32_bf16 v[108:111], v[120:123], v[172:175], v[108:111]
	v_mfma_f32_16x16x32_bf16 v[104:107], v[128:131], v[172:175], v[104:107]
	v_mfma_f32_16x16x32_bf16 v[92:95], v[120:123], v[180:183], v[92:95]
	v_mfma_f32_16x16x32_bf16 v[88:91], v[128:131], v[180:183], v[88:91]
	v_mfma_f32_16x16x32_bf16 v[76:79], v[120:123], v[188:191], v[76:79]
	v_mfma_f32_16x16x32_bf16 v[72:75], v[128:131], v[188:191], v[72:75]
	s_setprio 0
	s_setprio 1
	v_mfma_f32_16x16x32_bf16 v[132:135], v[136:139], v[160:163], 0
	v_mfma_f32_16x16x32_bf16 v[116:119], v[144:147], v[160:163], 0
	v_mfma_f32_16x16x32_bf16 v[100:103], v[136:139], v[168:171], 0
	v_mfma_f32_16x16x32_bf16 v[96:99], v[144:147], v[168:171], 0
	v_mfma_f32_16x16x32_bf16 v[84:87], v[136:139], v[176:179], 0
	v_mfma_f32_16x16x32_bf16 v[80:83], v[144:147], v[176:179], 0
	v_mfma_f32_16x16x32_bf16 v[68:71], v[136:139], v[184:187], 0
	v_mfma_f32_16x16x32_bf16 v[64:67], v[144:147], v[184:187], 0
	v_mfma_f32_16x16x32_bf16 v[132:135], v[140:143], v[164:167], v[132:135]
	v_mfma_f32_16x16x32_bf16 v[116:119], v[156:159], v[164:167], v[116:119]
	v_mfma_f32_16x16x32_bf16 v[100:103], v[140:143], v[172:175], v[100:103]
	v_mfma_f32_16x16x32_bf16 v[96:99], v[156:159], v[172:175], v[96:99]
	v_mfma_f32_16x16x32_bf16 v[84:87], v[140:143], v[180:183], v[84:87]
	v_mfma_f32_16x16x32_bf16 v[80:83], v[156:159], v[180:183], v[80:83]
	v_mfma_f32_16x16x32_bf16 v[68:71], v[140:143], v[188:191], v[68:71]
	v_mfma_f32_16x16x32_bf16 v[64:67], v[156:159], v[188:191], v[64:67]
	s_setprio 0
	s_barrier
	s_add_i32 s2, s2, s44
	v_lshl_add_u64 v[194:195], s[22:23], 0, v[192:193]
	s_mov_b32 m0, s2
	ds_read_b128 v[160:163], v251 offset:16384
	ds_read_b128 v[164:167], v251 offset:17408
	ds_read_b128 v[168:171], v251 offset:18432
	ds_read_b128 v[172:175], v251 offset:19456
	ds_read_b128 v[176:179], v251 offset:20480
	ds_read_b128 v[180:183], v251 offset:21504
	ds_read_b128 v[184:187], v251 offset:22528
	ds_read_b128 v[188:191], v251 offset:23552
	global_load_lds_dwordx4 v[194:195], off
	s_add_i32 m0, s2, 0x2000
	s_add_u32 s16, s22, 0xb0000
	v_lshl_add_u64 v[196:197], s[22:23], 0, v[198:199]
	s_addc_u32 s17, s23, 0
	s_add_i32 s2, s29, s44
	global_load_lds_dwordx4 v[196:197], off
	v_lshl_add_u64 v[208:209], s[16:17], 0, v[192:193]
	s_mov_b32 m0, s2
	v_lshl_add_u64 v[210:211], s[24:25], 0, v[200:201]
	global_load_lds_dwordx4 v[208:209], off
	v_lshl_add_u64 v[208:209], s[16:17], 0, v[198:199]
	s_add_i32 m0, s2, 0x2000
	s_nop 0
	global_load_lds_dwordx4 v[208:209], off
	v_lshl_add_u64 v[208:209], s[24:25], 0, v[202:203]
	s_mov_b32 m0, s45
	s_nop 0
	global_load_lds_dwordx4 v[208:209], off
	s_mov_b32 m0, s46
	s_nop 0
	global_load_lds_dwordx4 v[210:211], off
	s_waitcnt vmcnt(8)
	s_waitcnt lgkmcnt(0)
	s_barrier
; #define PG8_STAGE(bufoff, gbase, voff) do { _Pragma("unroll") for (int _i = 0; _i < 2; ++_i) \
;         __builtin_amdgcn_global_load_lds((const unsigned*)((const char*)(gbase) + (voff)[_i]), (PG8_LAS unsigned*)(lds + (bufoff) + ldsw + _i * 8192), 16, 0, 0); } while (0)
; #define PG8_LDA(dst, b, h) do { _Pragma("unroll") for (int m = 0; m < 4; ++m) _Pragma("unroll") for (int k = 0; k < 2; ++k) dst[m][k] = *(const PG8_LAS bf16x8*)(lds + PG8_SA(b, h) + aoff + m * 2048 + k * 1024); } while (0)
; #define PG8_LDB(dst, b, h) do { _Pragma("unroll") for (int n = 0; n < 2; ++n) _Pragma("unroll") for (int k = 0; k < 2; ++k) dst[n][k] = *(const PG8_LAS bf16x8*)(lds + PG8_SB(b, h) + boff + n * 2048 + k * 1024); } while (0)
; #define PG8_MMA(ai, bj, At, Bt) do { __builtin_amdgcn_s_setprio(1); _Pragma("unroll") for (int m = 0; m < 4; ++m) _Pragma("unroll") for (int n = 0; n < 2; ++n) _Pragma("unroll") for (int k = 0; k < 2; ++k) \
;         acc[ai][bj][m][n] = __builtin_amdgcn_mfma_f32_16x16x32_bf16(Bt[n][k], At[m][k], acc[ai][bj][m][n], 0, 0, 0); __builtin_amdgcn_s_setprio(0); } while (0)
; #define PG8_WAIT_V(n) asm volatile("s_waitcnt vmcnt(" #n ")" ::: "memory")
; #define PG8_WAIT_L(n) asm volatile("s_waitcnt lgkmcnt(" #n ")" ::: "memory")
; #define PG8_BAR __builtin_amdgcn_s_barrier()
; #define PG8_SCHED __builtin_amdgcn_sched_barrier(0)
; template <class Epi, class Sched, bool ALIGN_EPI = false, bool SP2 = false>
; __device__ __forceinline__ void gemm_phase(PG8_LAS unsigned char* lds, const Gemm g, const Sched& S, const Epi& E, int wave_in) {
;     ...
;             PG8_WAIT_V(8); PG8_WAIT_L(0); PG8_BAR; PG8_MMA(1, 0, At, B0); PG8_MMA(1, 1, At, B1); PG8_BAR; PG8_SCHED;
;             PG8_LDB(B0, 1, 0); PG8_LDB(B1, 1, 1); PG8_SCHED; PG8_LDA(At, 1, 0); PG8_STAGE(PG8_SA(0, 1), a2 + hstep, voffA);
;             PG8_WAIT_V(8); PG8_WAIT_L(0); PG8_BAR; PG8_MMA(0, 0, At, B0); PG8_MMA(0, 1, At, B1); PG8_BAR; PG8_SCHED;
	s_setprio 1
	s_waitcnt lgkmcnt(0)
	v_mfma_f32_16x16x32_bf16 v[60:63], v[112:115], v[160:163], 0
	v_mfma_f32_16x16x32_bf16 v[56:59], v[124:127], v[160:163], 0
	v_mfma_f32_16x16x32_bf16 v[44:47], v[112:115], v[168:171], 0
	v_mfma_f32_16x16x32_bf16 v[40:43], v[124:127], v[168:171], 0
	v_mfma_f32_16x16x32_bf16 v[28:31], v[112:115], v[176:179], 0
	v_mfma_f32_16x16x32_bf16 v[24:27], v[124:127], v[176:179], 0
	v_mfma_f32_16x16x32_bf16 v[12:15], v[112:115], v[184:187], 0
	v_mfma_f32_16x16x32_bf16 v[8:11], v[124:127], v[184:187], 0
	v_mfma_f32_16x16x32_bf16 v[60:63], v[120:123], v[164:167], v[60:63]
	v_mfma_f32_16x16x32_bf16 v[56:59], v[128:131], v[164:167], v[56:59]
	v_mfma_f32_16x16x32_bf16 v[44:47], v[120:123], v[172:175], v[44:47]
	v_mfma_f32_16x16x32_bf16 v[40:43], v[128:131], v[172:175], v[40:43]
	v_mfma_f32_16x16x32_bf16 v[28:31], v[120:123], v[180:183], v[28:31]
	v_mfma_f32_16x16x32_bf16 v[24:27], v[128:131], v[180:183], v[24:27]
	v_mfma_f32_16x16x32_bf16 v[12:15], v[120:123], v[188:191], v[12:15]
	v_mfma_f32_16x16x32_bf16 v[8:11], v[128:131], v[188:191], v[8:11]
	s_setprio 0
	s_setprio 1
	v_mfma_f32_16x16x32_bf16 v[52:55], v[136:139], v[160:163], 0
	v_mfma_f32_16x16x32_bf16 v[48:51], v[144:147], v[160:163], 0
	v_mfma_f32_16x16x32_bf16 v[36:39], v[136:139], v[168:171], 0
	v_mfma_f32_16x16x32_bf16 v[32:35], v[144:147], v[168:171], 0
	v_mfma_f32_16x16x32_bf16 v[20:23], v[136:139], v[176:179], 0
	v_mfma_f32_16x16x32_bf16 v[16:19], v[144:147], v[176:179], 0
	v_mfma_f32_16x16x32_bf16 v[4:7], v[136:139], v[184:187], 0
	v_mfma_f32_16x16x32_bf16 v[0:3], v[144:147], v[184:187], 0
	v_mfma_f32_16x16x32_bf16 v[52:55], v[140:143], v[164:167], v[52:55]
	v_mfma_f32_16x16x32_bf16 v[48:51], v[156:159], v[164:167], v[48:51]
	v_mfma_f32_16x16x32_bf16 v[36:39], v[140:143], v[172:175], v[36:39]
	v_mfma_f32_16x16x32_bf16 v[32:35], v[156:159], v[172:175], v[32:35]
	v_mfma_f32_16x16x32_bf16 v[20:23], v[140:143], v[180:183], v[20:23]
	v_mfma_f32_16x16x32_bf16 v[16:19], v[156:159], v[180:183], v[16:19]
	v_mfma_f32_16x16x32_bf16 v[4:7], v[140:143], v[188:191], v[4:7]
	v_mfma_f32_16x16x32_bf16 v[0:3], v[156:159], v[188:191], v[0:3]
	s_setprio 0
	s_barrier
	s_add_i32 s2, s65, 0x100
	s_add_i32 s29, s52, 0x100
	v_add_u32_e32 v128, s2, v249
	v_add_u32_e32 v156, s29, v249
	ds_read_b128 v[112:115], v128
	ds_read_b128 v[120:123], v128 offset:1024
	ds_read_b128 v[124:127], v128 offset:2048
	ds_read_b128 v[128:131], v128 offset:3072
	ds_read_b128 v[136:139], v156
	ds_read_b128 v[140:143], v156 offset:1024
	ds_read_b128 v[144:147], v156 offset:2048
	ds_read_b128 v[156:159], v156 offset:3072
	s_add_u32 s16, s24, 0xb0000
	s_addc_u32 s17, s25, 0
	s_mov_b32 m0, s47
	v_lshl_add_u64 v[212:213], s[16:17], 0, v[202:203]
	ds_read_b128 v[160:163], v251 offset:32768
	ds_read_b128 v[164:167], v251 offset:33792
	ds_read_b128 v[168:171], v251 offset:34816
	ds_read_b128 v[172:175], v251 offset:35840
	ds_read_b128 v[176:179], v251 offset:36864
	ds_read_b128 v[180:183], v251 offset:37888
	ds_read_b128 v[184:187], v251 offset:38912
	ds_read_b128 v[188:191], v251 offset:39936
	global_load_lds_dwordx4 v[212:213], off
	v_lshl_add_u64 v[212:213], s[16:17], 0, v[200:201]
	s_mov_b32 m0, s60
	s_nop 0
	global_load_lds_dwordx4 v[212:213], off
	s_waitcnt vmcnt(8)
	s_waitcnt lgkmcnt(0)
	s_barrier
	s_setprio 1
	s_waitcnt lgkmcnt(0)
	v_mfma_f32_16x16x32_bf16 v[152:155], v[112:115], v[160:163], v[152:155]
	v_mfma_f32_16x16x32_bf16 v[148:151], v[124:127], v[160:163], v[148:151]
	v_mfma_f32_16x16x32_bf16 v[108:111], v[112:115], v[168:171], v[108:111]
	v_mfma_f32_16x16x32_bf16 v[104:107], v[124:127], v[168:171], v[104:107]
	v_mfma_f32_16x16x32_bf16 v[92:95], v[112:115], v[176:179], v[92:95]
	v_mfma_f32_16x16x32_bf16 v[88:91], v[124:127], v[176:179], v[88:91]
	v_mfma_f32_16x16x32_bf16 v[76:79], v[112:115], v[184:187], v[76:79]
	v_mfma_f32_16x16x32_bf16 v[72:75], v[124:127], v[184:187], v[72:75]
	v_mfma_f32_16x16x32_bf16 v[152:155], v[120:123], v[164:167], v[152:155]
	v_mfma_f32_16x16x32_bf16 v[148:151], v[128:131], v[164:167], v[148:151]
	v_mfma_f32_16x16x32_bf16 v[108:111], v[120:123], v[172:175], v[108:111]
	v_mfma_f32_16x16x32_bf16 v[104:107], v[128:131], v[172:175], v[104:107]
	v_mfma_f32_16x16x32_bf16 v[92:95], v[120:123], v[180:183], v[92:95]
	v_mfma_f32_16x16x32_bf16 v[88:91], v[128:131], v[180:183], v[88:91]
	v_mfma_f32_16x16x32_bf16 v[76:79], v[120:123], v[188:191], v[76:79]
	v_mfma_f32_16x16x32_bf16 v[72:75], v[128:131], v[188:191], v[72:75]
	s_setprio 0
	s_setprio 1
	v_mfma_f32_16x16x32_bf16 v[132:135], v[136:139], v[160:163], v[132:135]
	v_mfma_f32_16x16x32_bf16 v[116:119], v[144:147], v[160:163], v[116:119]
	v_mfma_f32_16x16x32_bf16 v[100:103], v[136:139], v[168:171], v[100:103]
	v_mfma_f32_16x16x32_bf16 v[96:99], v[144:147], v[168:171], v[96:99]
	v_mfma_f32_16x16x32_bf16 v[84:87], v[136:139], v[176:179], v[84:87]
	v_mfma_f32_16x16x32_bf16 v[80:83], v[144:147], v[176:179], v[80:83]
	v_mfma_f32_16x16x32_bf16 v[68:71], v[136:139], v[184:187], v[68:71]
	v_mfma_f32_16x16x32_bf16 v[64:67], v[144:147], v[184:187], v[64:67]
	v_mfma_f32_16x16x32_bf16 v[132:135], v[140:143], v[164:167], v[132:135]
	v_mfma_f32_16x16x32_bf16 v[116:119], v[156:159], v[164:167], v[116:119]
	v_mfma_f32_16x16x32_bf16 v[100:103], v[140:143], v[172:175], v[100:103]
	v_mfma_f32_16x16x32_bf16 v[96:99], v[156:159], v[172:175], v[96:99]
	v_mfma_f32_16x16x32_bf16 v[84:87], v[140:143], v[180:183], v[84:87]
	v_mfma_f32_16x16x32_bf16 v[80:83], v[156:159], v[180:183], v[80:83]
	v_mfma_f32_16x16x32_bf16 v[68:71], v[140:143], v[188:191], v[68:71]
	v_mfma_f32_16x16x32_bf16 v[64:67], v[156:159], v[188:191], v[64:67]
	s_setprio 0
	s_barrier
; #define PG8_STAGE(bufoff, gbase, voff) do { _Pragma("unroll") for (int _i = 0; _i < 2; ++_i) \
;         __builtin_amdgcn_global_load_lds((const unsigned*)((const char*)(gbase) + (voff)[_i]), (PG8_LAS unsigned*)(lds + (bufoff) + ldsw + _i * 8192), 16, 0, 0); } while (0)
; #define PG8_LDA(dst, b, h) do { _Pragma("unroll") for (int m = 0; m < 4; ++m) _Pragma("unroll") for (int k = 0; k < 2; ++k) dst[m][k] = *(const PG8_LAS bf16x8*)(lds + PG8_SA(b, h) + aoff + m * 2048 + k * 1024); } while (0)
; #define PG8_WAIT_V(n) asm volatile("s_waitcnt vmcnt(" #n ")" ::: "memory")
; #define PG8_WAIT_L(n) asm volatile("s_waitcnt lgkmcnt(" #n ")" ::: "memory")
; #define PG8_BAR __builtin_amdgcn_s_barrier()
; template <class Epi, class Sched, bool ALIGN_EPI = false, bool SP2 = false>
; __device__ __forceinline__ void gemm_phase(PG8_LAS unsigned char* lds, const Gemm g, const Sched& S, const Epi& E, int wave_in) {
;     ...
;         for (int t = 0; t < nt; t += 2) {
;             const bool last = (t == nt - 2);
;             const char* a1 = cA + (size_t)(t + 1) * kstep;
;             const char* a2 = last ? nA : cA + (size_t)(t + 2) * kstep; const char* b2 = last ? nB : cB + (size_t)(t + 2) * kstep;
;             const char* a3 = a2 + kstep; const char* b3 = b2 + kstep;
;             if (last && has_next) S.a_ready(nxt);
;             if constexpr (SP2) {
;             PG8_LDB(B0, 0, 0); PG8_LDB(B1, 0, 1); PG8_SCHED; PG8_LDA(At, 0, 0); PG8_STAGE(PG8_SA(1, 1), a1 + hstep, voffA);
;             PG8_WAIT_V(8); PG8_WAIT_L(0); PG8_BAR; PG8_MMA(0, 0, At, B0); PG8_MMA(0, 1, At, B1); PG8_BAR; PG8_SCHED;
;             PG8_LDA(At, 0, 1); PG8_STAGE(PG8_SB(0, 0), b2, voffB); PG8_STAGE(PG8_SB(0, 1), b2 + hstep, voffB); PG8_STAGE(PG8_SA(0, 0), a2, voffA);
;             PG8_WAIT_V(8); PG8_WAIT_L(0); PG8_BAR; PG8_MMA(1, 0, At, B0); PG8_MMA(1, 1, At, B1); PG8_BAR; PG8_SCHED;
;             PG8_LDB(B0, 1, 0); PG8_LDB(B1, 1, 1); PG8_SCHED; PG8_LDA(At, 1, 0); PG8_STAGE(PG8_SA(0, 1), a2 + hstep, voffA);
;             PG8_WAIT_V(8); PG8_WAIT_L(0); PG8_BAR; PG8_MMA(0, 0, At, B0); PG8_MMA(0, 1, At, B1); PG8_BAR; PG8_SCHED;
;             PG8_LDA(At, 1, 1); PG8_STAGE(PG8_SB(1, 0), b3, voffB); PG8_STAGE(PG8_SB(1, 1), b3 + hstep, voffB); PG8_STAGE(PG8_SA(1, 0), a3, voffA);
;             PG8_WAIT_V(8); PG8_WAIT_L(0); PG8_BAR; PG8_MMA(1, 0, At, B0); PG8_MMA(1, 1, At, B1); PG8_BAR; PG8_SCHED;
	s_add_i32 s2, s2, s44
	v_lshl_add_u64 v[194:195], v[194:195], 0, s[88:89]
	s_mov_b32 m0, s2
	ds_read_b128 v[160:163], v251 offset:49152
	ds_read_b128 v[164:167], v251 offset:50176
	ds_read_b128 v[168:171], v251 offset:51200
	ds_read_b128 v[172:175], v251 offset:52224
	ds_read_b128 v[176:179], v251 offset:53248
	ds_read_b128 v[180:183], v251 offset:54272
	ds_read_b128 v[184:187], v251 offset:55296
	ds_read_b128 v[188:191], v251 offset:56320
	global_load_lds_dwordx4 v[194:195], off
	s_add_i32 m0, s2, 0x2000
	s_add_u32 s16, s22, 0xb0080
	v_lshl_add_u64 v[194:195], v[196:197], 0, s[88:89]
	s_addc_u32 s17, s23, 0
	s_add_i32 s2, s29, s44
	global_load_lds_dwordx4 v[194:195], off
	v_lshl_add_u64 v[194:195], s[16:17], 0, v[192:193]
	s_mov_b32 m0, s2
	s_nop 0
	global_load_lds_dwordx4 v[194:195], off
	v_lshl_add_u64 v[194:195], s[16:17], 0, v[198:199]
	s_add_i32 m0, s2, 0x2000
	s_nop 0
	global_load_lds_dwordx4 v[194:195], off
	v_lshl_add_u64 v[194:195], v[208:209], 0, s[88:89]
	s_mov_b32 m0, s62
	s_nop 0
	global_load_lds_dwordx4 v[194:195], off
	v_lshl_add_u64 v[194:195], v[210:211], 0, s[88:89]
	s_mov_b32 m0, s63
	s_nop 0
	global_load_lds_dwordx4 v[194:195], off
	s_waitcnt vmcnt(8)
	s_waitcnt lgkmcnt(0)
	s_barrier
	s_setprio 1
	s_waitcnt lgkmcnt(0)
	v_mfma_f32_16x16x32_bf16 v[60:63], v[112:115], v[160:163], v[60:63]
	v_mfma_f32_16x16x32_bf16 v[56:59], v[124:127], v[160:163], v[56:59]
	v_mfma_f32_16x16x32_bf16 v[44:47], v[112:115], v[168:171], v[44:47]
	v_mfma_f32_16x16x32_bf16 v[40:43], v[124:127], v[168:171], v[40:43]
	v_mfma_f32_16x16x32_bf16 v[28:31], v[112:115], v[176:179], v[28:31]
	v_mfma_f32_16x16x32_bf16 v[24:27], v[124:127], v[176:179], v[24:27]
	v_mfma_f32_16x16x32_bf16 v[12:15], v[112:115], v[184:187], v[12:15]
	v_mfma_f32_16x16x32_bf16 v[8:11], v[124:127], v[184:187], v[8:11]
	v_mfma_f32_16x16x32_bf16 v[60:63], v[120:123], v[164:167], v[60:63]
	v_mfma_f32_16x16x32_bf16 v[56:59], v[128:131], v[164:167], v[56:59]
	v_mfma_f32_16x16x32_bf16 v[44:47], v[120:123], v[172:175], v[44:47]
	v_mfma_f32_16x16x32_bf16 v[40:43], v[128:131], v[172:175], v[40:43]
	v_mfma_f32_16x16x32_bf16 v[28:31], v[120:123], v[180:183], v[28:31]
	v_mfma_f32_16x16x32_bf16 v[24:27], v[128:131], v[180:183], v[24:27]
	v_mfma_f32_16x16x32_bf16 v[12:15], v[120:123], v[188:191], v[12:15]
	v_mfma_f32_16x16x32_bf16 v[8:11], v[128:131], v[188:191], v[8:11]
	s_setprio 0
	s_setprio 1
	v_mfma_f32_16x16x32_bf16 v[52:55], v[136:139], v[160:163], v[52:55]
	v_mfma_f32_16x16x32_bf16 v[48:51], v[144:147], v[160:163], v[48:51]
	v_mfma_f32_16x16x32_bf16 v[36:39], v[136:139], v[168:171], v[36:39]
	v_mfma_f32_16x16x32_bf16 v[32:35], v[144:147], v[168:171], v[32:35]
	v_mfma_f32_16x16x32_bf16 v[20:23], v[136:139], v[176:179], v[20:23]
	v_mfma_f32_16x16x32_bf16 v[16:19], v[144:147], v[176:179], v[16:19]
	v_mfma_f32_16x16x32_bf16 v[4:7], v[136:139], v[184:187], v[4:7]
	v_mfma_f32_16x16x32_bf16 v[0:3], v[144:147], v[184:187], v[0:3]
	v_mfma_f32_16x16x32_bf16 v[52:55], v[140:143], v[164:167], v[52:55]
	v_mfma_f32_16x16x32_bf16 v[48:51], v[156:159], v[164:167], v[48:51]
	v_mfma_f32_16x16x32_bf16 v[36:39], v[140:143], v[172:175], v[36:39]
	v_mfma_f32_16x16x32_bf16 v[32:35], v[156:159], v[172:175], v[32:35]
	v_mfma_f32_16x16x32_bf16 v[20:23], v[140:143], v[180:183], v[20:23]
	v_mfma_f32_16x16x32_bf16 v[16:19], v[156:159], v[180:183], v[16:19]
	v_mfma_f32_16x16x32_bf16 v[4:7], v[140:143], v[188:191], v[4:7]
	v_mfma_f32_16x16x32_bf16 v[0:3], v[156:159], v[188:191], v[0:3]
	s_setprio 0
	s_add_i32 s43, s43, 2
	s_add_u32 s34, s34, 0x100
	s_addc_u32 s42, s42, 0
	s_cmp_gt_u32 s43, 41
	s_mov_b64 s[16:17], s[20:21]
	s_cbranch_scc1 .Lxbar_7
	s_add_u32 s20, s16, 0x100
	s_addc_u32 s21, s17, 0
	s_add_i32 s2, s35, 0x100
	s_cmp_eq_u32 s43, 40
	s_cselect_b32 s25, s13, s21
	s_cselect_b32 s24, s12, s20
	s_cselect_b32 s23, s15, s42
	s_cselect_b32 s22, s14, s34
	s_add_i32 s29, s90, 0x100

; #define PG8_STAGE(bufoff, gbase, voff) do { _Pragma("unroll") for (int _i = 0; _i < 2; ++_i) \
;         __builtin_amdgcn_global_load_lds((const unsigned*)((const char*)(gbase) + (voff)[_i]), (PG8_LAS unsigned*)(lds + (bufoff) + ldsw + _i * 8192), 16, 0, 0); } while (0)
; #define PG8_LDA(dst, b, h) do { _Pragma("unroll") for (int m = 0; m < 4; ++m) _Pragma("unroll") for (int k = 0; k < 2; ++k) dst[m][k] = *(const PG8_LAS bf16x8*)(lds + PG8_SA(b, h) + aoff + m * 2048 + k * 1024); } while (0)
; #define PG8_LDB(dst, b, h) do { _Pragma("unroll") for (int n = 0; n < 2; ++n) _Pragma("unroll") for (int k = 0; k < 2; ++k) dst[n][k] = *(const PG8_LAS bf16x8*)(lds + PG8_SB(b, h) + boff + n * 2048 + k * 1024); } while (0)
; #define PG8_MMA(ai, bj, At, Bt) do { __builtin_amdgcn_s_setprio(1); _Pragma("unroll") for (int m = 0; m < 4; ++m) _Pragma("unroll") for (int n = 0; n < 2; ++n) _Pragma("unroll") for (int k = 0; k < 2; ++k) \
;         acc[ai][bj][m][n] = __builtin_amdgcn_mfma_f32_16x16x32_bf16(Bt[n][k], At[m][k], acc[ai][bj][m][n], 0, 0, 0); __builtin_amdgcn_s_setprio(0); } while (0)
; #define PG8_WAIT_V(n) asm volatile("s_waitcnt vmcnt(" #n ")" ::: "memory")
; #define PG8_WAIT_L(n) asm volatile("s_waitcnt lgkmcnt(" #n ")" ::: "memory")
; #define PG8_BAR __builtin_amdgcn_s_barrier()
; #define PG8_SCHED __builtin_amdgcn_sched_barrier(0)
; template <class Epi, class Sched, bool ALIGN_EPI = false, bool SP2 = false>
; __device__ __forceinline__ void gemm_phase(PG8_LAS unsigned char* lds, const Gemm g, const Sched& S, const Epi& E, int wave_in) {
;     ...
;             PG8_LDB(B0, 0, 0); PG8_LDB(B1, 0, 1); PG8_SCHED; PG8_LDA(At, 0, 0); PG8_STAGE(PG8_SA(1, 1), a1 + hstep, voffA);
;             PG8_WAIT_V(8); PG8_WAIT_L(0); PG8_BAR; PG8_MMA(0, 0, At, B0); PG8_MMA(0, 1, At, B1); PG8_BAR; PG8_SCHED;
;             PG8_LDA(At, 0, 1); PG8_STAGE(PG8_SB(0, 0), b2, voffB); PG8_STAGE(PG8_SB(0, 1), b2 + hstep, voffB); PG8_STAGE(PG8_SA(0, 0), a2, voffA);
.LBB0_1031:
	v_add_u32_e32 v128, s2, v249
	v_add_u32_e32 v156, s29, v249
	ds_read_b128 v[112:115], v128
	ds_read_b128 v[120:123], v128 offset:1024
	ds_read_b128 v[124:127], v128 offset:2048
	ds_read_b128 v[128:131], v128 offset:3072
	ds_read_b128 v[136:139], v156
	ds_read_b128 v[140:143], v156 offset:1024
	ds_read_b128 v[144:147], v156 offset:2048
	ds_read_b128 v[156:159], v156 offset:3072
	v_lshl_add_u64 v[194:195], s[16:17], 0, v[206:207]
	s_add_i32 m0, s45, 0xc000
	ds_read_b128 v[160:163], v251
	ds_read_b128 v[164:167], v251 offset:1024
	ds_read_b128 v[168:171], v251 offset:2048
	ds_read_b128 v[172:175], v251 offset:3072
	ds_read_b128 v[176:179], v251 offset:4096
	ds_read_b128 v[180:183], v251 offset:5120
	ds_read_b128 v[184:187], v251 offset:6144
	ds_read_b128 v[188:191], v251 offset:7168
	global_load_lds_dwordx4 v[194:195], off
	v_lshl_add_u64 v[194:195], s[16:17], 0, v[204:205]
	s_add_i32 m0, s45, 0xe000
	s_nop 0
	global_load_lds_dwordx4 v[194:195], off
	s_waitcnt vmcnt(8)
	s_waitcnt lgkmcnt(0)
	s_barrier
	s_setprio 1
	s_waitcnt lgkmcnt(0)
	v_mfma_f32_16x16x32_bf16 v[152:155], v[112:115], v[160:163], v[152:155]
	v_mfma_f32_16x16x32_bf16 v[148:151], v[124:127], v[160:163], v[148:151]
	v_mfma_f32_16x16x32_bf16 v[108:111], v[112:115], v[168:171], v[108:111]
	v_mfma_f32_16x16x32_bf16 v[104:107], v[124:127], v[168:171], v[104:107]
	v_mfma_f32_16x16x32_bf16 v[92:95], v[112:115], v[176:179], v[92:95]
	v_mfma_f32_16x16x32_bf16 v[88:91], v[124:127], v[176:179], v[88:91]
	v_mfma_f32_16x16x32_bf16 v[76:79], v[112:115], v[184:187], v[76:79]
	v_mfma_f32_16x16x32_bf16 v[72:75], v[124:127], v[184:187], v[72:75]
	v_mfma_f32_16x16x32_bf16 v[152:155], v[120:123], v[164:167], v[152:155]
	v_mfma_f32_16x16x32_bf16 v[148:151], v[128:131], v[164:167], v[148:151]
	v_mfma_f32_16x16x32_bf16 v[108:111], v[120:123], v[172:175], v[108:111]
	v_mfma_f32_16x16x32_bf16 v[104:107], v[128:131], v[172:175], v[104:107]
	v_mfma_f32_16x16x32_bf16 v[92:95], v[120:123], v[180:183], v[92:95]
	v_mfma_f32_16x16x32_bf16 v[88:91], v[128:131], v[180:183], v[88:91]
	v_mfma_f32_16x16x32_bf16 v[76:79], v[120:123], v[188:191], v[76:79]
	v_mfma_f32_16x16x32_bf16 v[72:75], v[128:131], v[188:191], v[72:75]
	s_setprio 0
	s_setprio 1
	v_mfma_f32_16x16x32_bf16 v[132:135], v[136:139], v[160:163], v[132:135]
	v_mfma_f32_16x16x32_bf16 v[116:119], v[144:147], v[160:163], v[116:119]
	v_mfma_f32_16x16x32_bf16 v[100:103], v[136:139], v[168:171], v[100:103]
	v_mfma_f32_16x16x32_bf16 v[96:99], v[144:147], v[168:171], v[96:99]
	v_mfma_f32_16x16x32_bf16 v[84:87], v[136:139], v[176:179], v[84:87]
	v_mfma_f32_16x16x32_bf16 v[80:83], v[144:147], v[176:179], v[80:83]
	v_mfma_f32_16x16x32_bf16 v[68:71], v[136:139], v[184:187], v[68:71]
	v_mfma_f32_16x16x32_bf16 v[64:67], v[144:147], v[184:187], v[64:67]
	v_mfma_f32_16x16x32_bf16 v[132:135], v[140:143], v[164:167], v[132:135]
	v_mfma_f32_16x16x32_bf16 v[116:119], v[156:159], v[164:167], v[116:119]
	v_mfma_f32_16x16x32_bf16 v[100:103], v[140:143], v[172:175], v[100:103]
	v_mfma_f32_16x16x32_bf16 v[96:99], v[156:159], v[172:175], v[96:99]
	v_mfma_f32_16x16x32_bf16 v[84:87], v[140:143], v[180:183], v[84:87]
	v_mfma_f32_16x16x32_bf16 v[80:83], v[156:159], v[180:183], v[80:83]
	v_mfma_f32_16x16x32_bf16 v[68:71], v[140:143], v[188:191], v[68:71]
	v_mfma_f32_16x16x32_bf16 v[64:67], v[156:159], v[188:191], v[64:67]
	s_setprio 0
	s_barrier
	s_add_i32 s2, s2, s44
	v_lshl_add_u64 v[194:195], s[22:23], 0, v[192:193]
	s_mov_b32 m0, s2
	ds_read_b128 v[160:163], v251 offset:16384
	ds_read_b128 v[164:167], v251 offset:17408
	ds_read_b128 v[168:171], v251 offset:18432
	ds_read_b128 v[172:175], v251 offset:19456
	ds_read_b128 v[176:179], v251 offset:20480
	ds_read_b128 v[180:183], v251 offset:21504
	ds_read_b128 v[184:187], v251 offset:22528
	ds_read_b128 v[188:191], v251 offset:23552
	global_load_lds_dwordx4 v[194:195], off
	s_add_i32 m0, s2, 0x2000
	s_add_u32 s16, s22, 0xb0000
	v_lshl_add_u64 v[196:197], s[22:23], 0, v[198:199]
	s_addc_u32 s17, s23, 0
	s_add_i32 s2, s29, s44
	global_load_lds_dwordx4 v[196:197], off
	v_lshl_add_u64 v[208:209], s[16:17], 0, v[192:193]
	s_mov_b32 m0, s2
	v_lshl_add_u64 v[210:211], s[24:25], 0, v[200:201]
	global_load_lds_dwordx4 v[208:209], off
	v_lshl_add_u64 v[208:209], s[16:17], 0, v[198:199]
	s_add_i32 m0, s2, 0x2000
	s_nop 0
	global_load_lds_dwordx4 v[208:209], off
	v_lshl_add_u64 v[208:209], s[24:25], 0, v[202:203]
	s_mov_b32 m0, s45
	s_nop 0
	global_load_lds_dwordx4 v[208:209], off
	s_mov_b32 m0, s46
	s_nop 0
	global_load_lds_dwordx4 v[210:211], off
	s_waitcnt vmcnt(8)
	s_waitcnt lgkmcnt(0)
	s_barrier
; #define PG8_STAGE(bufoff, gbase, voff) do { _Pragma("unroll") for (int _i = 0; _i < 2; ++_i) \
;         __builtin_amdgcn_global_load_lds((const unsigned*)((const char*)(gbase) + (voff)[_i]), (PG8_LAS unsigned*)(lds + (bufoff) + ldsw + _i * 8192), 16, 0, 0); } while (0)
; #define PG8_LDA(dst, b, h) do { _Pragma("unroll") for (int m = 0; m < 4; ++m) _Pragma("unroll") for (int k = 0; k < 2; ++k) dst[m][k] = *(const PG8_LAS bf16x8*)(lds + PG8_SA(b, h) + aoff + m * 2048 + k * 1024); } while (0)
; #define PG8_LDB(dst, b, h) do { _Pragma("unroll") for (int n = 0; n < 2; ++n) _Pragma("unroll") for (int k = 0; k < 2; ++k) dst[n][k] = *(const PG8_LAS bf16x8*)(lds + PG8_SB(b, h) + boff + n * 2048 + k * 1024); } while (0)
; #define PG8_MMA(ai, bj, At, Bt) do { __builtin_amdgcn_s_setprio(1); _Pragma("unroll") for (int m = 0; m < 4; ++m) _Pragma("unroll") for (int n = 0; n < 2; ++n) _Pragma("unroll") for (int k = 0; k < 2; ++k) \
;         acc[ai][bj][m][n] = __builtin_amdgcn_mfma_f32_16x16x32_bf16(Bt[n][k], At[m][k], acc[ai][bj][m][n], 0, 0, 0); __builtin_amdgcn_s_setprio(0); } while (0)
; #define PG8_WAIT_V(n) asm volatile("s_waitcnt vmcnt(" #n ")" ::: "memory")
; #define PG8_WAIT_L(n) asm volatile("s_waitcnt lgkmcnt(" #n ")" ::: "memory")
; #define PG8_BAR __builtin_amdgcn_s_barrier()
; #define PG8_SCHED __builtin_amdgcn_sched_barrier(0)
; template <class Epi, class Sched, bool ALIGN_EPI = false, bool SP2 = false>
; __device__ __forceinline__ void gemm_phase(PG8_LAS unsigned char* lds, const Gemm g, const Sched& S, const Epi& E, int wave_in) {
;     ...
;             PG8_WAIT_V(8); PG8_WAIT_L(0); PG8_BAR; PG8_MMA(1, 0, At, B0); PG8_MMA(1, 1, At, B1); PG8_BAR; PG8_SCHED;
;             PG8_LDB(B0, 1, 0); PG8_LDB(B1, 1, 1); PG8_SCHED; PG8_LDA(At, 1, 0); PG8_STAGE(PG8_SA(0, 1), a2 + hstep, voffA);
;             PG8_WAIT_V(8); PG8_WAIT_L(0); PG8_BAR; PG8_MMA(0, 0, At, B0); PG8_MMA(0, 1, At, B1); PG8_BAR; PG8_SCHED;
	s_setprio 1
	s_waitcnt lgkmcnt(0)
	v_mfma_f32_16x16x32_bf16 v[60:63], v[112:115], v[160:163], v[60:63]
	v_mfma_f32_16x16x32_bf16 v[56:59], v[124:127], v[160:163], v[56:59]
	v_mfma_f32_16x16x32_bf16 v[44:47], v[112:115], v[168:171], v[44:47]
	v_mfma_f32_16x16x32_bf16 v[40:43], v[124:127], v[168:171], v[40:43]
	v_mfma_f32_16x16x32_bf16 v[28:31], v[112:115], v[176:179], v[28:31]
	v_mfma_f32_16x16x32_bf16 v[24:27], v[124:127], v[176:179], v[24:27]
	v_mfma_f32_16x16x32_bf16 v[12:15], v[112:115], v[184:187], v[12:15]
	v_mfma_f32_16x16x32_bf16 v[8:11], v[124:127], v[184:187], v[8:11]
	v_mfma_f32_16x16x32_bf16 v[60:63], v[120:123], v[164:167], v[60:63]
	v_mfma_f32_16x16x32_bf16 v[56:59], v[128:131], v[164:167], v[56:59]
	v_mfma_f32_16x16x32_bf16 v[44:47], v[120:123], v[172:175], v[44:47]
	v_mfma_f32_16x16x32_bf16 v[40:43], v[128:131], v[172:175], v[40:43]
	v_mfma_f32_16x16x32_bf16 v[28:31], v[120:123], v[180:183], v[28:31]
	v_mfma_f32_16x16x32_bf16 v[24:27], v[128:131], v[180:183], v[24:27]
	v_mfma_f32_16x16x32_bf16 v[12:15], v[120:123], v[188:191], v[12:15]
	v_mfma_f32_16x16x32_bf16 v[8:11], v[128:131], v[188:191], v[8:11]
	s_setprio 0
	s_setprio 1
	v_mfma_f32_16x16x32_bf16 v[52:55], v[136:139], v[160:163], v[52:55]
	v_mfma_f32_16x16x32_bf16 v[48:51], v[144:147], v[160:163], v[48:51]
	v_mfma_f32_16x16x32_bf16 v[36:39], v[136:139], v[168:171], v[36:39]
	v_mfma_f32_16x16x32_bf16 v[32:35], v[144:147], v[168:171], v[32:35]
	v_mfma_f32_16x16x32_bf16 v[20:23], v[136:139], v[176:179], v[20:23]
	v_mfma_f32_16x16x32_bf16 v[16:19], v[144:147], v[176:179], v[16:19]
	v_mfma_f32_16x16x32_bf16 v[4:7], v[136:139], v[184:187], v[4:7]
	v_mfma_f32_16x16x32_bf16 v[0:3], v[144:147], v[184:187], v[0:3]
	v_mfma_f32_16x16x32_bf16 v[52:55], v[140:143], v[164:167], v[52:55]
	v_mfma_f32_16x16x32_bf16 v[48:51], v[156:159], v[164:167], v[48:51]
	v_mfma_f32_16x16x32_bf16 v[36:39], v[140:143], v[172:175], v[36:39]
	v_mfma_f32_16x16x32_bf16 v[32:35], v[156:159], v[172:175], v[32:35]
	v_mfma_f32_16x16x32_bf16 v[20:23], v[140:143], v[180:183], v[20:23]
	v_mfma_f32_16x16x32_bf16 v[16:19], v[156:159], v[180:183], v[16:19]
	v_mfma_f32_16x16x32_bf16 v[4:7], v[140:143], v[188:191], v[4:7]
	v_mfma_f32_16x16x32_bf16 v[0:3], v[156:159], v[188:191], v[0:3]
	s_setprio 0
	s_barrier
	s_add_i32 s2, s65, 0x100
	s_add_i32 s29, s52, 0x100
	v_add_u32_e32 v128, s2, v249
	v_add_u32_e32 v156, s29, v249
	ds_read_b128 v[112:115], v128
	ds_read_b128 v[120:123], v128 offset:1024
	ds_read_b128 v[124:127], v128 offset:2048
	ds_read_b128 v[128:131], v128 offset:3072
	ds_read_b128 v[136:139], v156
	ds_read_b128 v[140:143], v156 offset:1024
	ds_read_b128 v[144:147], v156 offset:2048
	ds_read_b128 v[156:159], v156 offset:3072
	s_add_u32 s16, s24, 0xb0000
	s_addc_u32 s17, s25, 0
	s_mov_b32 m0, s47
	v_lshl_add_u64 v[212:213], s[16:17], 0, v[202:203]
	ds_read_b128 v[160:163], v251 offset:32768
	ds_read_b128 v[164:167], v251 offset:33792
	ds_read_b128 v[168:171], v251 offset:34816
	ds_read_b128 v[172:175], v251 offset:35840
	ds_read_b128 v[176:179], v251 offset:36864
	ds_read_b128 v[180:183], v251 offset:37888
	ds_read_b128 v[184:187], v251 offset:38912
	ds_read_b128 v[188:191], v251 offset:39936
	global_load_lds_dwordx4 v[212:213], off
	v_lshl_add_u64 v[212:213], s[16:17], 0, v[200:201]
	s_mov_b32 m0, s60
	s_nop 0
	global_load_lds_dwordx4 v[212:213], off
	s_waitcnt vmcnt(8)
	s_waitcnt lgkmcnt(0)
	s_barrier
	s_setprio 1
	s_waitcnt lgkmcnt(0)
	v_mfma_f32_16x16x32_bf16 v[152:155], v[112:115], v[160:163], v[152:155]
	v_mfma_f32_16x16x32_bf16 v[148:151], v[124:127], v[160:163], v[148:151]
	v_mfma_f32_16x16x32_bf16 v[108:111], v[112:115], v[168:171], v[108:111]
	v_mfma_f32_16x16x32_bf16 v[104:107], v[124:127], v[168:171], v[104:107]
	v_mfma_f32_16x16x32_bf16 v[92:95], v[112:115], v[176:179], v[92:95]
	v_mfma_f32_16x16x32_bf16 v[88:91], v[124:127], v[176:179], v[88:91]
	v_mfma_f32_16x16x32_bf16 v[76:79], v[112:115], v[184:187], v[76:79]
	v_mfma_f32_16x16x32_bf16 v[72:75], v[124:127], v[184:187], v[72:75]
	v_mfma_f32_16x16x32_bf16 v[152:155], v[120:123], v[164:167], v[152:155]
	v_mfma_f32_16x16x32_bf16 v[148:151], v[128:131], v[164:167], v[148:151]
	v_mfma_f32_16x16x32_bf16 v[108:111], v[120:123], v[172:175], v[108:111]
	v_mfma_f32_16x16x32_bf16 v[104:107], v[128:131], v[172:175], v[104:107]
	v_mfma_f32_16x16x32_bf16 v[92:95], v[120:123], v[180:183], v[92:95]
	v_mfma_f32_16x16x32_bf16 v[88:91], v[128:131], v[180:183], v[88:91]
	v_mfma_f32_16x16x32_bf16 v[76:79], v[120:123], v[188:191], v[76:79]
	v_mfma_f32_16x16x32_bf16 v[72:75], v[128:131], v[188:191], v[72:75]
	s_setprio 0
	s_setprio 1
	v_mfma_f32_16x16x32_bf16 v[132:135], v[136:139], v[160:163], v[132:135]
	v_mfma_f32_16x16x32_bf16 v[116:119], v[144:147], v[160:163], v[116:119]
	v_mfma_f32_16x16x32_bf16 v[100:103], v[136:139], v[168:171], v[100:103]
	v_mfma_f32_16x16x32_bf16 v[96:99], v[144:147], v[168:171], v[96:99]
	v_mfma_f32_16x16x32_bf16 v[84:87], v[136:139], v[176:179], v[84:87]
	v_mfma_f32_16x16x32_bf16 v[80:83], v[144:147], v[176:179], v[80:83]
	v_mfma_f32_16x16x32_bf16 v[68:71], v[136:139], v[184:187], v[68:71]
	v_mfma_f32_16x16x32_bf16 v[64:67], v[144:147], v[184:187], v[64:67]
	v_mfma_f32_16x16x32_bf16 v[132:135], v[140:143], v[164:167], v[132:135]
	v_mfma_f32_16x16x32_bf16 v[116:119], v[156:159], v[164:167], v[116:119]
	v_mfma_f32_16x16x32_bf16 v[100:103], v[140:143], v[172:175], v[100:103]
	v_mfma_f32_16x16x32_bf16 v[96:99], v[156:159], v[172:175], v[96:99]
	v_mfma_f32_16x16x32_bf16 v[84:87], v[140:143], v[180:183], v[84:87]
	v_mfma_f32_16x16x32_bf16 v[80:83], v[156:159], v[180:183], v[80:83]
	v_mfma_f32_16x16x32_bf16 v[68:71], v[140:143], v[188:191], v[68:71]
	v_mfma_f32_16x16x32_bf16 v[64:67], v[156:159], v[188:191], v[64:67]
	s_setprio 0
	s_barrier
; #define PG8_STAGE(bufoff, gbase, voff) do { _Pragma("unroll") for (int _i = 0; _i < 2; ++_i) \
;         __builtin_amdgcn_global_load_lds((const unsigned*)((const char*)(gbase) + (voff)[_i]), (PG8_LAS unsigned*)(lds + (bufoff) + ldsw + _i * 8192), 16, 0, 0); } while (0)
; #define PG8_LDA(dst, b, h) do { _Pragma("unroll") for (int m = 0; m < 4; ++m) _Pragma("unroll") for (int k = 0; k < 2; ++k) dst[m][k] = *(const PG8_LAS bf16x8*)(lds + PG8_SA(b, h) + aoff + m * 2048 + k * 1024); } while (0)
; #define PG8_MMA(ai, bj, At, Bt) do { __builtin_amdgcn_s_setprio(1); _Pragma("unroll") for (int m = 0; m < 4; ++m) _Pragma("unroll") for (int n = 0; n < 2; ++n) _Pragma("unroll") for (int k = 0; k < 2; ++k) \
;         acc[ai][bj][m][n] = __builtin_amdgcn_mfma_f32_16x16x32_bf16(Bt[n][k], At[m][k], acc[ai][bj][m][n], 0, 0, 0); __builtin_amdgcn_s_setprio(0); } while (0)
; #define PG8_WAIT_V(n) asm volatile("s_waitcnt vmcnt(" #n ")" ::: "memory")
; #define PG8_WAIT_L(n) asm volatile("s_waitcnt lgkmcnt(" #n ")" ::: "memory")
; #define PG8_BAR __builtin_amdgcn_s_barrier()
; #define PG8_SCHED __builtin_amdgcn_sched_barrier(0)
; template <class Epi, class Sched, bool ALIGN_EPI = false, bool SP2 = false>
; __device__ __forceinline__ void gemm_phase(PG8_LAS unsigned char* lds, const Gemm g, const Sched& S, const Epi& E, int wave_in) {
;     ...
;         for (int t = 0; t < nt; t += 2) {
;             const bool last = (t == nt - 2);
;             const char* a1 = cA + (size_t)(t + 1) * kstep;
;             const char* a2 = last ? nA : cA + (size_t)(t + 2) * kstep; const char* b2 = last ? nB : cB + (size_t)(t + 2) * kstep;
;             const char* a3 = a2 + kstep; const char* b3 = b2 + kstep;
;             if (last && has_next) S.a_ready(nxt);
;     ...
;             PG8_LDA(At, 1, 1); PG8_STAGE(PG8_SB(1, 0), b3, voffB); PG8_STAGE(PG8_SB(1, 1), b3 + hstep, voffB); PG8_STAGE(PG8_SA(1, 0), a3, voffA);
;             PG8_WAIT_V(8); PG8_WAIT_L(0); PG8_BAR; PG8_MMA(1, 0, At, B0); PG8_MMA(1, 1, At, B1); PG8_BAR; PG8_SCHED;
	s_add_i32 s2, s2, s44
	v_lshl_add_u64 v[194:195], v[194:195], 0, s[88:89]
	s_mov_b32 m0, s2
	ds_read_b128 v[160:163], v251 offset:49152
	ds_read_b128 v[164:167], v251 offset:50176
	ds_read_b128 v[168:171], v251 offset:51200
	ds_read_b128 v[172:175], v251 offset:52224
	ds_read_b128 v[176:179], v251 offset:53248
	ds_read_b128 v[180:183], v251 offset:54272
	ds_read_b128 v[184:187], v251 offset:55296
	ds_read_b128 v[188:191], v251 offset:56320
	global_load_lds_dwordx4 v[194:195], off
	s_add_i32 m0, s2, 0x2000
	s_add_u32 s16, s22, 0xb0080
	v_lshl_add_u64 v[194:195], v[196:197], 0, s[88:89]
	s_addc_u32 s17, s23, 0
	s_add_i32 s2, s29, s44
	global_load_lds_dwordx4 v[194:195], off
	v_lshl_add_u64 v[194:195], s[16:17], 0, v[192:193]
	s_mov_b32 m0, s2
	s_nop 0
	global_load_lds_dwordx4 v[194:195], off
	v_lshl_add_u64 v[194:195], s[16:17], 0, v[198:199]
	s_add_i32 m0, s2, 0x2000
	s_nop 0
	global_load_lds_dwordx4 v[194:195], off
	v_lshl_add_u64 v[194:195], v[208:209], 0, s[88:89]
	s_mov_b32 m0, s62
	s_nop 0
	global_load_lds_dwordx4 v[194:195], off
	v_lshl_add_u64 v[194:195], v[210:211], 0, s[88:89]
	s_mov_b32 m0, s63
	s_nop 0
	global_load_lds_dwordx4 v[194:195], off
	s_waitcnt vmcnt(8)
	s_waitcnt lgkmcnt(0)
	s_barrier
	s_setprio 1
	s_waitcnt lgkmcnt(0)
	v_mfma_f32_16x16x32_bf16 v[60:63], v[112:115], v[160:163], v[60:63]
	v_mfma_f32_16x16x32_bf16 v[56:59], v[124:127], v[160:163], v[56:59]
	v_mfma_f32_16x16x32_bf16 v[44:47], v[112:115], v[168:171], v[44:47]
	v_mfma_f32_16x16x32_bf16 v[40:43], v[124:127], v[168:171], v[40:43]
	v_mfma_f32_16x16x32_bf16 v[28:31], v[112:115], v[176:179], v[28:31]
	v_mfma_f32_16x16x32_bf16 v[24:27], v[124:127], v[176:179], v[24:27]
	v_mfma_f32_16x16x32_bf16 v[12:15], v[112:115], v[184:187], v[12:15]
	v_mfma_f32_16x16x32_bf16 v[8:11], v[124:127], v[184:187], v[8:11]
	v_mfma_f32_16x16x32_bf16 v[60:63], v[120:123], v[164:167], v[60:63]
	v_mfma_f32_16x16x32_bf16 v[56:59], v[128:131], v[164:167], v[56:59]
	v_mfma_f32_16x16x32_bf16 v[44:47], v[120:123], v[172:175], v[44:47]
	v_mfma_f32_16x16x32_bf16 v[40:43], v[128:131], v[172:175], v[40:43]
	v_mfma_f32_16x16x32_bf16 v[28:31], v[120:123], v[180:183], v[28:31]
	v_mfma_f32_16x16x32_bf16 v[24:27], v[128:131], v[180:183], v[24:27]
	v_mfma_f32_16x16x32_bf16 v[12:15], v[120:123], v[188:191], v[12:15]
	v_mfma_f32_16x16x32_bf16 v[8:11], v[128:131], v[188:191], v[8:11]
	s_setprio 0
	s_setprio 1
	v_mfma_f32_16x16x32_bf16 v[52:55], v[136:139], v[160:163], v[52:55]
	v_mfma_f32_16x16x32_bf16 v[48:51], v[144:147], v[160:163], v[48:51]
	v_mfma_f32_16x16x32_bf16 v[36:39], v[136:139], v[168:171], v[36:39]
	v_mfma_f32_16x16x32_bf16 v[32:35], v[144:147], v[168:171], v[32:35]
	v_mfma_f32_16x16x32_bf16 v[20:23], v[136:139], v[176:179], v[20:23]
	v_mfma_f32_16x16x32_bf16 v[16:19], v[144:147], v[176:179], v[16:19]
	v_mfma_f32_16x16x32_bf16 v[4:7], v[136:139], v[184:187], v[4:7]
	v_mfma_f32_16x16x32_bf16 v[0:3], v[144:147], v[184:187], v[0:3]
	v_mfma_f32_16x16x32_bf16 v[52:55], v[140:143], v[164:167], v[52:55]
	v_mfma_f32_16x16x32_bf16 v[48:51], v[156:159], v[164:167], v[48:51]
	v_mfma_f32_16x16x32_bf16 v[36:39], v[140:143], v[172:175], v[36:39]
	v_mfma_f32_16x16x32_bf16 v[32:35], v[156:159], v[172:175], v[32:35]
	v_mfma_f32_16x16x32_bf16 v[20:23], v[140:143], v[180:183], v[20:23]
	v_mfma_f32_16x16x32_bf16 v[16:19], v[156:159], v[180:183], v[16:19]
	v_mfma_f32_16x16x32_bf16 v[4:7], v[140:143], v[188:191], v[4:7]
	v_mfma_f32_16x16x32_bf16 v[0:3], v[156:159], v[188:191], v[0:3]
	s_setprio 0
	s_add_i32 s43, s43, 2
	s_add_u32 s34, s34, 0x100
	s_addc_u32 s42, s42, 0
	s_cmp_gt_u32 s43, 41
	s_mov_b64 s[16:17], s[20:21]
	s_cbranch_scc1 .Lxbar_7
	s_add_u32 s20, s16, 0x100
	s_addc_u32 s21, s17, 0
	s_add_i32 s2, s35, 0x100
	s_cmp_eq_u32 s43, 40
	s_cselect_b32 s25, s13, s21
	s_cselect_b32 s24, s12, s20
	s_cselect_b32 s23, s15, s42
	s_cselect_b32 s22, s14, s34
	s_add_i32 s29, s90, 0x100
	s_branch .Lhbar_7
